# m0 write hoisted above the address add so the s_nop before each second LDS-DMA load goes away (no setprio)
# baseline (speedup 1.0000x reference)
; #define PG8_STAGE(bufoff, gbase, voff) do { _Pragma("unroll") for (int _i = 0; _i < 2; ++_i) \
;         __builtin_amdgcn_global_load_lds((const unsigned*)((const char*)(gbase) + (voff)[_i]), (LAS unsigned*)(lds + (bufoff) + ldsw + _i * 8192), 16, 0, 0); } while (0)
; #define PG8_LDA(dst, b, h) do { _Pragma("unroll") for (int m = 0; m < 4; ++m) _Pragma("unroll") for (int k = 0; k < 2; ++k) dst[m][k] = *(const LAS h8*)(lds + PG8_SA(b, h) + aoff + m * 2048 + k * 1024); } while (0)
; #define PG8_LDB(dst, b, h) do { _Pragma("unroll") for (int n = 0; n < 2; ++n) _Pragma("unroll") for (int k = 0; k < 2; ++k) dst[n][k] = *(const LAS h8*)(lds + PG8_SB(b, h) + boff + n * 2048 + k * 1024); } while (0)
; #define PG8_WAIT_L(n) asm volatile("s_waitcnt lgkmcnt(" #n ")" ::: "memory")
; #define PG8_BAR __builtin_amdgcn_s_barrier()
; #define PG8_SCHED __builtin_amdgcn_sched_barrier(0)
; template <class Epi>
; __device__ __forceinline__ void gemm_phase(LAS unsigned char* lds, const Gemm g, const StaticOrder& S, const Epi& E, const int tid) {
;     ...
;         for (int t = 0; t < nt; t += 2) {
;             const bool last = (t == nt - 2);
;             const char* a1 = cA + (size_t)(t + 1) * kstep;
;             const char* a2 = last ? nA : cA + (size_t)(t + 2) * kstep; const char* b2 = last ? nB : cB + (size_t)(t + 2) * kstep;
;             const char* a3 = a2 + kstep; const char* b3 = b2 + kstep;
;             if constexpr (Epi::HAS_MID) { if (t == (nt >> 1)) E.mid(acc, cur, wr, wc, fr, fq); }
;             PG8_LDB(B0, 0, 0); PG8_SCHED; PG8_LDA(At, 0, 0); PG8_STAGE(PG8_SA(1, 1), a1 + hstep, voffA);
;             PG8_WAIT_L(8); PG8_BAR; PG8_WAIT_L(0); PG8_MMA(0, 0, At, B0); PG8_BAR; PG8_SCHED;
;             PG8_LDB(B1, 0, 1); PG8_STAGE(PG8_SB(0, 0), b2, voffB);
;             PG8_BAR; PG8_WAIT_L(0); PG8_MMA(0, 1, At, B1); PG8_BAR;
;             PG8_LDA(At, 0, 1); PG8_STAGE(PG8_SA(0, 0), a2, voffA);
;             PG8_BAR; PG8_WAIT_L(0); PG8_MMA(1, 0, At, B0); PG8_BAR; PG8_SCHED;
.LBB0_332:
	s_add_u32 s18, s14, 0xfff80080
	s_addc_u32 s19, s15, -1
	s_add_i32 s55, 0, 0x10000
	v_add_u32_e32 v157, s55, v140
	ds_read_b128 v[144:147], v157
	ds_read_b128 v[162:165], v157 offset:1024
	ds_read_b128 v[166:169], v157 offset:2048
	ds_read_b128 v[170:173], v157 offset:3072
	s_cmp_eq_u32 s54, 28
	s_cselect_b32 s23, s9, s19
	s_cselect_b32 s22, s50, s18
	s_cselect_b32 s19, s1, s53
	s_cselect_b32 s18, s51, s52
	v_lshl_add_u64 v[178:179], s[14:15], 0, v[136:137]
	s_add_i32 m0, s39, 0xc000
	ds_read_b128 v[174:177], v143
	ds_read_b128 v[190:193], v143 offset:1024
	ds_read_b128 v[194:197], v143 offset:2048
	ds_read_b128 v[198:201], v143 offset:3072
	ds_read_b128 v[202:205], v143 offset:4096
	ds_read_b128 v[206:209], v143 offset:5120
	ds_read_b128 v[210:213], v143 offset:6144
	ds_read_b128 v[214:217], v143 offset:7168
	global_load_lds_dwordx4 v[178:179], off
	s_add_i32 m0, s39, 0xe000
	v_lshl_add_u64 v[178:179], s[14:15], 0, v[138:139]
	global_load_lds_dwordx4 v[178:179], off
	s_waitcnt lgkmcnt(8)
	s_barrier
	s_waitcnt lgkmcnt(0)
	s_waitcnt lgkmcnt(0)
	v_mfma_f32_16x16x32_bf16 v[124:127], v[144:147], v[174:177], v[124:127]
	v_mfma_f32_16x16x32_bf16 v[128:131], v[166:169], v[174:177], v[128:131]
	v_mfma_f32_16x16x32_bf16 v[108:111], v[144:147], v[194:197], v[108:111]
	v_mfma_f32_16x16x32_bf16 v[112:115], v[166:169], v[194:197], v[112:115]
	v_mfma_f32_16x16x32_bf16 v[92:95], v[144:147], v[202:205], v[92:95]
	v_mfma_f32_16x16x32_bf16 v[96:99], v[166:169], v[202:205], v[96:99]
	v_mfma_f32_16x16x32_bf16 v[76:79], v[144:147], v[210:213], v[76:79]
	v_mfma_f32_16x16x32_bf16 v[80:83], v[166:169], v[210:213], v[80:83]
	v_mfma_f32_16x16x32_bf16 v[124:127], v[162:165], v[190:193], v[124:127]
	v_mfma_f32_16x16x32_bf16 v[128:131], v[170:173], v[190:193], v[128:131]
	v_mfma_f32_16x16x32_bf16 v[108:111], v[162:165], v[198:201], v[108:111]
	v_mfma_f32_16x16x32_bf16 v[112:115], v[170:173], v[198:201], v[112:115]
	v_mfma_f32_16x16x32_bf16 v[92:95], v[162:165], v[206:209], v[92:95]
	v_mfma_f32_16x16x32_bf16 v[96:99], v[170:173], v[206:209], v[96:99]
	v_mfma_f32_16x16x32_bf16 v[76:79], v[162:165], v[214:217], v[76:79]
	v_mfma_f32_16x16x32_bf16 v[80:83], v[170:173], v[214:217], v[80:83]
	s_barrier
	s_add_i32 s58, 0, 0x14000
	s_add_i32 s55, s55, s38
	v_add_u32_e32 v157, s58, v140
	v_lshl_add_u64 v[178:179], s[18:19], 0, v[2:3]
	s_mov_b32 m0, s55
	ds_read_b128 v[218:221], v157
	ds_read_b128 v[222:225], v157 offset:1024
	ds_read_b128 v[226:229], v157 offset:2048
	ds_read_b128 v[230:233], v157 offset:3072
	global_load_lds_dwordx4 v[178:179], off
	s_add_i32 m0, s55, 0x2000
	v_lshl_add_u64 v[234:235], s[18:19], 0, v[0:1]
	global_load_lds_dwordx4 v[234:235], off
	s_barrier
	s_waitcnt lgkmcnt(0)
	s_waitcnt lgkmcnt(0)
	v_mfma_f32_16x16x32_bf16 v[116:119], v[218:221], v[174:177], v[116:119]
	v_mfma_f32_16x16x32_bf16 v[120:123], v[226:229], v[174:177], v[120:123]
	v_mfma_f32_16x16x32_bf16 v[100:103], v[218:221], v[194:197], v[100:103]
	v_mfma_f32_16x16x32_bf16 v[104:107], v[226:229], v[194:197], v[104:107]
	v_mfma_f32_16x16x32_bf16 v[84:87], v[218:221], v[202:205], v[84:87]
	v_mfma_f32_16x16x32_bf16 v[88:91], v[226:229], v[202:205], v[88:91]
	v_mfma_f32_16x16x32_bf16 v[68:71], v[218:221], v[210:213], v[68:71]
	v_mfma_f32_16x16x32_bf16 v[72:75], v[226:229], v[210:213], v[72:75]
	v_mfma_f32_16x16x32_bf16 v[116:119], v[222:225], v[190:193], v[116:119]
	v_mfma_f32_16x16x32_bf16 v[120:123], v[230:233], v[190:193], v[120:123]
	v_mfma_f32_16x16x32_bf16 v[100:103], v[222:225], v[198:201], v[100:103]
	v_mfma_f32_16x16x32_bf16 v[104:107], v[230:233], v[198:201], v[104:107]
	v_mfma_f32_16x16x32_bf16 v[84:87], v[222:225], v[206:209], v[84:87]
	v_mfma_f32_16x16x32_bf16 v[88:91], v[230:233], v[206:209], v[88:91]
	v_mfma_f32_16x16x32_bf16 v[68:71], v[222:225], v[214:217], v[68:71]
	v_mfma_f32_16x16x32_bf16 v[72:75], v[230:233], v[214:217], v[72:75]
	s_mov_b32 m0, s39
	v_lshl_add_u64 v[236:237], s[22:23], 0, v[134:135]
	s_barrier
	ds_read_b128 v[174:177], v143 offset:16384
	ds_read_b128 v[190:193], v143 offset:17408
	ds_read_b128 v[194:197], v143 offset:18432
	ds_read_b128 v[198:201], v143 offset:19456
	ds_read_b128 v[202:205], v143 offset:20480
	ds_read_b128 v[206:209], v143 offset:21504
	ds_read_b128 v[210:213], v143 offset:22528
	ds_read_b128 v[214:217], v143 offset:23552
	global_load_lds_dwordx4 v[236:237], off
	s_mov_b32 m0, s40
	v_lshl_add_u64 v[238:239], s[22:23], 0, v[132:133]
	global_load_lds_dwordx4 v[238:239], off
	s_barrier
	s_waitcnt lgkmcnt(0)
	s_waitcnt lgkmcnt(0)
	v_mfma_f32_16x16x32_bf16 v[60:63], v[144:147], v[174:177], v[60:63]
	v_mfma_f32_16x16x32_bf16 v[64:67], v[166:169], v[174:177], v[64:67]
	v_mfma_f32_16x16x32_bf16 v[44:47], v[144:147], v[194:197], v[44:47]
	v_mfma_f32_16x16x32_bf16 v[48:51], v[166:169], v[194:197], v[48:51]
	v_mfma_f32_16x16x32_bf16 v[28:31], v[144:147], v[202:205], v[28:31]
	v_mfma_f32_16x16x32_bf16 v[32:35], v[166:169], v[202:205], v[32:35]
	v_mfma_f32_16x16x32_bf16 v[12:15], v[144:147], v[210:213], v[12:15]
	v_mfma_f32_16x16x32_bf16 v[16:19], v[166:169], v[210:213], v[16:19]
	v_mfma_f32_16x16x32_bf16 v[60:63], v[162:165], v[190:193], v[60:63]
	v_mfma_f32_16x16x32_bf16 v[64:67], v[170:173], v[190:193], v[64:67]
	v_mfma_f32_16x16x32_bf16 v[44:47], v[162:165], v[198:201], v[44:47]
	v_mfma_f32_16x16x32_bf16 v[48:51], v[170:173], v[198:201], v[48:51]
	v_mfma_f32_16x16x32_bf16 v[28:31], v[162:165], v[206:209], v[28:31]
	v_mfma_f32_16x16x32_bf16 v[32:35], v[170:173], v[206:209], v[32:35]
	v_mfma_f32_16x16x32_bf16 v[12:15], v[162:165], v[214:217], v[12:15]
	v_mfma_f32_16x16x32_bf16 v[16:19], v[170:173], v[214:217], v[16:19]
	s_barrier
; #define PG8_STAGE(bufoff, gbase, voff) do { _Pragma("unroll") for (int _i = 0; _i < 2; ++_i) \
;         __builtin_amdgcn_global_load_lds((const unsigned*)((const char*)(gbase) + (voff)[_i]), (LAS unsigned*)(lds + (bufoff) + ldsw + _i * 8192), 16, 0, 0); } while (0)
; #define PG8_LDA(dst, b, h) do { _Pragma("unroll") for (int m = 0; m < 4; ++m) _Pragma("unroll") for (int k = 0; k < 2; ++k) dst[m][k] = *(const LAS h8*)(lds + PG8_SA(b, h) + aoff + m * 2048 + k * 1024); } while (0)
; #define PG8_LDB(dst, b, h) do { _Pragma("unroll") for (int n = 0; n < 2; ++n) _Pragma("unroll") for (int k = 0; k < 2; ++k) dst[n][k] = *(const LAS h8*)(lds + PG8_SB(b, h) + boff + n * 2048 + k * 1024); } while (0)
; #define PG8_WAIT_V(n) asm volatile("s_waitcnt vmcnt(" #n ")" ::: "memory")
; #define PG8_WAIT_L(n) asm volatile("s_waitcnt lgkmcnt(" #n ")" ::: "memory")
; #define PG8_BAR __builtin_amdgcn_s_barrier()
; #define PG8_SCHED __builtin_amdgcn_sched_barrier(0)
; template <class Epi>
; __device__ __forceinline__ void gemm_phase(LAS unsigned char* lds, const Gemm g, const StaticOrder& S, const Epi& E, const int tid) {
;     ...
;             PG8_STAGE(PG8_SB(0, 1), b2 + hstepB, voffB);
;             PG8_WAIT_V(6); PG8_BAR; PG8_MMA(1, 1, At, B1); PG8_BAR;
;             PG8_LDB(B0, 1, 0); PG8_SCHED; PG8_LDA(At, 1, 0); PG8_STAGE(PG8_SA(0, 1), a2 + hstep, voffA);
;             PG8_WAIT_L(8); PG8_BAR; PG8_WAIT_L(0); PG8_MMA(0, 0, At, B0); PG8_BAR; PG8_SCHED;
;             PG8_LDB(B1, 1, 1); PG8_STAGE(PG8_SB(1, 0), b3, voffB);
;             PG8_BAR; PG8_WAIT_L(0); PG8_MMA(0, 1, At, B1); PG8_BAR;
;             PG8_LDA(At, 1, 1); PG8_STAGE(PG8_SA(1, 0), a3, voffA);
	s_add_u32 s56, s18, 0x20000
	s_addc_u32 s57, s19, 0
	s_add_i32 s55, s58, s38
	s_mov_b32 m0, s55
	v_lshl_add_u64 v[144:145], s[56:57], 0, v[2:3]
	global_load_lds_dwordx4 v[144:145], off
	s_add_i32 m0, s55, 0x2000
	v_lshl_add_u64 v[144:145], s[56:57], 0, v[0:1]
	global_load_lds_dwordx4 v[144:145], off
	s_waitcnt vmcnt(6)
	s_barrier
	v_mfma_f32_16x16x32_bf16 v[52:55], v[218:221], v[174:177], v[52:55]
	v_mfma_f32_16x16x32_bf16 v[56:59], v[226:229], v[174:177], v[56:59]
	v_mfma_f32_16x16x32_bf16 v[36:39], v[218:221], v[194:197], v[36:39]
	v_mfma_f32_16x16x32_bf16 v[40:43], v[226:229], v[194:197], v[40:43]
	v_mfma_f32_16x16x32_bf16 v[20:23], v[218:221], v[202:205], v[20:23]
	v_mfma_f32_16x16x32_bf16 v[24:27], v[226:229], v[202:205], v[24:27]
	v_mfma_f32_16x16x32_bf16 v[8:11], v[218:221], v[210:213], v[8:11]
	v_mfma_f32_16x16x32_bf16 v[4:7], v[226:229], v[210:213], v[4:7]
	v_mfma_f32_16x16x32_bf16 v[52:55], v[222:225], v[190:193], v[52:55]
	v_mfma_f32_16x16x32_bf16 v[56:59], v[230:233], v[190:193], v[56:59]
	v_mfma_f32_16x16x32_bf16 v[36:39], v[222:225], v[198:201], v[36:39]
	v_mfma_f32_16x16x32_bf16 v[40:43], v[230:233], v[198:201], v[40:43]
	v_mfma_f32_16x16x32_bf16 v[20:23], v[222:225], v[206:209], v[20:23]
	v_mfma_f32_16x16x32_bf16 v[24:27], v[230:233], v[206:209], v[24:27]
	v_mfma_f32_16x16x32_bf16 v[8:11], v[222:225], v[214:217], v[8:11]
	v_mfma_f32_16x16x32_bf16 v[4:7], v[230:233], v[214:217], v[4:7]
	s_add_i32 s55, 0, 0x18000
	v_add_u32_e32 v157, s55, v140
	s_barrier
	ds_read_b128 v[144:147], v157
	ds_read_b128 v[162:165], v157 offset:1024
	ds_read_b128 v[166:169], v157 offset:2048
	ds_read_b128 v[170:173], v157 offset:3072
	s_add_u32 s22, s22, 0x80000
	s_addc_u32 s23, s23, 0
	s_mov_b32 m0, s41
	v_lshl_add_u64 v[218:219], s[22:23], 0, v[134:135]
	ds_read_b128 v[174:177], v143 offset:32768
	ds_read_b128 v[190:193], v143 offset:33792
	ds_read_b128 v[194:197], v143 offset:34816
	ds_read_b128 v[198:201], v143 offset:35840
	ds_read_b128 v[202:205], v143 offset:36864
	ds_read_b128 v[206:209], v143 offset:37888
	ds_read_b128 v[210:213], v143 offset:38912
	ds_read_b128 v[214:217], v143 offset:39936
	global_load_lds_dwordx4 v[218:219], off
	s_mov_b32 m0, s42
	v_lshl_add_u64 v[218:219], s[22:23], 0, v[132:133]
	global_load_lds_dwordx4 v[218:219], off
	s_waitcnt lgkmcnt(8)
	s_barrier
	s_waitcnt lgkmcnt(0)
	s_waitcnt lgkmcnt(0)
	v_mfma_f32_16x16x32_bf16 v[124:127], v[144:147], v[174:177], v[124:127]
	v_mfma_f32_16x16x32_bf16 v[128:131], v[166:169], v[174:177], v[128:131]
	v_mfma_f32_16x16x32_bf16 v[108:111], v[144:147], v[194:197], v[108:111]
	v_mfma_f32_16x16x32_bf16 v[112:115], v[166:169], v[194:197], v[112:115]
	v_mfma_f32_16x16x32_bf16 v[92:95], v[144:147], v[202:205], v[92:95]
	v_mfma_f32_16x16x32_bf16 v[96:99], v[166:169], v[202:205], v[96:99]
	v_mfma_f32_16x16x32_bf16 v[76:79], v[144:147], v[210:213], v[76:79]
	v_mfma_f32_16x16x32_bf16 v[80:83], v[166:169], v[210:213], v[80:83]
	v_mfma_f32_16x16x32_bf16 v[124:127], v[162:165], v[190:193], v[124:127]
	v_mfma_f32_16x16x32_bf16 v[128:131], v[170:173], v[190:193], v[128:131]
	v_mfma_f32_16x16x32_bf16 v[108:111], v[162:165], v[198:201], v[108:111]
	v_mfma_f32_16x16x32_bf16 v[112:115], v[170:173], v[198:201], v[112:115]
	v_mfma_f32_16x16x32_bf16 v[92:95], v[162:165], v[206:209], v[92:95]
	v_mfma_f32_16x16x32_bf16 v[96:99], v[170:173], v[206:209], v[96:99]
	v_mfma_f32_16x16x32_bf16 v[76:79], v[162:165], v[214:217], v[76:79]
	v_mfma_f32_16x16x32_bf16 v[80:83], v[170:173], v[214:217], v[80:83]
	s_barrier
	s_add_i32 s22, 0, 0x1c000
	s_add_i32 s23, s55, s38
	v_add_u32_e32 v157, s22, v140
	v_lshl_add_u64 v[178:179], v[178:179], 0, s[30:31]
	s_mov_b32 m0, s23
	ds_read_b128 v[218:221], v157
	ds_read_b128 v[222:225], v157 offset:1024
	ds_read_b128 v[226:229], v157 offset:2048
	ds_read_b128 v[230:233], v157 offset:3072
	global_load_lds_dwordx4 v[178:179], off
	s_add_i32 m0, s23, 0x2000
	v_lshl_add_u64 v[178:179], v[234:235], 0, s[30:31]
	global_load_lds_dwordx4 v[178:179], off
	s_barrier
	s_waitcnt lgkmcnt(0)
	s_waitcnt lgkmcnt(0)
	v_mfma_f32_16x16x32_bf16 v[116:119], v[218:221], v[174:177], v[116:119]
	v_mfma_f32_16x16x32_bf16 v[120:123], v[226:229], v[174:177], v[120:123]
	v_mfma_f32_16x16x32_bf16 v[100:103], v[218:221], v[194:197], v[100:103]
	v_mfma_f32_16x16x32_bf16 v[104:107], v[226:229], v[194:197], v[104:107]
	v_mfma_f32_16x16x32_bf16 v[84:87], v[218:221], v[202:205], v[84:87]
	v_mfma_f32_16x16x32_bf16 v[88:91], v[226:229], v[202:205], v[88:91]
	v_mfma_f32_16x16x32_bf16 v[68:71], v[218:221], v[210:213], v[68:71]
	v_mfma_f32_16x16x32_bf16 v[72:75], v[226:229], v[210:213], v[72:75]
	v_mfma_f32_16x16x32_bf16 v[116:119], v[222:225], v[190:193], v[116:119]
	v_mfma_f32_16x16x32_bf16 v[120:123], v[230:233], v[190:193], v[120:123]
	v_mfma_f32_16x16x32_bf16 v[100:103], v[222:225], v[198:201], v[100:103]
	v_mfma_f32_16x16x32_bf16 v[104:107], v[230:233], v[198:201], v[104:107]
	v_mfma_f32_16x16x32_bf16 v[84:87], v[222:225], v[206:209], v[84:87]
	v_mfma_f32_16x16x32_bf16 v[88:91], v[230:233], v[206:209], v[88:91]
	v_mfma_f32_16x16x32_bf16 v[68:71], v[222:225], v[214:217], v[68:71]
	v_mfma_f32_16x16x32_bf16 v[72:75], v[230:233], v[214:217], v[72:75]
	s_mov_b32 m0, s43
	v_lshl_add_u64 v[178:179], v[236:237], 0, s[30:31]
	s_barrier
	ds_read_b128 v[174:177], v143 offset:49152
	ds_read_b128 v[190:193], v143 offset:50176
	ds_read_b128 v[194:197], v143 offset:51200
	ds_read_b128 v[198:201], v143 offset:52224
	ds_read_b128 v[202:205], v143 offset:53248
	ds_read_b128 v[206:209], v143 offset:54272
	ds_read_b128 v[210:213], v143 offset:55296
	ds_read_b128 v[214:217], v143 offset:56320
	global_load_lds_dwordx4 v[178:179], off
	s_mov_b32 m0, s46
	v_lshl_add_u64 v[178:179], v[238:239], 0, s[30:31]
	global_load_lds_dwordx4 v[178:179], off
	s_barrier
; #define PG8_STAGE(bufoff, gbase, voff) do { _Pragma("unroll") for (int _i = 0; _i < 2; ++_i) \
;         __builtin_amdgcn_global_load_lds((const unsigned*)((const char*)(gbase) + (voff)[_i]), (LAS unsigned*)(lds + (bufoff) + ldsw + _i * 8192), 16, 0, 0); } while (0)
; #define PG8_WAIT_V(n) asm volatile("s_waitcnt vmcnt(" #n ")" ::: "memory")
; #define PG8_WAIT_L(n) asm volatile("s_waitcnt lgkmcnt(" #n ")" ::: "memory")
; #define PG8_BAR __builtin_amdgcn_s_barrier()
; #define PG8_SCHED __builtin_amdgcn_sched_barrier(0)
; template <class Epi>
; __device__ __forceinline__ void gemm_phase(LAS unsigned char* lds, const Gemm g, const StaticOrder& S, const Epi& E, const int tid) {
;     ...
;             PG8_BAR; PG8_WAIT_L(0); PG8_MMA(1, 0, At, B0); PG8_BAR; PG8_SCHED;
;             PG8_STAGE(PG8_SB(1, 1), b3 + hstepB, voffB);
;             PG8_WAIT_V(6); PG8_BAR; PG8_MMA(1, 1, At, B1); PG8_BAR;
;         }
;     __device__ __forceinline__ void operator()(f32x4 (&acc)[2][2][4][2], const pg8::Unit& u, int wr, int wc, int fr, int fq) const {
;         const bool hi = fr >= 8;
;         const int row0 = u.pm * 256 + wr * 64 + (fr & 7), col = u.pn * 256 + wc * 64 + fq * 8 + (hi ? 32 : 0);
; #pragma unroll
;         for (int ai = 0; ai < 2; ++ai)
; #pragma unroll
;             for (int m = 0; m < 4; ++m) {
;                 const h8 x0 = pack8(acc[ai][0][m][0], acc[ai][0][m][1]), x1 = pack8(acc[ai][1][m][0], acc[ai][1][m][1]);
;                 const i32x4 snd = hi ? __builtin_bit_cast(i32x4, x0) : __builtin_bit_cast(i32x4, x1);
;                 i32x4 rcv;
; #pragma unroll
;                 for (int d = 0; d < 4; ++d) rcv[d] = __builtin_amdgcn_update_dpp(0, snd[d], 0x128  , 0xF, 0xF, false);
;                 const h8 rv = __builtin_bit_cast(h8, rcv);
;                 const h8 vA = hi ? rv : x0;
;                 const h8 vB = hi ? x1 : rv;
;                 half_t* rowp = O + (size_t)(row0 + ai * 128 + m * 16) * NIN + col;
;                 __builtin_nontemporal_store(vA, (h8*)rowp); __builtin_nontemporal_store(vB, (h8*)(rowp + (size_t)8 * NIN)); }
	s_waitcnt lgkmcnt(0)
	s_waitcnt lgkmcnt(0)
	v_mfma_f32_16x16x32_bf16 v[60:63], v[144:147], v[174:177], v[60:63]
	v_mfma_f32_16x16x32_bf16 v[64:67], v[166:169], v[174:177], v[64:67]
	v_mfma_f32_16x16x32_bf16 v[44:47], v[144:147], v[194:197], v[44:47]
	v_mfma_f32_16x16x32_bf16 v[48:51], v[166:169], v[194:197], v[48:51]
	v_mfma_f32_16x16x32_bf16 v[28:31], v[144:147], v[202:205], v[28:31]
	v_mfma_f32_16x16x32_bf16 v[32:35], v[166:169], v[202:205], v[32:35]
	v_mfma_f32_16x16x32_bf16 v[12:15], v[144:147], v[210:213], v[12:15]
	v_mfma_f32_16x16x32_bf16 v[16:19], v[166:169], v[210:213], v[16:19]
	v_mfma_f32_16x16x32_bf16 v[60:63], v[162:165], v[190:193], v[60:63]
	v_mfma_f32_16x16x32_bf16 v[64:67], v[170:173], v[190:193], v[64:67]
	v_mfma_f32_16x16x32_bf16 v[44:47], v[162:165], v[198:201], v[44:47]
	v_mfma_f32_16x16x32_bf16 v[48:51], v[170:173], v[198:201], v[48:51]
	v_mfma_f32_16x16x32_bf16 v[28:31], v[162:165], v[206:209], v[28:31]
	v_mfma_f32_16x16x32_bf16 v[32:35], v[170:173], v[206:209], v[32:35]
	v_mfma_f32_16x16x32_bf16 v[12:15], v[162:165], v[214:217], v[12:15]
	v_mfma_f32_16x16x32_bf16 v[16:19], v[170:173], v[214:217], v[16:19]
	s_barrier
	s_add_u32 s18, s18, 0x20080
	s_addc_u32 s19, s19, 0
	s_add_i32 s22, s22, s38
	s_mov_b32 m0, s22
	v_lshl_add_u64 v[144:145], s[18:19], 0, v[2:3]
	global_load_lds_dwordx4 v[144:145], off
	s_add_i32 m0, s22, 0x2000
	v_lshl_add_u64 v[144:145], s[18:19], 0, v[0:1]
	global_load_lds_dwordx4 v[144:145], off
	s_waitcnt vmcnt(6)
	s_barrier
	v_mfma_f32_16x16x32_bf16 v[52:55], v[218:221], v[174:177], v[52:55]
	v_mfma_f32_16x16x32_bf16 v[56:59], v[226:229], v[174:177], v[56:59]
	v_mfma_f32_16x16x32_bf16 v[36:39], v[218:221], v[194:197], v[36:39]
	v_mfma_f32_16x16x32_bf16 v[40:43], v[226:229], v[194:197], v[40:43]
	v_mfma_f32_16x16x32_bf16 v[20:23], v[218:221], v[202:205], v[20:23]
	v_mfma_f32_16x16x32_bf16 v[24:27], v[226:229], v[202:205], v[24:27]
	v_mfma_f32_16x16x32_bf16 v[8:11], v[218:221], v[210:213], v[8:11]
	v_mfma_f32_16x16x32_bf16 v[4:7], v[226:229], v[210:213], v[4:7]
	v_mfma_f32_16x16x32_bf16 v[52:55], v[222:225], v[190:193], v[52:55]
	v_mfma_f32_16x16x32_bf16 v[56:59], v[230:233], v[190:193], v[56:59]
	v_mfma_f32_16x16x32_bf16 v[36:39], v[222:225], v[198:201], v[36:39]
	v_mfma_f32_16x16x32_bf16 v[40:43], v[230:233], v[198:201], v[40:43]
	v_mfma_f32_16x16x32_bf16 v[20:23], v[222:225], v[206:209], v[20:23]
	v_mfma_f32_16x16x32_bf16 v[24:27], v[230:233], v[206:209], v[24:27]
	v_mfma_f32_16x16x32_bf16 v[8:11], v[222:225], v[214:217], v[8:11]
	v_mfma_f32_16x16x32_bf16 v[4:7], v[230:233], v[214:217], v[4:7]
	s_add_i32 s54, s54, 2
	s_add_u32 s14, s14, 0x100
	s_addc_u32 s15, s15, 0
	s_add_u32 s52, s52, 0x100
	s_addc_u32 s53, s53, 0
	s_cmp_gt_u32 s54, 29
	s_barrier
	s_cbranch_scc0 .LBB0_332
	v_cvt_pk_f16_f32 v124, v124, v125
	v_cvt_pk_f16_f32 v116, v116, v117
	v_cvt_pk_f16_f32 v130, v130, v131
	v_cvt_pk_f16_f32 v131, v122, v123
	v_cvt_pk_f16_f32 v128, v128, v129
	v_cvt_pk_f16_f32 v129, v120, v121
	v_cvt_pk_f16_f32 v121, v126, v127
	v_cvt_pk_f16_f32 v118, v118, v119
	v_cndmask_b32_e64 v117, v116, v124, s[4:5]
	v_mov_b32_e32 v147, v3
	v_cndmask_b32_e64 v122, v131, v130, s[4:5]
	v_cndmask_b32_e64 v119, v118, v121, s[4:5]
	v_mov_b32_dpp v147, v117 row_ror:8 row_mask:0xf bank_mask:0xf
	v_mov_b32_e32 v117, v3
	v_mov_b32_e32 v125, v3
	v_lshl_or_b32 v144, s48, 8, v142
	v_cndmask_b32_e64 v120, v129, v128, s[4:5]
	v_mov_b32_dpp v117, v119 row_ror:8 row_mask:0xf bank_mask:0xf
	v_mov_b32_e32 v119, v3
	v_mov_b32_dpp v125, v122 row_ror:8 row_mask:0xf bank_mask:0xf
	v_lshl_add_u32 v146, s49, 8, v141
	v_ashrrev_i32_e32 v145, 31, v144
	v_mov_b32_dpp v119, v120 row_ror:8 row_mask:0xf bank_mask:0xf
	v_cndmask_b32_e64 v123, v130, v125, s[4:5]
	v_cndmask_b32_e64 v121, v121, v117, s[4:5]
	v_cndmask_b32_e64 v120, v124, v147, s[4:5]
	v_cndmask_b32_e64 v127, v125, v131, s[4:5]
	v_cndmask_b32_e64 v125, v117, v118, s[4:5]
	v_cndmask_b32_e64 v124, v147, v116, s[4:5]
	v_mov_b64_e32 v[116:117], s[36:37]
	v_cndmask_b32_e64 v122, v128, v119, s[4:5]
	v_cndmask_b32_e64 v126, v119, v129, s[4:5]
	v_mad_i64_i32 v[128:129], s[14:15], v146, s35, v[116:117]
	v_lshlrev_b64 v[118:119], 1, v[144:145]
	v_lshl_add_u64 v[128:129], v[128:129], 0, v[118:119]
	s_mov_b32 s1, 0x3c000
	global_store_dwordx4 v[128:129], v[120:123], off nt
	v_cvt_pk_f16_f32 v112, v112, v113
	v_cvt_pk_f16_f32 v104, v104, v105
	v_add_co_u32_e32 v120, vcc, s1, v128
	v_cvt_pk_f16_f32 v108, v108, v109
	s_nop 0
	v_addc_co_u32_e32 v121, vcc, 0, v129, vcc
	v_cvt_pk_f16_f32 v109, v100, v101
	global_store_dwordx4 v[120:121], v[124:127], off nt
	v_cvt_pk_f16_f32 v114, v114, v115
	v_cvt_pk_f16_f32 v106, v106, v107
	v_cndmask_b32_e64 v105, v104, v112, s[4:5]
	v_cndmask_b32_e64 v100, v109, v108, s[4:5]
	v_mov_b32_e32 v113, v3
	v_mov_b32_e32 v120, v3
	v_cndmask_b32_e64 v107, v106, v114, s[4:5]
	v_cvt_pk_f16_f32 v110, v110, v111
	v_cvt_pk_f16_f32 v111, v102, v103
	v_mov_b32_dpp v113, v100 row_ror:8 row_mask:0xf bank_mask:0xf
	v_mov_b32_dpp v120, v105 row_ror:8 row_mask:0xf bank_mask:0xf
	v_mov_b32_e32 v105, v3
	v_cndmask_b32_e64 v102, v111, v110, s[4:5]
	v_mov_b32_e32 v115, v3
	v_mov_b32_dpp v105, v107 row_ror:8 row_mask:0xf bank_mask:0xf
	v_cndmask_b32_e64 v100, v108, v113, s[4:5]
	v_or_b32_e32 v108, 16, v146
	v_mov_b32_dpp v115, v102 row_ror:8 row_mask:0xf bank_mask:0xf
	v_cndmask_b32_e64 v107, v105, v106, s[4:5]
	v_cndmask_b32_e64 v106, v120, v104, s[4:5]
	v_cndmask_b32_e64 v104, v113, v109, s[4:5]
	v_mad_i64_i32 v[108:109], s[14:15], v108, s35, v[116:117]
	v_cndmask_b32_e64 v103, v114, v105, s[4:5]
	v_cndmask_b32_e64 v102, v112, v120, s[4:5]
	v_cndmask_b32_e64 v101, v110, v115, s[4:5]
;     __device__ __forceinline__ void operator()(f32x4 (&acc)[2][2][4][2], const pg8::Unit& u, int wr, int wc, int fr, int fq) const {
;         const bool hi = fr >= 8;
;         const int row0 = u.pm * 256 + wr * 64 + (fr & 7), col = u.pn * 256 + wc * 64 + fq * 8 + (hi ? 32 : 0);
; #pragma unroll
;         for (int ai = 0; ai < 2; ++ai)
; #pragma unroll
;             for (int m = 0; m < 4; ++m) {
;                 const h8 x0 = pack8(acc[ai][0][m][0], acc[ai][0][m][1]), x1 = pack8(acc[ai][1][m][0], acc[ai][1][m][1]);
;                 const i32x4 snd = hi ? __builtin_bit_cast(i32x4, x0) : __builtin_bit_cast(i32x4, x1);
;                 i32x4 rcv;
; #pragma unroll
;                 for (int d = 0; d < 4; ++d) rcv[d] = __builtin_amdgcn_update_dpp(0, snd[d], 0x128  , 0xF, 0xF, false);
;                 const h8 rv = __builtin_bit_cast(h8, rcv);
;                 const h8 vA = hi ? rv : x0;
;                 const h8 vB = hi ? x1 : rv;
;                 half_t* rowp = O + (size_t)(row0 + ai * 128 + m * 16) * NIN + col;
;                 __builtin_nontemporal_store(vA, (h8*)rowp); __builtin_nontemporal_store(vB, (h8*)(rowp + (size_t)8 * NIN)); }
	v_lshl_add_u64 v[108:109], v[108:109], 0, v[118:119]
	global_store_dwordx4 v[108:109], v[100:103], off nt
	v_cndmask_b32_e64 v105, v115, v111, s[4:5]
	v_cvt_pk_f16_f32 v96, v96, v97
	v_add_co_u32_e32 v100, vcc, s1, v108
	v_cvt_pk_f16_f32 v88, v88, v89
	s_nop 0
	v_addc_co_u32_e32 v101, vcc, 0, v109, vcc
	v_cvt_pk_f16_f32 v92, v92, v93
	v_cvt_pk_f16_f32 v93, v84, v85
	global_store_dwordx4 v[100:101], v[104:107], off nt
	v_cvt_pk_f16_f32 v98, v98, v99
	v_cvt_pk_f16_f32 v90, v90, v91
	v_cndmask_b32_e64 v89, v88, v96, s[4:5]
	v_cndmask_b32_e64 v84, v93, v92, s[4:5]
	v_mov_b32_e32 v97, v3
	v_mov_b32_e32 v100, v3
	v_cndmask_b32_e64 v91, v90, v98, s[4:5]
	v_cvt_pk_f16_f32 v94, v94, v95
	v_cvt_pk_f16_f32 v95, v86, v87
	v_mov_b32_dpp v97, v84 row_ror:8 row_mask:0xf bank_mask:0xf
	v_mov_b32_dpp v100, v89 row_ror:8 row_mask:0xf bank_mask:0xf
	v_mov_b32_e32 v89, v3
	v_cndmask_b32_e64 v86, v95, v94, s[4:5]
	v_mov_b32_e32 v99, v3
	v_mov_b32_dpp v89, v91 row_ror:8 row_mask:0xf bank_mask:0xf
	v_cndmask_b32_e64 v84, v92, v97, s[4:5]
	v_or_b32_e32 v92, 32, v146
	v_mov_b32_dpp v99, v86 row_ror:8 row_mask:0xf bank_mask:0xf
	v_cndmask_b32_e64 v91, v89, v90, s[4:5]
	v_cndmask_b32_e64 v90, v100, v88, s[4:5]
	v_cndmask_b32_e64 v88, v97, v93, s[4:5]
	v_mad_i64_i32 v[92:93], s[14:15], v92, s35, v[116:117]
	v_cndmask_b32_e64 v87, v98, v89, s[4:5]
	v_cndmask_b32_e64 v86, v96, v100, s[4:5]
	v_cndmask_b32_e64 v85, v94, v99, s[4:5]
	v_lshl_add_u64 v[92:93], v[92:93], 0, v[118:119]
	global_store_dwordx4 v[92:93], v[84:87], off nt
	v_cndmask_b32_e64 v89, v99, v95, s[4:5]
	v_cvt_pk_f16_f32 v80, v80, v81
	v_add_co_u32_e32 v84, vcc, s1, v92
	v_cvt_pk_f16_f32 v72, v72, v73
	s_nop 0
	v_addc_co_u32_e32 v85, vcc, 0, v93, vcc
	v_cvt_pk_f16_f32 v76, v76, v77
	v_cvt_pk_f16_f32 v77, v68, v69
	global_store_dwordx4 v[84:85], v[88:91], off nt
	v_cvt_pk_f16_f32 v82, v82, v83
	v_cvt_pk_f16_f32 v74, v74, v75
	v_cndmask_b32_e64 v73, v72, v80, s[4:5]
	v_cndmask_b32_e64 v68, v77, v76, s[4:5]
	v_mov_b32_e32 v81, v3
	v_mov_b32_e32 v84, v3
	v_cndmask_b32_e64 v75, v74, v82, s[4:5]
	v_cvt_pk_f16_f32 v78, v78, v79
	v_cvt_pk_f16_f32 v79, v70, v71
	v_mov_b32_dpp v81, v68 row_ror:8 row_mask:0xf bank_mask:0xf
	v_mov_b32_dpp v84, v73 row_ror:8 row_mask:0xf bank_mask:0xf
	v_mov_b32_e32 v73, v3
	v_cndmask_b32_e64 v70, v79, v78, s[4:5]
	v_mov_b32_e32 v83, v3
	v_mov_b32_dpp v73, v75 row_ror:8 row_mask:0xf bank_mask:0xf
	v_cndmask_b32_e64 v68, v76, v81, s[4:5]
	v_or_b32_e32 v76, 48, v146
	v_mov_b32_dpp v83, v70 row_ror:8 row_mask:0xf bank_mask:0xf
	v_cndmask_b32_e64 v75, v73, v74, s[4:5]
	v_cndmask_b32_e64 v74, v84, v72, s[4:5]
	v_cndmask_b32_e64 v72, v81, v77, s[4:5]
	v_mad_i64_i32 v[76:77], s[14:15], v76, s35, v[116:117]
	v_cndmask_b32_e64 v71, v82, v73, s[4:5]
	v_cndmask_b32_e64 v70, v80, v84, s[4:5]
	v_cndmask_b32_e64 v69, v78, v83, s[4:5]
	v_lshl_add_u64 v[76:77], v[76:77], 0, v[118:119]
	global_store_dwordx4 v[76:77], v[68:71], off nt
	v_cndmask_b32_e64 v73, v83, v79, s[4:5]
	v_cvt_pk_f16_f32 v64, v64, v65
	v_add_co_u32_e32 v68, vcc, s1, v76
	v_cvt_pk_f16_f32 v56, v56, v57
	s_nop 0
	v_addc_co_u32_e32 v69, vcc, 0, v77, vcc
	global_store_dwordx4 v[68:69], v[72:75], off nt
	v_cvt_pk_f16_f32 v66, v66, v67
	v_cvt_pk_f16_f32 v58, v58, v59
	v_cndmask_b32_e64 v57, v56, v64, s[4:5]
	v_cvt_pk_f16_f32 v60, v60, v61
	v_cvt_pk_f16_f32 v61, v52, v53
	v_mov_b32_e32 v69, v3
	v_cndmask_b32_e64 v59, v58, v66, s[4:5]
	v_cvt_pk_f16_f32 v62, v62, v63
	v_cvt_pk_f16_f32 v63, v54, v55
	v_cndmask_b32_e64 v52, v61, v60, s[4:5]
	v_mov_b32_e32 v65, v3
	v_mov_b32_dpp v69, v57 row_ror:8 row_mask:0xf bank_mask:0xf
	v_mov_b32_e32 v57, v3
	v_add_u32_e32 v68, 0x80, v146
	v_cndmask_b32_e64 v54, v63, v62, s[4:5]
	v_mov_b32_dpp v65, v52 row_ror:8 row_mask:0xf bank_mask:0xf
	v_mov_b32_e32 v67, v3
	v_mov_b32_dpp v57, v59 row_ror:8 row_mask:0xf bank_mask:0xf
	v_cndmask_b32_e64 v52, v60, v65, s[4:5]
	v_mov_b32_dpp v67, v54 row_ror:8 row_mask:0xf bank_mask:0xf
	v_cndmask_b32_e64 v59, v57, v58, s[4:5]
	v_cndmask_b32_e64 v58, v69, v56, s[4:5]
	v_cndmask_b32_e64 v56, v65, v61, s[4:5]
	v_mad_i64_i32 v[60:61], s[14:15], v68, s35, v[116:117]
	v_cndmask_b32_e64 v55, v66, v57, s[4:5]
	v_cndmask_b32_e64 v54, v64, v69, s[4:5]
	v_cndmask_b32_e64 v53, v62, v67, s[4:5]
	v_lshl_add_u64 v[60:61], v[60:61], 0, v[118:119]
	global_store_dwordx4 v[60:61], v[52:55], off nt
	v_cndmask_b32_e64 v57, v67, v63, s[4:5]
	v_cvt_pk_f16_f32 v48, v48, v49
	v_add_co_u32_e32 v52, vcc, s1, v60
	v_cvt_pk_f16_f32 v40, v40, v41
	s_nop 0
	v_addc_co_u32_e32 v53, vcc, 0, v61, vcc
	v_cvt_pk_f16_f32 v44, v44, v45
; #define PG8_WAIT_V(n) asm volatile("s_waitcnt vmcnt(" #n ")" ::: "memory")
; #define PG8_BAR __builtin_amdgcn_s_barrier()
; template <class Epi>
; __device__ __forceinline__ void gemm_phase(LAS unsigned char* lds, const Gemm g, const StaticOrder& S, const Epi& E, const int tid) {
;     ...
;         E(acc, cur, wr, wc, fr, fq);
;         if (!has_next) break;
; #pragma unroll
;         for (int a = 0; a < 2; ++a)
; #pragma unroll
;             for (int b = 0; b < 2; ++b)
; #pragma unroll
;                 for (int m = 0; m < 4; ++m)
; #pragma unroll
;                     for (int n = 0; n < 2; ++n) acc[a][b][m][n] = (f32x4){0.f, 0.f, 0.f, 0.f};
;         cur = nxt; cA = nA; cB = nB; ++ui;
;     }
;     PG8_WAIT_V(0);
;     if (wr == 0) PG8_BAR;
;     PG8_BAR;
;     __device__ __forceinline__ void operator()(f32x4 (&acc)[2][2][4][2], const pg8::Unit& u, int wr, int wc, int fr, int fq) const {
;     ...
; #pragma unroll
;         for (int ai = 0; ai < 2; ++ai)
; #pragma unroll
;             for (int m = 0; m < 4; ++m) {
;                 const h8 x0 = pack8(acc[ai][0][m][0], acc[ai][0][m][1]), x1 = pack8(acc[ai][1][m][0], acc[ai][1][m][1]);
;                 const i32x4 snd = hi ? __builtin_bit_cast(i32x4, x0) : __builtin_bit_cast(i32x4, x1);
;                 i32x4 rcv;
; #pragma unroll
;                 for (int d = 0; d < 4; ++d) rcv[d] = __builtin_amdgcn_update_dpp(0, snd[d], 0x128  , 0xF, 0xF, false);
;                 const h8 rv = __builtin_bit_cast(h8, rcv);
;                 const h8 vA = hi ? rv : x0;
;                 const h8 vB = hi ? x1 : rv;
;                 half_t* rowp = O + (size_t)(row0 + ai * 128 + m * 16) * NIN + col;
;                 __builtin_nontemporal_store(vA, (h8*)rowp); __builtin_nontemporal_store(vB, (h8*)(rowp + (size_t)8 * NIN)); }
	v_cvt_pk_f16_f32 v45, v36, v37
	global_store_dwordx4 v[52:53], v[56:59], off nt
	v_cvt_pk_f16_f32 v50, v50, v51
	v_cvt_pk_f16_f32 v42, v42, v43
	v_cndmask_b32_e64 v41, v40, v48, s[4:5]
	v_cndmask_b32_e64 v36, v45, v44, s[4:5]
	v_mov_b32_e32 v49, v3
	v_mov_b32_e32 v52, v3
	v_cndmask_b32_e64 v43, v42, v50, s[4:5]
	v_cvt_pk_f16_f32 v46, v46, v47
	v_cvt_pk_f16_f32 v47, v38, v39
	v_mov_b32_dpp v49, v36 row_ror:8 row_mask:0xf bank_mask:0xf
	v_mov_b32_dpp v52, v41 row_ror:8 row_mask:0xf bank_mask:0xf
	v_mov_b32_e32 v41, v3
	v_cndmask_b32_e64 v38, v47, v46, s[4:5]
	v_mov_b32_e32 v51, v3
	v_mov_b32_dpp v41, v43 row_ror:8 row_mask:0xf bank_mask:0xf
	v_cndmask_b32_e64 v36, v44, v49, s[4:5]
	v_add_u32_e32 v44, 0x90, v146
	v_mov_b32_dpp v51, v38 row_ror:8 row_mask:0xf bank_mask:0xf
	v_cndmask_b32_e64 v43, v41, v42, s[4:5]
	v_cndmask_b32_e64 v42, v52, v40, s[4:5]
	v_cndmask_b32_e64 v40, v49, v45, s[4:5]
	v_mad_i64_i32 v[44:45], s[14:15], v44, s35, v[116:117]
	v_cndmask_b32_e64 v39, v50, v41, s[4:5]
	v_cndmask_b32_e64 v38, v48, v52, s[4:5]
	v_cndmask_b32_e64 v37, v46, v51, s[4:5]
	v_lshl_add_u64 v[44:45], v[44:45], 0, v[118:119]
	global_store_dwordx4 v[44:45], v[36:39], off nt
	v_cndmask_b32_e64 v41, v51, v47, s[4:5]
	v_cvt_pk_f16_f32 v32, v32, v33
	v_add_co_u32_e32 v36, vcc, s1, v44
	v_cvt_pk_f16_f32 v24, v24, v25
	s_nop 0
	v_addc_co_u32_e32 v37, vcc, 0, v45, vcc
	v_cvt_pk_f16_f32 v28, v28, v29
	v_cvt_pk_f16_f32 v29, v20, v21
	global_store_dwordx4 v[36:37], v[40:43], off nt
	v_cvt_pk_f16_f32 v34, v34, v35
	v_cvt_pk_f16_f32 v26, v26, v27
	v_cndmask_b32_e64 v25, v24, v32, s[4:5]
	v_cndmask_b32_e64 v20, v29, v28, s[4:5]
	v_mov_b32_e32 v33, v3
	v_mov_b32_e32 v36, v3
	v_cndmask_b32_e64 v27, v26, v34, s[4:5]
	v_cvt_pk_f16_f32 v30, v30, v31
	v_cvt_pk_f16_f32 v31, v22, v23
	v_mov_b32_dpp v33, v20 row_ror:8 row_mask:0xf bank_mask:0xf
	v_mov_b32_dpp v36, v25 row_ror:8 row_mask:0xf bank_mask:0xf
	v_mov_b32_e32 v25, v3
	v_cvt_pk_f16_f32 v16, v16, v17
	v_cvt_pk_f16_f32 v17, v4, v5
	v_cvt_pk_f16_f32 v5, v14, v15
	v_cvt_pk_f16_f32 v14, v10, v11
	v_cvt_pk_f16_f32 v10, v12, v13
	v_cvt_pk_f16_f32 v8, v8, v9
	v_cndmask_b32_e64 v22, v31, v30, s[4:5]
	v_mov_b32_e32 v35, v3
	v_mov_b32_dpp v25, v27 row_ror:8 row_mask:0xf bank_mask:0xf
	v_cndmask_b32_e64 v20, v28, v33, s[4:5]
	v_add_u32_e32 v28, 0xa0, v146
	v_cndmask_b32_e64 v9, v8, v10, s[4:5]
	v_mov_b32_e32 v12, v3
	v_mov_b32_dpp v35, v22 row_ror:8 row_mask:0xf bank_mask:0xf
	v_cndmask_b32_e64 v27, v25, v26, s[4:5]
	v_cndmask_b32_e64 v26, v36, v24, s[4:5]
	v_cndmask_b32_e64 v24, v33, v29, s[4:5]
	v_mad_i64_i32 v[28:29], s[14:15], v28, s35, v[116:117]
	v_cvt_pk_f16_f32 v18, v18, v19
	v_cvt_pk_f16_f32 v19, v6, v7
	v_cndmask_b32_e64 v4, v17, v16, s[4:5]
	v_mov_b32_dpp v12, v9 row_ror:8 row_mask:0xf bank_mask:0xf
	v_mov_b32_e32 v13, v3
	v_cndmask_b32_e64 v23, v34, v25, s[4:5]
	v_cndmask_b32_e64 v22, v32, v36, s[4:5]
	v_cndmask_b32_e64 v21, v30, v35, s[4:5]
	v_lshl_add_u64 v[28:29], v[28:29], 0, v[118:119]
	v_cndmask_b32_e64 v6, v19, v18, s[4:5]
	v_cndmask_b32_e64 v7, v14, v5, s[4:5]
	v_mov_b32_e32 v9, v3
	v_mov_b32_dpp v13, v4 row_ror:8 row_mask:0xf bank_mask:0xf
	v_mov_b32_e32 v11, v3
	v_cndmask_b32_e64 v4, v10, v12, s[4:5]
	v_cndmask_b32_e64 v8, v12, v8, s[4:5]
	v_add_u32_e32 v12, 0xb0, v146
	global_store_dwordx4 v[28:29], v[20:23], off nt
	v_mov_b32_dpp v9, v7 row_ror:8 row_mask:0xf bank_mask:0xf
	v_mov_b32_dpp v11, v6 row_ror:8 row_mask:0xf bank_mask:0xf
	v_add_co_u32_e32 v20, vcc, s1, v28
	v_cndmask_b32_e64 v6, v16, v13, s[4:5]
	v_cndmask_b32_e64 v10, v13, v17, s[4:5]
	v_mad_i64_i32 v[12:13], s[14:15], v12, s35, v[116:117]
	v_addc_co_u32_e32 v21, vcc, 0, v29, vcc
	v_cndmask_b32_e64 v7, v18, v11, s[4:5]
	v_cndmask_b32_e64 v5, v5, v9, s[4:5]
	v_lshl_add_u64 v[12:13], v[12:13], 0, v[118:119]
	global_store_dwordx4 v[12:13], v[4:7], off nt
	v_cndmask_b32_e64 v25, v35, v31, s[4:5]
	v_cndmask_b32_e64 v11, v11, v19, s[4:5]
	v_add_co_u32_e32 v4, vcc, 0x3c000, v12
	v_cndmask_b32_e64 v9, v9, v14, s[4:5]
	s_nop 0
	v_addc_co_u32_e32 v5, vcc, 0, v13, vcc
	s_and_b64 vcc, exec, s[6:7]
	s_mov_b32 s48, s0
	s_mov_b32 s49, s8
	s_mov_b64 s[18:19], s[12:13]
	s_mov_b64 s[14:15], s[10:11]
	global_store_dwordx4 v[20:21], v[24:27], off nt
	global_store_dwordx4 v[4:5], v[8:11], off nt
	s_cbranch_vccz .LBB0_329
	s_waitcnt vmcnt(0)
	v_readlane_b32 s42, v251, 7
	v_readlane_b32 s46, v251, 9
	v_readlane_b32 s48, v251, 13
	s_cmpk_gt_u32 s20, 0xff
	v_readlane_b32 s43, v251, 8
	v_readlane_b32 s47, v251, 10
	v_readlane_b32 s49, v251, 14
	s_cbranch_scc1 .LBB0_336
	s_barrier

; #define PG8_STAGE(bufoff, gbase, voff) do { _Pragma("unroll") for (int _i = 0; _i < 2; ++_i) \
;         __builtin_amdgcn_global_load_lds((const unsigned*)((const char*)(gbase) + (voff)[_i]), (LAS unsigned*)(lds + (bufoff) + ldsw + _i * 8192), 16, 0, 0); } while (0)
; #define PG8_LDA(dst, b, h) do { _Pragma("unroll") for (int m = 0; m < 4; ++m) _Pragma("unroll") for (int k = 0; k < 2; ++k) dst[m][k] = *(const LAS h8*)(lds + PG8_SA(b, h) + aoff + m * 2048 + k * 1024); } while (0)
; #define PG8_LDB(dst, b, h) do { _Pragma("unroll") for (int n = 0; n < 2; ++n) _Pragma("unroll") for (int k = 0; k < 2; ++k) dst[n][k] = *(const LAS h8*)(lds + PG8_SB(b, h) + boff + n * 2048 + k * 1024); } while (0)
; #define PG8_WAIT_L(n) asm volatile("s_waitcnt lgkmcnt(" #n ")" ::: "memory")
; #define PG8_BAR __builtin_amdgcn_s_barrier()
; #define PG8_SCHED __builtin_amdgcn_sched_barrier(0)
; template <class Epi>
; __device__ __forceinline__ void gemm_phase(LAS unsigned char* lds, const Gemm g, const StaticOrder& S, const Epi& E, const int tid) {
;     ...
;         for (int t = 0; t < nt; t += 2) {
;             const bool last = (t == nt - 2);
;             const char* a1 = cA + (size_t)(t + 1) * kstep;
;             const char* a2 = last ? nA : cA + (size_t)(t + 2) * kstep; const char* b2 = last ? nB : cB + (size_t)(t + 2) * kstep;
;             const char* a3 = a2 + kstep; const char* b3 = b2 + kstep;
;             if constexpr (Epi::HAS_MID) { if (t == (nt >> 1)) E.mid(acc, cur, wr, wc, fr, fq); }
;             PG8_LDB(B0, 0, 0); PG8_SCHED; PG8_LDA(At, 0, 0); PG8_STAGE(PG8_SA(1, 1), a1 + hstep, voffA);
;             PG8_WAIT_L(8); PG8_BAR; PG8_WAIT_L(0); PG8_MMA(0, 0, At, B0); PG8_BAR; PG8_SCHED;
;             PG8_LDB(B1, 0, 1); PG8_STAGE(PG8_SB(0, 0), b2, voffB);
;             PG8_BAR; PG8_WAIT_L(0); PG8_MMA(0, 1, At, B1); PG8_BAR;
;             PG8_LDA(At, 0, 1); PG8_STAGE(PG8_SA(0, 0), a2, voffA);
;             PG8_BAR; PG8_WAIT_L(0); PG8_MMA(1, 0, At, B0); PG8_BAR; PG8_SCHED;
.LBB0_594:
	s_add_u32 s14, s10, s12
	s_addc_u32 s15, s11, s13
	s_add_u32 s14, s14, 0x100
	s_addc_u32 s15, s15, 0
	s_add_u32 s55, s52, s12
	s_addc_u32 s56, s53, s13
	s_cmpk_eq_i32 s12, 0x1f00
	s_cselect_b32 s19, s5, s15
	s_cselect_b32 s18, s50, s14
	s_cselect_b32 s15, s1, s56
	s_cselect_b32 s14, s51, s55
	s_add_i32 s55, 0, 0x10000
	v_add_u32_e32 v0, s55, v189
	ds_read_b128 v[132:135], v0
	ds_read_b128 v[136:139], v0 offset:1024
	ds_read_b128 v[176:179], v0 offset:2048
	ds_read_b128 v[192:195], v0 offset:3072
	v_lshl_add_u64 v[0:1], v[172:173], 0, s[12:13]
	s_add_i32 m0, s25, 0xc000
	ds_read_b128 v[196:199], v191
	ds_read_b128 v[200:203], v191 offset:1024
	ds_read_b128 v[204:207], v191 offset:2048
	ds_read_b128 v[208:211], v191 offset:3072
	ds_read_b128 v[212:215], v191 offset:4096
	ds_read_b128 v[216:219], v191 offset:5120
	ds_read_b128 v[220:223], v191 offset:6144
	ds_read_b128 v[224:227], v191 offset:7168
	global_load_lds_dwordx4 v[0:1], off
	s_add_i32 m0, s25, 0xe000
	v_lshl_add_u64 v[0:1], v[174:175], 0, s[12:13]
	global_load_lds_dwordx4 v[0:1], off
	s_waitcnt lgkmcnt(8)
	s_barrier
	s_waitcnt lgkmcnt(0)
	s_waitcnt lgkmcnt(0)
	v_mfma_f32_16x16x32_bf16 v[128:131], v[132:135], v[196:199], v[128:131]
	v_mfma_f32_16x16x32_bf16 v[124:127], v[176:179], v[196:199], v[124:127]
	v_mfma_f32_16x16x32_bf16 v[112:115], v[132:135], v[204:207], v[112:115]
	v_mfma_f32_16x16x32_bf16 v[108:111], v[176:179], v[204:207], v[108:111]
	v_mfma_f32_16x16x32_bf16 v[96:99], v[132:135], v[212:215], v[96:99]
	v_mfma_f32_16x16x32_bf16 v[92:95], v[176:179], v[212:215], v[92:95]
	v_mfma_f32_16x16x32_bf16 v[80:83], v[132:135], v[220:223], v[80:83]
	v_mfma_f32_16x16x32_bf16 v[76:79], v[176:179], v[220:223], v[76:79]
	v_mfma_f32_16x16x32_bf16 v[128:131], v[136:139], v[200:203], v[128:131]
	v_mfma_f32_16x16x32_bf16 v[124:127], v[192:195], v[200:203], v[124:127]
	v_mfma_f32_16x16x32_bf16 v[112:115], v[136:139], v[208:211], v[112:115]
	v_mfma_f32_16x16x32_bf16 v[108:111], v[192:195], v[208:211], v[108:111]
	v_mfma_f32_16x16x32_bf16 v[96:99], v[136:139], v[216:219], v[96:99]
	v_mfma_f32_16x16x32_bf16 v[92:95], v[192:195], v[216:219], v[92:95]
	v_mfma_f32_16x16x32_bf16 v[80:83], v[136:139], v[224:227], v[80:83]
	v_mfma_f32_16x16x32_bf16 v[76:79], v[192:195], v[224:227], v[76:79]
	s_barrier
	s_add_i32 s58, 0, 0x14000
	v_add_u32_e32 v0, s58, v189
	s_add_i32 s55, s55, s24
	ds_read_b128 v[228:231], v0
	ds_read_b128 v[232:235], v0 offset:1024
	ds_read_b128 v[236:239], v0 offset:2048
	ds_read_b128 v[240:243], v0 offset:3072
	v_lshl_add_u64 v[0:1], s[14:15], 0, v[144:145]
	s_mov_b32 m0, s55
	v_lshl_add_u64 v[244:245], s[14:15], 0, v[140:141]
	global_load_lds_dwordx4 v[0:1], off
	s_add_i32 m0, s55, 0x2000
	s_nop 0
	global_load_lds_dwordx4 v[244:245], off
	s_barrier
	s_waitcnt lgkmcnt(0)
	s_waitcnt lgkmcnt(0)
	v_mfma_f32_16x16x32_bf16 v[120:123], v[228:231], v[196:199], v[120:123]
	v_mfma_f32_16x16x32_bf16 v[116:119], v[236:239], v[196:199], v[116:119]
	v_mfma_f32_16x16x32_bf16 v[104:107], v[228:231], v[204:207], v[104:107]
	v_mfma_f32_16x16x32_bf16 v[100:103], v[236:239], v[204:207], v[100:103]
	v_mfma_f32_16x16x32_bf16 v[88:91], v[228:231], v[212:215], v[88:91]
	v_mfma_f32_16x16x32_bf16 v[84:87], v[236:239], v[212:215], v[84:87]
	v_mfma_f32_16x16x32_bf16 v[72:75], v[228:231], v[220:223], v[72:75]
	v_mfma_f32_16x16x32_bf16 v[68:71], v[236:239], v[220:223], v[68:71]
	v_mfma_f32_16x16x32_bf16 v[120:123], v[232:235], v[200:203], v[120:123]
	v_mfma_f32_16x16x32_bf16 v[116:119], v[240:243], v[200:203], v[116:119]
	v_mfma_f32_16x16x32_bf16 v[104:107], v[232:235], v[208:211], v[104:107]
	v_mfma_f32_16x16x32_bf16 v[100:103], v[240:243], v[208:211], v[100:103]
	v_mfma_f32_16x16x32_bf16 v[88:91], v[232:235], v[216:219], v[88:91]
	v_mfma_f32_16x16x32_bf16 v[84:87], v[240:243], v[216:219], v[84:87]
	v_mfma_f32_16x16x32_bf16 v[72:75], v[232:235], v[224:227], v[72:75]
	v_mfma_f32_16x16x32_bf16 v[68:71], v[240:243], v[224:227], v[68:71]
	s_mov_b32 m0, s25
	v_lshl_add_u64 v[246:247], s[18:19], 0, v[146:147]
	s_barrier
	ds_read_b128 v[196:199], v191 offset:16384
	ds_read_b128 v[200:203], v191 offset:17408
	ds_read_b128 v[204:207], v191 offset:18432
	ds_read_b128 v[208:211], v191 offset:19456
	ds_read_b128 v[212:215], v191 offset:20480
	ds_read_b128 v[216:219], v191 offset:21504
	ds_read_b128 v[220:223], v191 offset:22528
	ds_read_b128 v[224:227], v191 offset:23552
	global_load_lds_dwordx4 v[246:247], off
	s_mov_b32 m0, s42
	v_lshl_add_u64 v[248:249], s[18:19], 0, v[142:143]
	global_load_lds_dwordx4 v[248:249], off
	s_barrier
	s_waitcnt lgkmcnt(0)
	s_waitcnt lgkmcnt(0)
	v_mfma_f32_16x16x32_bf16 v[64:67], v[132:135], v[196:199], v[64:67]
	v_mfma_f32_16x16x32_bf16 v[60:63], v[176:179], v[196:199], v[60:63]
	v_mfma_f32_16x16x32_bf16 v[48:51], v[132:135], v[204:207], v[48:51]
	v_mfma_f32_16x16x32_bf16 v[44:47], v[176:179], v[204:207], v[44:47]
	v_mfma_f32_16x16x32_bf16 v[32:35], v[132:135], v[212:215], v[32:35]
	v_mfma_f32_16x16x32_bf16 v[28:31], v[176:179], v[212:215], v[28:31]
	v_mfma_f32_16x16x32_bf16 v[16:19], v[132:135], v[220:223], v[16:19]
	v_mfma_f32_16x16x32_bf16 v[12:15], v[176:179], v[220:223], v[12:15]
	v_mfma_f32_16x16x32_bf16 v[64:67], v[136:139], v[200:203], v[64:67]
	v_mfma_f32_16x16x32_bf16 v[60:63], v[192:195], v[200:203], v[60:63]
	v_mfma_f32_16x16x32_bf16 v[48:51], v[136:139], v[208:211], v[48:51]
	v_mfma_f32_16x16x32_bf16 v[44:47], v[192:195], v[208:211], v[44:47]
	v_mfma_f32_16x16x32_bf16 v[32:35], v[136:139], v[216:219], v[32:35]
	v_mfma_f32_16x16x32_bf16 v[28:31], v[192:195], v[216:219], v[28:31]
	v_mfma_f32_16x16x32_bf16 v[16:19], v[136:139], v[224:227], v[16:19]
	v_mfma_f32_16x16x32_bf16 v[12:15], v[192:195], v[224:227], v[12:15]
	s_barrier
; #define PG8_STAGE(bufoff, gbase, voff) do { _Pragma("unroll") for (int _i = 0; _i < 2; ++_i) \
;         __builtin_amdgcn_global_load_lds((const unsigned*)((const char*)(gbase) + (voff)[_i]), (LAS unsigned*)(lds + (bufoff) + ldsw + _i * 8192), 16, 0, 0); } while (0)
; #define PG8_LDA(dst, b, h) do { _Pragma("unroll") for (int m = 0; m < 4; ++m) _Pragma("unroll") for (int k = 0; k < 2; ++k) dst[m][k] = *(const LAS h8*)(lds + PG8_SA(b, h) + aoff + m * 2048 + k * 1024); } while (0)
; #define PG8_LDB(dst, b, h) do { _Pragma("unroll") for (int n = 0; n < 2; ++n) _Pragma("unroll") for (int k = 0; k < 2; ++k) dst[n][k] = *(const LAS h8*)(lds + PG8_SB(b, h) + boff + n * 2048 + k * 1024); } while (0)
; #define PG8_WAIT_V(n) asm volatile("s_waitcnt vmcnt(" #n ")" ::: "memory")
; #define PG8_WAIT_L(n) asm volatile("s_waitcnt lgkmcnt(" #n ")" ::: "memory")
; #define PG8_BAR __builtin_amdgcn_s_barrier()
; #define PG8_SCHED __builtin_amdgcn_sched_barrier(0)
; template <class Epi>
; __device__ __forceinline__ void gemm_phase(LAS unsigned char* lds, const Gemm g, const StaticOrder& S, const Epi& E, const int tid) {
;     ...
;             PG8_STAGE(PG8_SB(0, 1), b2 + hstepB, voffB);
;             PG8_WAIT_V(6); PG8_BAR; PG8_MMA(1, 1, At, B1); PG8_BAR;
;             PG8_LDB(B0, 1, 0); PG8_SCHED; PG8_LDA(At, 1, 0); PG8_STAGE(PG8_SA(0, 1), a2 + hstep, voffA);
;             PG8_WAIT_L(8); PG8_BAR; PG8_WAIT_L(0); PG8_MMA(0, 0, At, B0); PG8_BAR; PG8_SCHED;
;             PG8_LDB(B1, 1, 1); PG8_STAGE(PG8_SB(1, 0), b3, voffB);
;             PG8_BAR; PG8_WAIT_L(0); PG8_MMA(0, 1, At, B1); PG8_BAR;
	s_add_u32 s56, s14, 0x100000
	s_addc_u32 s57, s15, 0
	s_add_i32 s55, s58, s24
	s_mov_b32 m0, s55
	v_lshl_add_u64 v[132:133], s[56:57], 0, v[144:145]
	global_load_lds_dwordx4 v[132:133], off
	s_add_i32 m0, s55, 0x2000
	v_lshl_add_u64 v[132:133], s[56:57], 0, v[140:141]
	global_load_lds_dwordx4 v[132:133], off
	s_waitcnt vmcnt(6)
	s_barrier
	v_mfma_f32_16x16x32_bf16 v[56:59], v[228:231], v[196:199], v[56:59]
	v_mfma_f32_16x16x32_bf16 v[52:55], v[236:239], v[196:199], v[52:55]
	v_mfma_f32_16x16x32_bf16 v[40:43], v[228:231], v[204:207], v[40:43]
	v_mfma_f32_16x16x32_bf16 v[36:39], v[236:239], v[204:207], v[36:39]
	v_mfma_f32_16x16x32_bf16 v[24:27], v[228:231], v[212:215], v[24:27]
	v_mfma_f32_16x16x32_bf16 v[20:23], v[236:239], v[212:215], v[20:23]
	v_mfma_f32_16x16x32_bf16 v[8:11], v[228:231], v[220:223], v[8:11]
	v_mfma_f32_16x16x32_bf16 v[4:7], v[236:239], v[220:223], v[4:7]
	v_mfma_f32_16x16x32_bf16 v[56:59], v[232:235], v[200:203], v[56:59]
	v_mfma_f32_16x16x32_bf16 v[52:55], v[240:243], v[200:203], v[52:55]
	v_mfma_f32_16x16x32_bf16 v[40:43], v[232:235], v[208:211], v[40:43]
	v_mfma_f32_16x16x32_bf16 v[36:39], v[240:243], v[208:211], v[36:39]
	v_mfma_f32_16x16x32_bf16 v[24:27], v[232:235], v[216:219], v[24:27]
	v_mfma_f32_16x16x32_bf16 v[20:23], v[240:243], v[216:219], v[20:23]
	v_mfma_f32_16x16x32_bf16 v[8:11], v[232:235], v[224:227], v[8:11]
	v_mfma_f32_16x16x32_bf16 v[4:7], v[240:243], v[224:227], v[4:7]
	s_add_i32 s55, 0, 0x18000
	v_add_u32_e32 v2, s55, v189
	s_barrier
	ds_read_b128 v[132:135], v2
	ds_read_b128 v[136:139], v2 offset:1024
	ds_read_b128 v[176:179], v2 offset:2048
	ds_read_b128 v[192:195], v2 offset:3072
	s_add_u32 s18, s18, 0x100000
	s_addc_u32 s19, s19, 0
	s_mov_b32 m0, s43
	v_lshl_add_u64 v[228:229], s[18:19], 0, v[146:147]
	ds_read_b128 v[196:199], v191 offset:32768
	ds_read_b128 v[200:203], v191 offset:33792
	ds_read_b128 v[204:207], v191 offset:34816
	ds_read_b128 v[208:211], v191 offset:35840
	ds_read_b128 v[212:215], v191 offset:36864
	ds_read_b128 v[216:219], v191 offset:37888
	ds_read_b128 v[220:223], v191 offset:38912
	ds_read_b128 v[224:227], v191 offset:39936
	global_load_lds_dwordx4 v[228:229], off
	s_mov_b32 m0, s46
	v_lshl_add_u64 v[228:229], s[18:19], 0, v[142:143]
	global_load_lds_dwordx4 v[228:229], off
	s_waitcnt lgkmcnt(8)
	s_barrier
	s_waitcnt lgkmcnt(0)
	s_waitcnt lgkmcnt(0)
	v_mfma_f32_16x16x32_bf16 v[128:131], v[132:135], v[196:199], v[128:131]
	v_mfma_f32_16x16x32_bf16 v[124:127], v[176:179], v[196:199], v[124:127]
	v_mfma_f32_16x16x32_bf16 v[112:115], v[132:135], v[204:207], v[112:115]
	v_mfma_f32_16x16x32_bf16 v[108:111], v[176:179], v[204:207], v[108:111]
	v_mfma_f32_16x16x32_bf16 v[96:99], v[132:135], v[212:215], v[96:99]
	v_mfma_f32_16x16x32_bf16 v[92:95], v[176:179], v[212:215], v[92:95]
	v_mfma_f32_16x16x32_bf16 v[80:83], v[132:135], v[220:223], v[80:83]
	v_mfma_f32_16x16x32_bf16 v[76:79], v[176:179], v[220:223], v[76:79]
	v_mfma_f32_16x16x32_bf16 v[128:131], v[136:139], v[200:203], v[128:131]
	v_mfma_f32_16x16x32_bf16 v[124:127], v[192:195], v[200:203], v[124:127]
	v_mfma_f32_16x16x32_bf16 v[112:115], v[136:139], v[208:211], v[112:115]
	v_mfma_f32_16x16x32_bf16 v[108:111], v[192:195], v[208:211], v[108:111]
	v_mfma_f32_16x16x32_bf16 v[96:99], v[136:139], v[216:219], v[96:99]
	v_mfma_f32_16x16x32_bf16 v[92:95], v[192:195], v[216:219], v[92:95]
	v_mfma_f32_16x16x32_bf16 v[80:83], v[136:139], v[224:227], v[80:83]
	v_mfma_f32_16x16x32_bf16 v[76:79], v[192:195], v[224:227], v[76:79]
	s_barrier
	s_add_i32 s18, 0, 0x1c000
	s_add_i32 s19, s55, s24
	v_add_u32_e32 v2, s18, v189
	v_lshl_add_u64 v[0:1], v[0:1], 0, s[30:31]
	s_mov_b32 m0, s19
	ds_read_b128 v[228:231], v2
	ds_read_b128 v[232:235], v2 offset:1024
	ds_read_b128 v[236:239], v2 offset:2048
	ds_read_b128 v[240:243], v2 offset:3072
	global_load_lds_dwordx4 v[0:1], off
	s_add_i32 m0, s19, 0x2000
	v_lshl_add_u64 v[0:1], v[244:245], 0, s[30:31]
	global_load_lds_dwordx4 v[0:1], off
	s_barrier
; #define PG8_STAGE(bufoff, gbase, voff) do { _Pragma("unroll") for (int _i = 0; _i < 2; ++_i) \
;         __builtin_amdgcn_global_load_lds((const unsigned*)((const char*)(gbase) + (voff)[_i]), (LAS unsigned*)(lds + (bufoff) + ldsw + _i * 8192), 16, 0, 0); } while (0)
; #define PG8_LDA(dst, b, h) do { _Pragma("unroll") for (int m = 0; m < 4; ++m) _Pragma("unroll") for (int k = 0; k < 2; ++k) dst[m][k] = *(const LAS h8*)(lds + PG8_SA(b, h) + aoff + m * 2048 + k * 1024); } while (0)
; #define PG8_WAIT_V(n) asm volatile("s_waitcnt vmcnt(" #n ")" ::: "memory")
; #define PG8_WAIT_L(n) asm volatile("s_waitcnt lgkmcnt(" #n ")" ::: "memory")
; #define PG8_BAR __builtin_amdgcn_s_barrier()
; #define PG8_SCHED __builtin_amdgcn_sched_barrier(0)
; template <class Epi>
; __device__ __forceinline__ void gemm_phase(LAS unsigned char* lds, const Gemm g, const StaticOrder& S, const Epi& E, const int tid) {
;     ...
;             PG8_BAR; PG8_WAIT_L(0); PG8_MMA(0, 1, At, B1); PG8_BAR;
;             PG8_LDA(At, 1, 1); PG8_STAGE(PG8_SA(1, 0), a3, voffA);
;             PG8_BAR; PG8_WAIT_L(0); PG8_MMA(1, 0, At, B0); PG8_BAR; PG8_SCHED;
;             PG8_STAGE(PG8_SB(1, 1), b3 + hstepB, voffB);
;             PG8_WAIT_V(6); PG8_BAR; PG8_MMA(1, 1, At, B1); PG8_BAR;
	s_waitcnt lgkmcnt(0)
	s_waitcnt lgkmcnt(0)
	v_mfma_f32_16x16x32_bf16 v[120:123], v[228:231], v[196:199], v[120:123]
	v_mfma_f32_16x16x32_bf16 v[116:119], v[236:239], v[196:199], v[116:119]
	v_mfma_f32_16x16x32_bf16 v[104:107], v[228:231], v[204:207], v[104:107]
	v_mfma_f32_16x16x32_bf16 v[100:103], v[236:239], v[204:207], v[100:103]
	v_mfma_f32_16x16x32_bf16 v[88:91], v[228:231], v[212:215], v[88:91]
	v_mfma_f32_16x16x32_bf16 v[84:87], v[236:239], v[212:215], v[84:87]
	v_mfma_f32_16x16x32_bf16 v[72:75], v[228:231], v[220:223], v[72:75]
	v_mfma_f32_16x16x32_bf16 v[68:71], v[236:239], v[220:223], v[68:71]
	v_mfma_f32_16x16x32_bf16 v[120:123], v[232:235], v[200:203], v[120:123]
	v_mfma_f32_16x16x32_bf16 v[116:119], v[240:243], v[200:203], v[116:119]
	v_mfma_f32_16x16x32_bf16 v[104:107], v[232:235], v[208:211], v[104:107]
	v_mfma_f32_16x16x32_bf16 v[100:103], v[240:243], v[208:211], v[100:103]
	v_mfma_f32_16x16x32_bf16 v[88:91], v[232:235], v[216:219], v[88:91]
	v_mfma_f32_16x16x32_bf16 v[84:87], v[240:243], v[216:219], v[84:87]
	v_mfma_f32_16x16x32_bf16 v[72:75], v[232:235], v[224:227], v[72:75]
	v_mfma_f32_16x16x32_bf16 v[68:71], v[240:243], v[224:227], v[68:71]
	s_mov_b32 m0, s47
	v_lshl_add_u64 v[0:1], v[246:247], 0, s[30:31]
	s_barrier
	ds_read_b128 v[196:199], v191 offset:49152
	ds_read_b128 v[200:203], v191 offset:50176
	ds_read_b128 v[204:207], v191 offset:51200
	ds_read_b128 v[208:211], v191 offset:52224
	ds_read_b128 v[212:215], v191 offset:53248
	ds_read_b128 v[216:219], v191 offset:54272
	ds_read_b128 v[220:223], v191 offset:55296
	ds_read_b128 v[224:227], v191 offset:56320
	global_load_lds_dwordx4 v[0:1], off
	s_mov_b32 m0, s48
	v_lshl_add_u64 v[0:1], v[248:249], 0, s[30:31]
	global_load_lds_dwordx4 v[0:1], off
	s_barrier
	s_waitcnt lgkmcnt(0)
	s_waitcnt lgkmcnt(0)
	v_mfma_f32_16x16x32_bf16 v[64:67], v[132:135], v[196:199], v[64:67]
	v_mfma_f32_16x16x32_bf16 v[60:63], v[176:179], v[196:199], v[60:63]
	v_mfma_f32_16x16x32_bf16 v[48:51], v[132:135], v[204:207], v[48:51]
	v_mfma_f32_16x16x32_bf16 v[44:47], v[176:179], v[204:207], v[44:47]
	v_mfma_f32_16x16x32_bf16 v[32:35], v[132:135], v[212:215], v[32:35]
	v_mfma_f32_16x16x32_bf16 v[28:31], v[176:179], v[212:215], v[28:31]
	v_mfma_f32_16x16x32_bf16 v[16:19], v[132:135], v[220:223], v[16:19]
	v_mfma_f32_16x16x32_bf16 v[12:15], v[176:179], v[220:223], v[12:15]
	v_mfma_f32_16x16x32_bf16 v[64:67], v[136:139], v[200:203], v[64:67]
	v_mfma_f32_16x16x32_bf16 v[60:63], v[192:195], v[200:203], v[60:63]
	v_mfma_f32_16x16x32_bf16 v[48:51], v[136:139], v[208:211], v[48:51]
	v_mfma_f32_16x16x32_bf16 v[44:47], v[192:195], v[208:211], v[44:47]
	v_mfma_f32_16x16x32_bf16 v[32:35], v[136:139], v[216:219], v[32:35]
	v_mfma_f32_16x16x32_bf16 v[28:31], v[192:195], v[216:219], v[28:31]
	v_mfma_f32_16x16x32_bf16 v[16:19], v[136:139], v[224:227], v[16:19]
	v_mfma_f32_16x16x32_bf16 v[12:15], v[192:195], v[224:227], v[12:15]
	s_barrier
	s_add_u32 s14, s14, 0x100080
	s_addc_u32 s15, s15, 0
	s_add_i32 s18, s18, s24
	s_mov_b32 m0, s18
	v_lshl_add_u64 v[0:1], s[14:15], 0, v[144:145]
	global_load_lds_dwordx4 v[0:1], off
	s_add_i32 m0, s18, 0x2000
	v_lshl_add_u64 v[0:1], s[14:15], 0, v[140:141]
	global_load_lds_dwordx4 v[0:1], off
	s_waitcnt vmcnt(6)
	s_barrier
	v_mfma_f32_16x16x32_bf16 v[56:59], v[228:231], v[196:199], v[56:59]
	v_mfma_f32_16x16x32_bf16 v[52:55], v[236:239], v[196:199], v[52:55]
	v_mfma_f32_16x16x32_bf16 v[40:43], v[228:231], v[204:207], v[40:43]
	v_mfma_f32_16x16x32_bf16 v[36:39], v[236:239], v[204:207], v[36:39]
	v_mfma_f32_16x16x32_bf16 v[24:27], v[228:231], v[212:215], v[24:27]
	v_mfma_f32_16x16x32_bf16 v[20:23], v[236:239], v[212:215], v[20:23]
	v_mfma_f32_16x16x32_bf16 v[8:11], v[228:231], v[220:223], v[8:11]
	v_mfma_f32_16x16x32_bf16 v[4:7], v[236:239], v[220:223], v[4:7]
	v_mfma_f32_16x16x32_bf16 v[56:59], v[232:235], v[200:203], v[56:59]
	v_mfma_f32_16x16x32_bf16 v[52:55], v[240:243], v[200:203], v[52:55]
	v_mfma_f32_16x16x32_bf16 v[40:43], v[232:235], v[208:211], v[40:43]
	v_mfma_f32_16x16x32_bf16 v[36:39], v[240:243], v[208:211], v[36:39]
	v_mfma_f32_16x16x32_bf16 v[24:27], v[232:235], v[216:219], v[24:27]
	v_mfma_f32_16x16x32_bf16 v[20:23], v[240:243], v[216:219], v[20:23]
	v_mfma_f32_16x16x32_bf16 v[8:11], v[232:235], v[224:227], v[8:11]
	v_mfma_f32_16x16x32_bf16 v[4:7], v[240:243], v[224:227], v[4:7]
	s_add_i32 s54, s54, 2
	s_add_u32 s12, s12, 0x100
	s_addc_u32 s13, s13, 0
	s_cmp_gt_u32 s54, 61
	s_barrier
	s_cbranch_scc1 .LBB0_586

; #define PG8_STAGE(bufoff, gbase, voff) do { _Pragma("unroll") for (int _i = 0; _i < 2; ++_i) \
;         __builtin_amdgcn_global_load_lds((const unsigned*)((const char*)(gbase) + (voff)[_i]), (LAS unsigned*)(lds + (bufoff) + ldsw + _i * 8192), 16, 0, 0); } while (0)
; #define PG8_LDA(dst, b, h) do { _Pragma("unroll") for (int m = 0; m < 4; ++m) _Pragma("unroll") for (int k = 0; k < 2; ++k) dst[m][k] = *(const LAS h8*)(lds + PG8_SA(b, h) + aoff + m * 2048 + k * 1024); } while (0)
; #define PG8_LDB(dst, b, h) do { _Pragma("unroll") for (int n = 0; n < 2; ++n) _Pragma("unroll") for (int k = 0; k < 2; ++k) dst[n][k] = *(const LAS h8*)(lds + PG8_SB(b, h) + boff + n * 2048 + k * 1024); } while (0)
; #define PG8_WAIT_L(n) asm volatile("s_waitcnt lgkmcnt(" #n ")" ::: "memory")
; #define PG8_BAR __builtin_amdgcn_s_barrier()
; #define PG8_SCHED __builtin_amdgcn_sched_barrier(0)
; template <class Epi>
; __device__ __forceinline__ void gemm_phase(LAS unsigned char* lds, const Gemm g, const StaticOrder& S, const Epi& E, const int tid) {
;     ...
;         for (int t = 0; t < nt; t += 2) {
;             const bool last = (t == nt - 2);
;             const char* a1 = cA + (size_t)(t + 1) * kstep;
;             const char* a2 = last ? nA : cA + (size_t)(t + 2) * kstep; const char* b2 = last ? nB : cB + (size_t)(t + 2) * kstep;
;             const char* a3 = a2 + kstep; const char* b3 = b2 + kstep;
;             if constexpr (Epi::HAS_MID) { if (t == (nt >> 1)) E.mid(acc, cur, wr, wc, fr, fq); }
;             PG8_LDB(B0, 0, 0); PG8_SCHED; PG8_LDA(At, 0, 0); PG8_STAGE(PG8_SA(1, 1), a1 + hstep, voffA);
;             PG8_WAIT_L(8); PG8_BAR; PG8_WAIT_L(0); PG8_MMA(0, 0, At, B0); PG8_BAR; PG8_SCHED;
;             PG8_LDB(B1, 0, 1); PG8_STAGE(PG8_SB(0, 0), b2, voffB);
;             PG8_BAR; PG8_WAIT_L(0); PG8_MMA(0, 1, At, B1); PG8_BAR;
;             PG8_LDA(At, 0, 1); PG8_STAGE(PG8_SA(0, 0), a2, voffA);
;             PG8_BAR; PG8_WAIT_L(0); PG8_MMA(1, 0, At, B0); PG8_BAR; PG8_SCHED;
.LBB0_660:
	s_add_u32 s14, s12, 0xfff80080
	s_addc_u32 s15, s13, -1
	s_add_i32 s57, 0, 0x10000
	v_add_u32_e32 v64, s57, v190
	ds_read_b128 v[28:31], v64
	ds_read_b128 v[32:35], v64 offset:1024
	ds_read_b128 v[60:63], v64 offset:2048
	ds_read_b128 v[64:67], v64 offset:3072
	s_cmp_eq_u32 s56, 28
	s_cselect_b32 s19, s7, s15
	s_cselect_b32 s18, s52, s14
	s_cselect_b32 s15, s1, s55
	s_cselect_b32 s14, s53, s54
	v_lshl_add_u64 v[174:175], s[12:13], 0, v[166:167]
	s_add_i32 m0, s41, 0xc000
	ds_read_b128 v[170:173], v192
	ds_read_b128 v[194:197], v192 offset:1024
	ds_read_b128 v[198:201], v192 offset:2048
	ds_read_b128 v[202:205], v192 offset:3072
	ds_read_b128 v[206:209], v192 offset:4096
	ds_read_b128 v[210:213], v192 offset:5120
	ds_read_b128 v[214:217], v192 offset:6144
	ds_read_b128 v[218:221], v192 offset:7168
	global_load_lds_dwordx4 v[174:175], off
	s_add_i32 m0, s41, 0xe000
	v_lshl_add_u64 v[174:175], s[12:13], 0, v[168:169]
	global_load_lds_dwordx4 v[174:175], off
	s_waitcnt lgkmcnt(8)
	s_barrier
	s_waitcnt lgkmcnt(0)
	s_waitcnt lgkmcnt(0)
	v_mfma_f32_16x16x32_bf16 v[144:147], v[28:31], v[170:173], v[144:147]
	v_mfma_f32_16x16x32_bf16 v[140:143], v[60:63], v[170:173], v[140:143]
	v_mfma_f32_16x16x32_bf16 v[128:131], v[28:31], v[198:201], v[128:131]
	v_mfma_f32_16x16x32_bf16 v[124:127], v[60:63], v[198:201], v[124:127]
	v_mfma_f32_16x16x32_bf16 v[112:115], v[28:31], v[206:209], v[112:115]
	v_mfma_f32_16x16x32_bf16 v[108:111], v[60:63], v[206:209], v[108:111]
	v_mfma_f32_16x16x32_bf16 v[96:99], v[28:31], v[214:217], v[96:99]
	v_mfma_f32_16x16x32_bf16 v[92:95], v[60:63], v[214:217], v[92:95]
	v_mfma_f32_16x16x32_bf16 v[144:147], v[32:35], v[194:197], v[144:147]
	v_mfma_f32_16x16x32_bf16 v[140:143], v[64:67], v[194:197], v[140:143]
	v_mfma_f32_16x16x32_bf16 v[128:131], v[32:35], v[202:205], v[128:131]
	v_mfma_f32_16x16x32_bf16 v[124:127], v[64:67], v[202:205], v[124:127]
	v_mfma_f32_16x16x32_bf16 v[112:115], v[32:35], v[210:213], v[112:115]
	v_mfma_f32_16x16x32_bf16 v[108:111], v[64:67], v[210:213], v[108:111]
	v_mfma_f32_16x16x32_bf16 v[96:99], v[32:35], v[218:221], v[96:99]
	v_mfma_f32_16x16x32_bf16 v[92:95], v[64:67], v[218:221], v[92:95]
	s_barrier
	s_add_i32 s60, 0, 0x14000
	v_add_u32_e32 v174, s60, v190
	s_add_i32 s57, s57, s40
	ds_read_b128 v[222:225], v174
	ds_read_b128 v[226:229], v174 offset:1024
	ds_read_b128 v[230:233], v174 offset:2048
	ds_read_b128 v[234:237], v174 offset:3072
	v_lshl_add_u64 v[174:175], s[14:15], 0, v[2:3]
	s_mov_b32 m0, s57
	v_lshl_add_u64 v[238:239], s[14:15], 0, v[0:1]
	global_load_lds_dwordx4 v[174:175], off
	s_add_i32 m0, s57, 0x2000
	s_nop 0
	global_load_lds_dwordx4 v[238:239], off
	s_barrier
	s_waitcnt lgkmcnt(0)
	s_waitcnt lgkmcnt(0)
	v_mfma_f32_16x16x32_bf16 v[136:139], v[222:225], v[170:173], v[136:139]
	v_mfma_f32_16x16x32_bf16 v[132:135], v[230:233], v[170:173], v[132:135]
	v_mfma_f32_16x16x32_bf16 v[120:123], v[222:225], v[198:201], v[120:123]
	v_mfma_f32_16x16x32_bf16 v[116:119], v[230:233], v[198:201], v[116:119]
	v_mfma_f32_16x16x32_bf16 v[104:107], v[222:225], v[206:209], v[104:107]
	v_mfma_f32_16x16x32_bf16 v[100:103], v[230:233], v[206:209], v[100:103]
	v_mfma_f32_16x16x32_bf16 v[88:91], v[222:225], v[214:217], v[88:91]
	v_mfma_f32_16x16x32_bf16 v[84:87], v[230:233], v[214:217], v[84:87]
	v_mfma_f32_16x16x32_bf16 v[136:139], v[226:229], v[194:197], v[136:139]
	v_mfma_f32_16x16x32_bf16 v[132:135], v[234:237], v[194:197], v[132:135]
	v_mfma_f32_16x16x32_bf16 v[120:123], v[226:229], v[202:205], v[120:123]
	v_mfma_f32_16x16x32_bf16 v[116:119], v[234:237], v[202:205], v[116:119]
	v_mfma_f32_16x16x32_bf16 v[104:107], v[226:229], v[210:213], v[104:107]
	v_mfma_f32_16x16x32_bf16 v[100:103], v[234:237], v[210:213], v[100:103]
	v_mfma_f32_16x16x32_bf16 v[88:91], v[226:229], v[218:221], v[88:91]
	v_mfma_f32_16x16x32_bf16 v[84:87], v[234:237], v[218:221], v[84:87]
	s_mov_b32 m0, s41
	v_lshl_add_u64 v[240:241], s[18:19], 0, v[164:165]
	s_barrier
	ds_read_b128 v[170:173], v192 offset:16384
	ds_read_b128 v[194:197], v192 offset:17408
	ds_read_b128 v[198:201], v192 offset:18432
	ds_read_b128 v[202:205], v192 offset:19456
	ds_read_b128 v[206:209], v192 offset:20480
	ds_read_b128 v[210:213], v192 offset:21504
	ds_read_b128 v[214:217], v192 offset:22528
	ds_read_b128 v[218:221], v192 offset:23552
	global_load_lds_dwordx4 v[240:241], off
	s_mov_b32 m0, s42
	v_lshl_add_u64 v[242:243], s[18:19], 0, v[162:163]
	global_load_lds_dwordx4 v[242:243], off
	s_barrier
	s_waitcnt lgkmcnt(0)
	s_waitcnt lgkmcnt(0)
	v_mfma_f32_16x16x32_bf16 v[80:83], v[28:31], v[170:173], v[80:83]
	v_mfma_f32_16x16x32_bf16 v[76:79], v[60:63], v[170:173], v[76:79]
	v_mfma_f32_16x16x32_bf16 v[56:59], v[28:31], v[198:201], v[56:59]
	v_mfma_f32_16x16x32_bf16 v[52:55], v[60:63], v[198:201], v[52:55]
	v_mfma_f32_16x16x32_bf16 v[40:43], v[28:31], v[206:209], v[40:43]
	v_mfma_f32_16x16x32_bf16 v[36:39], v[60:63], v[206:209], v[36:39]
	v_mfma_f32_16x16x32_bf16 v[16:19], v[28:31], v[214:217], v[16:19]
	v_mfma_f32_16x16x32_bf16 v[12:15], v[60:63], v[214:217], v[12:15]
	v_mfma_f32_16x16x32_bf16 v[80:83], v[32:35], v[194:197], v[80:83]
	v_mfma_f32_16x16x32_bf16 v[76:79], v[64:67], v[194:197], v[76:79]
	v_mfma_f32_16x16x32_bf16 v[56:59], v[32:35], v[202:205], v[56:59]
	v_mfma_f32_16x16x32_bf16 v[52:55], v[64:67], v[202:205], v[52:55]
	v_mfma_f32_16x16x32_bf16 v[40:43], v[32:35], v[210:213], v[40:43]
	v_mfma_f32_16x16x32_bf16 v[36:39], v[64:67], v[210:213], v[36:39]
	v_mfma_f32_16x16x32_bf16 v[16:19], v[32:35], v[218:221], v[16:19]
	v_mfma_f32_16x16x32_bf16 v[12:15], v[64:67], v[218:221], v[12:15]
	s_barrier
; #define PG8_STAGE(bufoff, gbase, voff) do { _Pragma("unroll") for (int _i = 0; _i < 2; ++_i) \
;         __builtin_amdgcn_global_load_lds((const unsigned*)((const char*)(gbase) + (voff)[_i]), (LAS unsigned*)(lds + (bufoff) + ldsw + _i * 8192), 16, 0, 0); } while (0)
; #define PG8_LDA(dst, b, h) do { _Pragma("unroll") for (int m = 0; m < 4; ++m) _Pragma("unroll") for (int k = 0; k < 2; ++k) dst[m][k] = *(const LAS h8*)(lds + PG8_SA(b, h) + aoff + m * 2048 + k * 1024); } while (0)
; #define PG8_LDB(dst, b, h) do { _Pragma("unroll") for (int n = 0; n < 2; ++n) _Pragma("unroll") for (int k = 0; k < 2; ++k) dst[n][k] = *(const LAS h8*)(lds + PG8_SB(b, h) + boff + n * 2048 + k * 1024); } while (0)
; #define PG8_WAIT_V(n) asm volatile("s_waitcnt vmcnt(" #n ")" ::: "memory")
; #define PG8_WAIT_L(n) asm volatile("s_waitcnt lgkmcnt(" #n ")" ::: "memory")
; #define PG8_BAR __builtin_amdgcn_s_barrier()
; #define PG8_SCHED __builtin_amdgcn_sched_barrier(0)
; template <class Epi>
; __device__ __forceinline__ void gemm_phase(LAS unsigned char* lds, const Gemm g, const StaticOrder& S, const Epi& E, const int tid) {
;     ...
;             PG8_STAGE(PG8_SB(0, 1), b2 + hstepB, voffB);
;             PG8_WAIT_V(6); PG8_BAR; PG8_MMA(1, 1, At, B1); PG8_BAR;
;             PG8_LDB(B0, 1, 0); PG8_SCHED; PG8_LDA(At, 1, 0); PG8_STAGE(PG8_SA(0, 1), a2 + hstep, voffA);
;             PG8_WAIT_L(8); PG8_BAR; PG8_WAIT_L(0); PG8_MMA(0, 0, At, B0); PG8_BAR; PG8_SCHED;
;             PG8_LDB(B1, 1, 1); PG8_STAGE(PG8_SB(1, 0), b3, voffB);
;             PG8_BAR; PG8_WAIT_L(0); PG8_MMA(0, 1, At, B1); PG8_BAR;
;             PG8_LDA(At, 1, 1); PG8_STAGE(PG8_SA(1, 0), a3, voffA);
	s_add_u32 s58, s14, 0x80000
	s_addc_u32 s59, s15, 0
	s_add_i32 s57, s60, s40
	s_mov_b32 m0, s57
	v_lshl_add_u64 v[28:29], s[58:59], 0, v[2:3]
	global_load_lds_dwordx4 v[28:29], off
	s_add_i32 m0, s57, 0x2000
	v_lshl_add_u64 v[28:29], s[58:59], 0, v[0:1]
	global_load_lds_dwordx4 v[28:29], off
	s_waitcnt vmcnt(6)
	s_barrier
	v_mfma_f32_16x16x32_bf16 v[48:51], v[222:225], v[198:201], v[48:51]
	v_mfma_f32_16x16x32_bf16 v[44:47], v[230:233], v[198:201], v[44:47]
	v_mfma_f32_16x16x32_bf16 v[24:27], v[222:225], v[206:209], v[24:27]
	v_mfma_f32_16x16x32_bf16 v[20:23], v[230:233], v[206:209], v[20:23]
	v_mfma_f32_16x16x32_bf16 v[8:11], v[222:225], v[214:217], v[8:11]
	v_mfma_f32_16x16x32_bf16 v[4:7], v[230:233], v[214:217], v[4:7]
	v_mfma_f32_16x16x32_bf16 v[28:31], v[222:225], v[170:173], v[72:75]
	v_mfma_f32_16x16x32_bf16 v[32:35], v[230:233], v[170:173], v[68:71]
	v_mfma_f32_16x16x32_bf16 v[48:51], v[226:229], v[202:205], v[48:51]
	v_mfma_f32_16x16x32_bf16 v[44:47], v[234:237], v[202:205], v[44:47]
	v_mfma_f32_16x16x32_bf16 v[24:27], v[226:229], v[210:213], v[24:27]
	v_mfma_f32_16x16x32_bf16 v[20:23], v[234:237], v[210:213], v[20:23]
	v_mfma_f32_16x16x32_bf16 v[8:11], v[226:229], v[218:221], v[8:11]
	v_mfma_f32_16x16x32_bf16 v[4:7], v[234:237], v[218:221], v[4:7]
	v_mfma_f32_16x16x32_bf16 v[28:31], v[226:229], v[194:197], v[28:31]
	v_mfma_f32_16x16x32_bf16 v[32:35], v[234:237], v[194:197], v[32:35]
	s_add_i32 s57, 0, 0x18000
	v_add_u32_e32 v72, s57, v190
	s_barrier
	ds_read_b128 v[60:63], v72
	ds_read_b128 v[64:67], v72 offset:1024
	ds_read_b128 v[68:71], v72 offset:2048
	ds_read_b128 v[72:75], v72 offset:3072
	s_add_u32 s18, s18, 0x80000
	s_addc_u32 s19, s19, 0
	s_mov_b32 m0, s43
	v_lshl_add_u64 v[222:223], s[18:19], 0, v[164:165]
	ds_read_b128 v[170:173], v192 offset:32768
	ds_read_b128 v[194:197], v192 offset:33792
	ds_read_b128 v[198:201], v192 offset:34816
	ds_read_b128 v[202:205], v192 offset:35840
	ds_read_b128 v[206:209], v192 offset:36864
	ds_read_b128 v[210:213], v192 offset:37888
	ds_read_b128 v[214:217], v192 offset:38912
	ds_read_b128 v[218:221], v192 offset:39936
	global_load_lds_dwordx4 v[222:223], off
	s_mov_b32 m0, s46
	v_lshl_add_u64 v[222:223], s[18:19], 0, v[162:163]
	global_load_lds_dwordx4 v[222:223], off
	s_waitcnt lgkmcnt(8)
	s_barrier
	s_waitcnt lgkmcnt(0)
	s_waitcnt lgkmcnt(0)
	v_mfma_f32_16x16x32_bf16 v[144:147], v[60:63], v[170:173], v[144:147]
	v_mfma_f32_16x16x32_bf16 v[140:143], v[68:71], v[170:173], v[140:143]
	v_mfma_f32_16x16x32_bf16 v[128:131], v[60:63], v[198:201], v[128:131]
	v_mfma_f32_16x16x32_bf16 v[124:127], v[68:71], v[198:201], v[124:127]
	v_mfma_f32_16x16x32_bf16 v[112:115], v[60:63], v[206:209], v[112:115]
	v_mfma_f32_16x16x32_bf16 v[108:111], v[68:71], v[206:209], v[108:111]
	v_mfma_f32_16x16x32_bf16 v[96:99], v[60:63], v[214:217], v[96:99]
	v_mfma_f32_16x16x32_bf16 v[92:95], v[68:71], v[214:217], v[92:95]
	v_mfma_f32_16x16x32_bf16 v[144:147], v[64:67], v[194:197], v[144:147]
	v_mfma_f32_16x16x32_bf16 v[140:143], v[72:75], v[194:197], v[140:143]
	v_mfma_f32_16x16x32_bf16 v[128:131], v[64:67], v[202:205], v[128:131]
	v_mfma_f32_16x16x32_bf16 v[124:127], v[72:75], v[202:205], v[124:127]
	v_mfma_f32_16x16x32_bf16 v[112:115], v[64:67], v[210:213], v[112:115]
	v_mfma_f32_16x16x32_bf16 v[108:111], v[72:75], v[210:213], v[108:111]
	v_mfma_f32_16x16x32_bf16 v[96:99], v[64:67], v[218:221], v[96:99]
	v_mfma_f32_16x16x32_bf16 v[92:95], v[72:75], v[218:221], v[92:95]
	s_barrier
	s_add_i32 s18, 0, 0x1c000
	s_add_i32 s19, s57, s40
	v_add_u32_e32 v193, s18, v190
	v_lshl_add_u64 v[174:175], v[174:175], 0, s[30:31]
	s_mov_b32 m0, s19
	ds_read_b128 v[222:225], v193
	ds_read_b128 v[226:229], v193 offset:1024
	ds_read_b128 v[230:233], v193 offset:2048
	ds_read_b128 v[234:237], v193 offset:3072
	global_load_lds_dwordx4 v[174:175], off
	s_add_i32 m0, s19, 0x2000
	v_lshl_add_u64 v[174:175], v[238:239], 0, s[30:31]
	global_load_lds_dwordx4 v[174:175], off
	s_barrier
	s_waitcnt lgkmcnt(0)
	s_waitcnt lgkmcnt(0)
	v_mfma_f32_16x16x32_bf16 v[136:139], v[222:225], v[170:173], v[136:139]
	v_mfma_f32_16x16x32_bf16 v[132:135], v[230:233], v[170:173], v[132:135]
	v_mfma_f32_16x16x32_bf16 v[120:123], v[222:225], v[198:201], v[120:123]
	v_mfma_f32_16x16x32_bf16 v[116:119], v[230:233], v[198:201], v[116:119]
	v_mfma_f32_16x16x32_bf16 v[104:107], v[222:225], v[206:209], v[104:107]
	v_mfma_f32_16x16x32_bf16 v[100:103], v[230:233], v[206:209], v[100:103]
	v_mfma_f32_16x16x32_bf16 v[88:91], v[222:225], v[214:217], v[88:91]
	v_mfma_f32_16x16x32_bf16 v[84:87], v[230:233], v[214:217], v[84:87]
	v_mfma_f32_16x16x32_bf16 v[136:139], v[226:229], v[194:197], v[136:139]
	v_mfma_f32_16x16x32_bf16 v[132:135], v[234:237], v[194:197], v[132:135]
	v_mfma_f32_16x16x32_bf16 v[120:123], v[226:229], v[202:205], v[120:123]
	v_mfma_f32_16x16x32_bf16 v[116:119], v[234:237], v[202:205], v[116:119]
	v_mfma_f32_16x16x32_bf16 v[104:107], v[226:229], v[210:213], v[104:107]
	v_mfma_f32_16x16x32_bf16 v[100:103], v[234:237], v[210:213], v[100:103]
	v_mfma_f32_16x16x32_bf16 v[88:91], v[226:229], v[218:221], v[88:91]
	v_mfma_f32_16x16x32_bf16 v[84:87], v[234:237], v[218:221], v[84:87]
	s_mov_b32 m0, s47
	v_lshl_add_u64 v[174:175], v[240:241], 0, s[30:31]
	s_barrier
	ds_read_b128 v[170:173], v192 offset:49152
	ds_read_b128 v[194:197], v192 offset:50176
	ds_read_b128 v[198:201], v192 offset:51200
	ds_read_b128 v[202:205], v192 offset:52224
	ds_read_b128 v[206:209], v192 offset:53248
	ds_read_b128 v[210:213], v192 offset:54272
	ds_read_b128 v[214:217], v192 offset:55296
	ds_read_b128 v[218:221], v192 offset:56320
	global_load_lds_dwordx4 v[174:175], off
	s_mov_b32 m0, s48
	v_lshl_add_u64 v[174:175], v[242:243], 0, s[30:31]
	global_load_lds_dwordx4 v[174:175], off
	s_barrier
; #define PG8_STAGE(bufoff, gbase, voff) do { _Pragma("unroll") for (int _i = 0; _i < 2; ++_i) \
;         __builtin_amdgcn_global_load_lds((const unsigned*)((const char*)(gbase) + (voff)[_i]), (LAS unsigned*)(lds + (bufoff) + ldsw + _i * 8192), 16, 0, 0); } while (0)
; #define PG8_WAIT_V(n) asm volatile("s_waitcnt vmcnt(" #n ")" ::: "memory")
; #define PG8_WAIT_L(n) asm volatile("s_waitcnt lgkmcnt(" #n ")" ::: "memory")
; #define PG8_BAR __builtin_amdgcn_s_barrier()
; #define PG8_SCHED __builtin_amdgcn_sched_barrier(0)
; template <class Epi>
; __device__ __forceinline__ void gemm_phase(LAS unsigned char* lds, const Gemm g, const StaticOrder& S, const Epi& E, const int tid) {
;     ...
;             PG8_BAR; PG8_WAIT_L(0); PG8_MMA(1, 0, At, B0); PG8_BAR; PG8_SCHED;
;             PG8_STAGE(PG8_SB(1, 1), b3 + hstepB, voffB);
;             PG8_WAIT_V(6); PG8_BAR; PG8_MMA(1, 1, At, B1); PG8_BAR;
;     __device__ __forceinline__ void operator()(const f32x4 (&acc)[2][2][4][2], const pg8::Unit& u, int wr, int wc, int fr, int fq) const {
;         const int row0 = u.pm * 256 + wr * 64 + fr, col0 = u.pn * 256 + wc * 32 + 8 * fq;
;         const float* gp = gate + (size_t)((u.pm * 256) >> 12) * 6144 + col0;
;         f32x4 gv[2][2];
; #pragma unroll
;         for (int bj = 0; bj < 2; ++bj)
; #pragma unroll
;             for (int n = 0; n < 2; ++n) gv[bj][n] = *(const f32x4*)(gp + bj * 128 + 4 * n);
; #pragma unroll
;         for (int ai = 0; ai < 2; ++ai)
; #pragma unroll
;             for (int m = 0; m < 4; ++m) { const size_t ro = (size_t)(row0 + ai * 128 + m * 16) * DM + col0;
; #pragma unroll
;                 for (int bj = 0; bj < 2; ++bj) {
;                     f32x4 x0, x1;
;                     if (XF32) { x0 = *(const f32x4*)(xin + ro + bj * 128); x1 = *(const f32x4*)(xin + ro + bj * 128 + 4); }
;                     else { const h8 xh = *(const h8*)(H + ro + bj * 128); x0 = (f32x4){(float)xh[0], (float)xh[1], (float)xh[2], (float)xh[3]}; x1 = (f32x4){(float)xh[4], (float)xh[5], (float)xh[6], (float)xh[7]}; }
;                     const f32x4 y0 = x0 + gv[bj][0] * acc[ai][bj][m][0], y1 = x1 + gv[bj][1] * acc[ai][bj][m][1];
	s_waitcnt lgkmcnt(0)
	s_waitcnt lgkmcnt(0)
	v_mfma_f32_16x16x32_bf16 v[80:83], v[60:63], v[170:173], v[80:83]
	v_mfma_f32_16x16x32_bf16 v[76:79], v[68:71], v[170:173], v[76:79]
	v_mfma_f32_16x16x32_bf16 v[56:59], v[60:63], v[198:201], v[56:59]
	v_mfma_f32_16x16x32_bf16 v[52:55], v[68:71], v[198:201], v[52:55]
	v_mfma_f32_16x16x32_bf16 v[40:43], v[60:63], v[206:209], v[40:43]
	v_mfma_f32_16x16x32_bf16 v[36:39], v[68:71], v[206:209], v[36:39]
	v_mfma_f32_16x16x32_bf16 v[16:19], v[60:63], v[214:217], v[16:19]
	v_mfma_f32_16x16x32_bf16 v[12:15], v[68:71], v[214:217], v[12:15]
	v_mfma_f32_16x16x32_bf16 v[80:83], v[64:67], v[194:197], v[80:83]
	v_mfma_f32_16x16x32_bf16 v[76:79], v[72:75], v[194:197], v[76:79]
	v_mfma_f32_16x16x32_bf16 v[56:59], v[64:67], v[202:205], v[56:59]
	v_mfma_f32_16x16x32_bf16 v[52:55], v[72:75], v[202:205], v[52:55]
	v_mfma_f32_16x16x32_bf16 v[40:43], v[64:67], v[210:213], v[40:43]
	v_mfma_f32_16x16x32_bf16 v[36:39], v[72:75], v[210:213], v[36:39]
	v_mfma_f32_16x16x32_bf16 v[16:19], v[64:67], v[218:221], v[16:19]
	v_mfma_f32_16x16x32_bf16 v[12:15], v[72:75], v[218:221], v[12:15]
	s_barrier
	s_add_u32 s14, s14, 0x80080
	s_addc_u32 s15, s15, 0
	s_add_i32 s18, s18, s40
	s_mov_b32 m0, s18
	v_lshl_add_u64 v[60:61], s[14:15], 0, v[2:3]
	global_load_lds_dwordx4 v[60:61], off
	s_add_i32 m0, s18, 0x2000
	v_lshl_add_u64 v[60:61], s[14:15], 0, v[0:1]
	global_load_lds_dwordx4 v[60:61], off
	s_waitcnt vmcnt(6)
	s_barrier
	v_mfma_f32_16x16x32_bf16 v[28:31], v[222:225], v[170:173], v[28:31]
	v_mfma_f32_16x16x32_bf16 v[72:75], v[226:229], v[194:197], v[28:31]
	v_mfma_f32_16x16x32_bf16 v[28:31], v[230:233], v[170:173], v[32:35]
	v_mfma_f32_16x16x32_bf16 v[68:71], v[234:237], v[194:197], v[28:31]
	v_mfma_f32_16x16x32_bf16 v[28:31], v[222:225], v[198:201], v[48:51]
	v_mfma_f32_16x16x32_bf16 v[48:51], v[226:229], v[202:205], v[28:31]
	v_mfma_f32_16x16x32_bf16 v[28:31], v[230:233], v[198:201], v[44:47]
	v_mfma_f32_16x16x32_bf16 v[24:27], v[222:225], v[206:209], v[24:27]
	v_mfma_f32_16x16x32_bf16 v[20:23], v[230:233], v[206:209], v[20:23]
	v_mfma_f32_16x16x32_bf16 v[8:11], v[222:225], v[214:217], v[8:11]
	v_mfma_f32_16x16x32_bf16 v[4:7], v[230:233], v[214:217], v[4:7]
	v_mfma_f32_16x16x32_bf16 v[44:47], v[234:237], v[202:205], v[28:31]
	v_mfma_f32_16x16x32_bf16 v[24:27], v[226:229], v[210:213], v[24:27]
	v_mfma_f32_16x16x32_bf16 v[20:23], v[234:237], v[210:213], v[20:23]
	v_mfma_f32_16x16x32_bf16 v[8:11], v[226:229], v[218:221], v[8:11]
	v_mfma_f32_16x16x32_bf16 v[4:7], v[234:237], v[218:221], v[4:7]
	s_add_i32 s56, s56, 2
	s_add_u32 s12, s12, 0x100
	s_addc_u32 s13, s13, 0
	s_add_u32 s54, s54, 0x100
	s_addc_u32 s55, s55, 0
	s_cmp_gt_u32 s56, 29
	s_barrier
	s_cbranch_scc0 .LBB0_660
	s_ashr_i32 s1, s50, 4
	v_lshl_add_u32 v172, s50, 8, v189
	v_lshl_or_b32 v170, s51, 8, v191
	s_mul_hi_i32 s7, s1, 0x6000
	s_mulk_i32 s1, 0x6000
	v_ashrrev_i32_e32 v173, 31, v172
	s_add_u32 s12, s23, s1
	v_ashrrev_i32_e32 v171, 31, v170
	v_lshlrev_b64 v[174:175], 12, v[172:173]
	s_addc_u32 s13, s24, s7
	v_lshl_add_u64 v[194:195], s[16:17], 0, v[174:175]
	v_lshlrev_b64 v[174:175], 1, v[170:171]
	v_lshl_add_u64 v[32:33], v[170:171], 2, s[12:13]
	v_lshl_add_u64 v[170:171], v[194:195], 0, v[174:175]
	global_load_dwordx4 v[60:63], v[32:33], off offset:16
	global_load_dwordx4 v[64:67], v[32:33], off
	global_load_dwordx4 v[28:31], v[32:33], off offset:528
	s_nop 0
	global_load_dwordx4 v[32:35], v[32:33], off offset:512
	v_add_co_u32_e32 v242, vcc, 0, v170
	s_nop 1
	v_addc_co_u32_e32 v243, vcc, 0, v171, vcc
	global_load_dwordx4 v[202:205], v[242:243], off
	v_add_co_u32_e32 v242, vcc, 0, v170
	s_nop 1
	v_addc_co_u32_e32 v243, vcc, 0, v171, vcc
	global_load_dwordx4 v[206:209], v[242:243], off offset:256
	v_add_co_u32_e32 v242, vcc, 0x10000, v170
	s_nop 1
	v_addc_co_u32_e32 v243, vcc, 0, v171, vcc
	global_load_dwordx4 v[210:213], v[242:243], off
	v_add_co_u32_e32 v242, vcc, 0x10000, v170
	s_nop 1
	v_addc_co_u32_e32 v243, vcc, 0, v171, vcc
	global_load_dwordx4 v[214:217], v[242:243], off offset:256
	v_add_co_u32_e32 v242, vcc, 0x20000, v170
	s_nop 1
	v_addc_co_u32_e32 v243, vcc, 0, v171, vcc
	global_load_dwordx4 v[218:221], v[242:243], off
	v_add_co_u32_e32 v242, vcc, 0x20000, v170
	s_nop 1
	v_addc_co_u32_e32 v243, vcc, 0, v171, vcc
	global_load_dwordx4 v[222:225], v[242:243], off offset:256
	v_add_co_u32_e32 v242, vcc, 0x30000, v170
	s_nop 1
	v_addc_co_u32_e32 v243, vcc, 0, v171, vcc
	global_load_dwordx4 v[226:229], v[242:243], off
	v_add_co_u32_e32 v242, vcc, 0x30000, v170
	s_nop 1
	v_addc_co_u32_e32 v243, vcc, 0, v171, vcc
	global_load_dwordx4 v[230:233], v[242:243], off offset:256
	v_add_co_u32_e32 v242, vcc, 0x80000, v170
	s_nop 1
	v_addc_co_u32_e32 v243, vcc, 0, v171, vcc
	global_load_dwordx4 v[234:237], v[242:243], off
	v_add_co_u32_e32 v242, vcc, 0x80000, v170
	s_nop 1
	v_addc_co_u32_e32 v243, vcc, 0, v171, vcc
	global_load_dwordx4 v[238:241], v[242:243], off offset:256
	v_add_co_u32_e32 v242, vcc, 0x90000, v170
	s_nop 1
	v_addc_co_u32_e32 v243, vcc, 0, v171, vcc
	global_load_dwordx4 v[244:247], v[242:243], off
	s_mov_b32 s1, 0x80000
	s_nop 1
	s_waitcnt vmcnt(10)
;     __device__ __forceinline__ void operator()(const f32x4 (&acc)[2][2][4][2], const pg8::Unit& u, int wr, int wc, int fr, int fq) const {
;     ...
;         for (int ai = 0; ai < 2; ++ai)
; #pragma unroll
;             for (int m = 0; m < 4; ++m) { const size_t ro = (size_t)(row0 + ai * 128 + m * 16) * DM + col0;
; #pragma unroll
;                 for (int bj = 0; bj < 2; ++bj) {
;                     f32x4 x0, x1;
;                     if (XF32) { x0 = *(const f32x4*)(xin + ro + bj * 128); x1 = *(const f32x4*)(xin + ro + bj * 128 + 4); }
;                     else { const h8 xh = *(const h8*)(H + ro + bj * 128); x0 = (f32x4){(float)xh[0], (float)xh[1], (float)xh[2], (float)xh[3]}; x1 = (f32x4){(float)xh[4], (float)xh[5], (float)xh[6], (float)xh[7]}; }
;                     const f32x4 y0 = x0 + gv[bj][0] * acc[ai][bj][m][0], y1 = x1 + gv[bj][1] * acc[ai][bj][m][1];
;                     h8 o; o[0] = (half_t)y0[0]; o[1] = (half_t)y0[1]; o[2] = (half_t)y0[2]; o[3] = (half_t)y0[3]; o[4] = (half_t)y1[0]; o[5] = (half_t)y1[1]; o[6] = (half_t)y1[2]; o[7] = (half_t)y1[3];
;                     *(h8*)(H + ro + bj * 128) = o; } }
	v_mov_b32_e32 v194, v202
	v_mov_b32_e32 v195, v203
	v_mov_b32_e32 v196, v204
	v_mov_b32_e32 v197, v205
	v_add_co_u32_e32 v242, vcc, 0x90000, v170
	s_nop 1
	v_addc_co_u32_e32 v243, vcc, 0, v171, vcc
	global_load_dwordx4 v[202:205], v[242:243], off offset:256
	s_mov_b64 s[12:13], 0x80000
	s_mov_b32 s51, s0
	s_mov_b32 s50, s6
	s_mov_b64 s[14:15], s[10:11]
	v_readlane_b32 s59, v251, 43
	s_nop 0
	v_cvt_f32_f16_e32 v198, v194
	v_cvt_f32_f16_sdwa v199, v194 dst_sel:DWORD dst_unused:UNUSED_PAD src0_sel:WORD_1
	v_cvt_f32_f16_e32 v194, v195
	v_cvt_f32_f16_sdwa v195, v195 dst_sel:DWORD dst_unused:UNUSED_PAD src0_sel:WORD_1
	v_cvt_f32_f16_e32 v200, v196
	v_cvt_f32_f16_sdwa v201, v196 dst_sel:DWORD dst_unused:UNUSED_PAD src0_sel:WORD_1
	v_cvt_f32_f16_e32 v196, v197
	v_cvt_f32_f16_sdwa v197, v197 dst_sel:DWORD dst_unused:UNUSED_PAD src0_sel:WORD_1
	v_pk_fma_f32 v[146:147], v[146:147], v[66:67], v[194:195]
	v_pk_fma_f32 v[144:145], v[144:145], v[64:65], v[198:199]
	v_pk_fma_f32 v[140:141], v[140:141], v[60:61], v[200:201]
	v_pk_fma_f32 v[142:143], v[142:143], v[62:63], v[196:197]
	s_nop 0
	v_cvt_pk_f16_f32 v143, v142, v143
	v_cvt_pk_f16_f32 v142, v140, v141
	v_cvt_pk_f16_f32 v141, v146, v147
	v_cvt_pk_f16_f32 v140, v144, v145
	global_store_dwordx4 v[170:171], v[140:143], off
	s_nop 1
	s_waitcnt vmcnt(10)
	v_mov_b32_e32 v140, v206
	v_mov_b32_e32 v141, v207
	v_mov_b32_e32 v142, v208
	v_mov_b32_e32 v143, v209
	v_add_co_u32_e32 v242, vcc, 0xa0000, v170
	s_nop 1
	v_addc_co_u32_e32 v243, vcc, 0, v171, vcc
	global_load_dwordx4 v[206:209], v[242:243], off
	s_nop 0
	v_cvt_f32_f16_e32 v144, v140
	v_cvt_f32_f16_sdwa v145, v140 dst_sel:DWORD dst_unused:UNUSED_PAD src0_sel:WORD_1
	v_cvt_f32_f16_e32 v140, v141
	v_cvt_f32_f16_sdwa v141, v141 dst_sel:DWORD dst_unused:UNUSED_PAD src0_sel:WORD_1
	v_cvt_f32_f16_e32 v146, v142
	v_cvt_f32_f16_sdwa v147, v142 dst_sel:DWORD dst_unused:UNUSED_PAD src0_sel:WORD_1
	v_cvt_f32_f16_e32 v142, v143
	v_cvt_f32_f16_sdwa v143, v143 dst_sel:DWORD dst_unused:UNUSED_PAD src0_sel:WORD_1
	v_pk_fma_f32 v[138:139], v[138:139], v[34:35], v[140:141]
	v_pk_fma_f32 v[136:137], v[136:137], v[32:33], v[144:145]
	v_pk_fma_f32 v[132:133], v[132:133], v[28:29], v[146:147]
	v_pk_fma_f32 v[134:135], v[134:135], v[30:31], v[142:143]
	s_nop 0
	v_cvt_pk_f16_f32 v135, v134, v135
	v_cvt_pk_f16_f32 v134, v132, v133
	v_cvt_pk_f16_f32 v133, v138, v139
	v_cvt_pk_f16_f32 v132, v136, v137
	global_store_dwordx4 v[170:171], v[132:135], off offset:256
	s_nop 1
	v_or_b32_e32 v132, 16, v172
	v_ashrrev_i32_e32 v133, 31, v132
	v_lshlrev_b64 v[132:133], 12, v[132:133]
	v_lshl_add_u64 v[132:133], s[16:17], 0, v[132:133]
	v_lshl_add_u64 v[136:137], v[132:133], 0, v[174:175]
	s_nop 1
	s_waitcnt vmcnt(10)
	v_mov_b32_e32 v132, v210
	v_mov_b32_e32 v133, v211
	v_mov_b32_e32 v134, v212
	v_mov_b32_e32 v135, v213
	v_add_co_u32_e32 v242, vcc, 0xa0000, v170
	s_nop 1
	v_addc_co_u32_e32 v243, vcc, 0, v171, vcc
	global_load_dwordx4 v[210:213], v[242:243], off offset:256
	s_nop 0
	v_cvt_f32_f16_e32 v138, v132
	v_cvt_f32_f16_sdwa v139, v132 dst_sel:DWORD dst_unused:UNUSED_PAD src0_sel:WORD_1
	v_cvt_f32_f16_e32 v132, v133
	v_cvt_f32_f16_sdwa v133, v133 dst_sel:DWORD dst_unused:UNUSED_PAD src0_sel:WORD_1
	v_cvt_f32_f16_e32 v140, v134
	v_cvt_f32_f16_sdwa v141, v134 dst_sel:DWORD dst_unused:UNUSED_PAD src0_sel:WORD_1
	v_cvt_f32_f16_e32 v134, v135
	v_cvt_f32_f16_sdwa v135, v135 dst_sel:DWORD dst_unused:UNUSED_PAD src0_sel:WORD_1
	v_pk_fma_f32 v[130:131], v[130:131], v[66:67], v[132:133]
	v_pk_fma_f32 v[128:129], v[128:129], v[64:65], v[138:139]
	v_pk_fma_f32 v[124:125], v[124:125], v[60:61], v[140:141]
	v_pk_fma_f32 v[126:127], v[126:127], v[62:63], v[134:135]
	s_nop 0
	v_cvt_pk_f16_f32 v127, v126, v127
	v_cvt_pk_f16_f32 v126, v124, v125
	v_cvt_pk_f16_f32 v125, v130, v131
	v_cvt_pk_f16_f32 v124, v128, v129
	global_store_dwordx4 v[136:137], v[124:127], off
	s_nop 1
	s_waitcnt vmcnt(10)
	v_mov_b32_e32 v124, v214
	v_mov_b32_e32 v125, v215
	v_mov_b32_e32 v126, v216
	v_mov_b32_e32 v127, v217
	v_add_co_u32_e32 v242, vcc, 0xb0000, v170
	s_nop 1
	v_addc_co_u32_e32 v243, vcc, 0, v171, vcc
	global_load_dwordx4 v[214:217], v[242:243], off
	s_nop 0
	v_cvt_f32_f16_e32 v128, v124
	v_cvt_f32_f16_sdwa v129, v124 dst_sel:DWORD dst_unused:UNUSED_PAD src0_sel:WORD_1
	v_cvt_f32_f16_e32 v124, v125
	v_cvt_f32_f16_sdwa v125, v125 dst_sel:DWORD dst_unused:UNUSED_PAD src0_sel:WORD_1
	v_cvt_f32_f16_e32 v130, v126
	v_cvt_f32_f16_sdwa v131, v126 dst_sel:DWORD dst_unused:UNUSED_PAD src0_sel:WORD_1
	v_cvt_f32_f16_e32 v126, v127
	v_cvt_f32_f16_sdwa v127, v127 dst_sel:DWORD dst_unused:UNUSED_PAD src0_sel:WORD_1
	v_pk_fma_f32 v[122:123], v[122:123], v[34:35], v[124:125]
	v_pk_fma_f32 v[120:121], v[120:121], v[32:33], v[128:129]
	v_pk_fma_f32 v[116:117], v[116:117], v[28:29], v[130:131]
	v_pk_fma_f32 v[118:119], v[118:119], v[30:31], v[126:127]
	s_nop 0
	v_cvt_pk_f16_f32 v119, v118, v119
	v_cvt_pk_f16_f32 v118, v116, v117
	v_cvt_pk_f16_f32 v117, v122, v123
	v_cvt_pk_f16_f32 v116, v120, v121
	global_store_dwordx4 v[136:137], v[116:119], off offset:256
	s_nop 1
	v_or_b32_e32 v116, 32, v172
	v_ashrrev_i32_e32 v117, 31, v116
	v_lshlrev_b64 v[116:117], 12, v[116:117]
	v_lshl_add_u64 v[116:117], s[16:17], 0, v[116:117]
	v_lshl_add_u64 v[120:121], v[116:117], 0, v[174:175]
	s_nop 1
	s_waitcnt vmcnt(10)
;     __device__ __forceinline__ void operator()(const f32x4 (&acc)[2][2][4][2], const pg8::Unit& u, int wr, int wc, int fr, int fq) const {
;     ...
;         for (int ai = 0; ai < 2; ++ai)
; #pragma unroll
;             for (int m = 0; m < 4; ++m) { const size_t ro = (size_t)(row0 + ai * 128 + m * 16) * DM + col0;
; #pragma unroll
;                 for (int bj = 0; bj < 2; ++bj) {
;                     f32x4 x0, x1;
;                     if (XF32) { x0 = *(const f32x4*)(xin + ro + bj * 128); x1 = *(const f32x4*)(xin + ro + bj * 128 + 4); }
;                     else { const h8 xh = *(const h8*)(H + ro + bj * 128); x0 = (f32x4){(float)xh[0], (float)xh[1], (float)xh[2], (float)xh[3]}; x1 = (f32x4){(float)xh[4], (float)xh[5], (float)xh[6], (float)xh[7]}; }
;                     const f32x4 y0 = x0 + gv[bj][0] * acc[ai][bj][m][0], y1 = x1 + gv[bj][1] * acc[ai][bj][m][1];
;                     h8 o; o[0] = (half_t)y0[0]; o[1] = (half_t)y0[1]; o[2] = (half_t)y0[2]; o[3] = (half_t)y0[3]; o[4] = (half_t)y1[0]; o[5] = (half_t)y1[1]; o[6] = (half_t)y1[2]; o[7] = (half_t)y1[3];
;                     *(h8*)(H + ro + bj * 128) = o; } }
	v_mov_b32_e32 v116, v218
	v_mov_b32_e32 v117, v219
	v_mov_b32_e32 v118, v220
	v_mov_b32_e32 v119, v221
	v_add_co_u32_e32 v242, vcc, 0xb0000, v170
	s_nop 1
	v_addc_co_u32_e32 v243, vcc, 0, v171, vcc
	global_load_dwordx4 v[218:221], v[242:243], off offset:256
	s_nop 0
	v_cvt_f32_f16_e32 v122, v116
	v_cvt_f32_f16_sdwa v123, v116 dst_sel:DWORD dst_unused:UNUSED_PAD src0_sel:WORD_1
	v_cvt_f32_f16_e32 v116, v117
	v_cvt_f32_f16_sdwa v117, v117 dst_sel:DWORD dst_unused:UNUSED_PAD src0_sel:WORD_1
	v_cvt_f32_f16_e32 v124, v118
	v_cvt_f32_f16_sdwa v125, v118 dst_sel:DWORD dst_unused:UNUSED_PAD src0_sel:WORD_1
	v_cvt_f32_f16_e32 v118, v119
	v_cvt_f32_f16_sdwa v119, v119 dst_sel:DWORD dst_unused:UNUSED_PAD src0_sel:WORD_1
	v_pk_fma_f32 v[114:115], v[114:115], v[66:67], v[116:117]
	v_pk_fma_f32 v[112:113], v[112:113], v[64:65], v[122:123]
	v_pk_fma_f32 v[108:109], v[108:109], v[60:61], v[124:125]
	v_pk_fma_f32 v[110:111], v[110:111], v[62:63], v[118:119]
	s_nop 0
	v_cvt_pk_f16_f32 v111, v110, v111
	v_cvt_pk_f16_f32 v110, v108, v109
	v_cvt_pk_f16_f32 v109, v114, v115
	v_cvt_pk_f16_f32 v108, v112, v113
	global_store_dwordx4 v[120:121], v[108:111], off
	s_nop 1
	s_waitcnt vmcnt(10)
	v_mov_b32_e32 v108, v222
	v_mov_b32_e32 v109, v223
	v_mov_b32_e32 v110, v224
	v_mov_b32_e32 v111, v225
	s_nop 0
	v_cvt_f32_f16_e32 v112, v108
	v_cvt_f32_f16_sdwa v113, v108 dst_sel:DWORD dst_unused:UNUSED_PAD src0_sel:WORD_1
	v_cvt_f32_f16_e32 v108, v109
	v_cvt_f32_f16_sdwa v109, v109 dst_sel:DWORD dst_unused:UNUSED_PAD src0_sel:WORD_1
	v_cvt_f32_f16_e32 v114, v110
	v_cvt_f32_f16_sdwa v115, v110 dst_sel:DWORD dst_unused:UNUSED_PAD src0_sel:WORD_1
	v_cvt_f32_f16_e32 v110, v111
	v_cvt_f32_f16_sdwa v111, v111 dst_sel:DWORD dst_unused:UNUSED_PAD src0_sel:WORD_1
	v_pk_fma_f32 v[106:107], v[106:107], v[34:35], v[108:109]
	v_pk_fma_f32 v[104:105], v[104:105], v[32:33], v[112:113]
	v_pk_fma_f32 v[100:101], v[100:101], v[28:29], v[114:115]
	v_pk_fma_f32 v[102:103], v[102:103], v[30:31], v[110:111]
	s_nop 0
	v_cvt_pk_f16_f32 v103, v102, v103
	v_cvt_pk_f16_f32 v102, v100, v101
	v_cvt_pk_f16_f32 v101, v106, v107
	v_cvt_pk_f16_f32 v100, v104, v105
	global_store_dwordx4 v[120:121], v[100:103], off offset:256
	s_nop 1
	v_or_b32_e32 v100, 48, v172
	v_ashrrev_i32_e32 v101, 31, v100
	v_lshlrev_b64 v[100:101], 12, v[100:101]
	v_lshl_add_u64 v[100:101], s[16:17], 0, v[100:101]
	v_lshl_add_u64 v[104:105], v[100:101], 0, v[174:175]
	s_nop 1
	s_waitcnt vmcnt(9)
	v_mov_b32_e32 v100, v226
	v_mov_b32_e32 v101, v227
	v_mov_b32_e32 v102, v228
	v_mov_b32_e32 v103, v229
	s_nop 0
	v_cvt_f32_f16_e32 v106, v100
	v_cvt_f32_f16_sdwa v107, v100 dst_sel:DWORD dst_unused:UNUSED_PAD src0_sel:WORD_1
	v_cvt_f32_f16_e32 v100, v101
	v_cvt_f32_f16_sdwa v101, v101 dst_sel:DWORD dst_unused:UNUSED_PAD src0_sel:WORD_1
	v_cvt_f32_f16_e32 v108, v102
	v_cvt_f32_f16_sdwa v109, v102 dst_sel:DWORD dst_unused:UNUSED_PAD src0_sel:WORD_1
	v_cvt_f32_f16_e32 v102, v103
	v_cvt_f32_f16_sdwa v103, v103 dst_sel:DWORD dst_unused:UNUSED_PAD src0_sel:WORD_1
	v_pk_fma_f32 v[98:99], v[98:99], v[66:67], v[100:101]
	v_pk_fma_f32 v[96:97], v[96:97], v[64:65], v[106:107]
	v_pk_fma_f32 v[92:93], v[92:93], v[60:61], v[108:109]
	v_pk_fma_f32 v[94:95], v[94:95], v[62:63], v[102:103]
	s_nop 0
	v_cvt_pk_f16_f32 v95, v94, v95
	v_cvt_pk_f16_f32 v94, v92, v93
	v_cvt_pk_f16_f32 v93, v98, v99
	v_cvt_pk_f16_f32 v92, v96, v97
	global_store_dwordx4 v[104:105], v[92:95], off
	s_nop 1
	s_waitcnt vmcnt(8)
	v_mov_b32_e32 v92, v230
	v_mov_b32_e32 v93, v231
	v_mov_b32_e32 v94, v232
	v_mov_b32_e32 v95, v233
	s_nop 0
	v_cvt_f32_f16_e32 v96, v92
	v_cvt_f32_f16_sdwa v97, v92 dst_sel:DWORD dst_unused:UNUSED_PAD src0_sel:WORD_1
	v_cvt_f32_f16_e32 v92, v93
	v_cvt_f32_f16_sdwa v93, v93 dst_sel:DWORD dst_unused:UNUSED_PAD src0_sel:WORD_1
	v_cvt_f32_f16_e32 v98, v94
	v_cvt_f32_f16_sdwa v99, v94 dst_sel:DWORD dst_unused:UNUSED_PAD src0_sel:WORD_1
	v_cvt_f32_f16_e32 v94, v95
	v_cvt_f32_f16_sdwa v95, v95 dst_sel:DWORD dst_unused:UNUSED_PAD src0_sel:WORD_1
	v_pk_fma_f32 v[90:91], v[90:91], v[34:35], v[92:93]
	v_pk_fma_f32 v[84:85], v[84:85], v[28:29], v[98:99]
	v_pk_fma_f32 v[88:89], v[88:89], v[32:33], v[96:97]
	v_pk_fma_f32 v[86:87], v[86:87], v[30:31], v[94:95]
	s_nop 0
	v_cvt_pk_f16_f32 v87, v86, v87
	v_cvt_pk_f16_f32 v86, v84, v85
	v_cvt_pk_f16_f32 v85, v90, v91
	v_add_co_u32_e32 v90, vcc, s1, v170
	v_cvt_pk_f16_f32 v84, v88, v89
	s_nop 0
	v_addc_co_u32_e32 v91, vcc, 0, v171, vcc
	global_store_dwordx4 v[104:105], v[84:87], off offset:256
	s_nop 1
	s_waitcnt vmcnt(7)
	v_mov_b32_e32 v86, v234
	v_mov_b32_e32 v87, v235
	v_mov_b32_e32 v88, v236
	v_mov_b32_e32 v89, v237
	s_mov_b32 s1, 0x90000
	v_lshl_add_u64 v[84:85], v[170:171], 0, s[12:13]
	s_mov_b64 s[12:13], 0x90000
	s_nop 0
	v_cvt_f32_f16_e32 v92, v86
	v_cvt_f32_f16_sdwa v93, v86 dst_sel:DWORD dst_unused:UNUSED_PAD src0_sel:WORD_1
	v_cvt_f32_f16_e32 v86, v87
	v_cvt_f32_f16_sdwa v87, v87 dst_sel:DWORD dst_unused:UNUSED_PAD src0_sel:WORD_1
	v_cvt_f32_f16_e32 v94, v88
	v_cvt_f32_f16_sdwa v95, v88 dst_sel:DWORD dst_unused:UNUSED_PAD src0_sel:WORD_1
	v_cvt_f32_f16_e32 v88, v89
	v_cvt_f32_f16_sdwa v89, v89 dst_sel:DWORD dst_unused:UNUSED_PAD src0_sel:WORD_1
	v_pk_fma_f32 v[82:83], v[82:83], v[66:67], v[86:87]
	v_pk_fma_f32 v[80:81], v[80:81], v[64:65], v[92:93]
	v_pk_fma_f32 v[76:77], v[76:77], v[60:61], v[94:95]
	v_pk_fma_f32 v[78:79], v[78:79], v[62:63], v[88:89]
	s_nop 0
	v_cvt_pk_f16_f32 v79, v78, v79
	v_cvt_pk_f16_f32 v78, v76, v77
	v_cvt_pk_f16_f32 v77, v82, v83
	v_cvt_pk_f16_f32 v76, v80, v81
	global_store_dwordx4 v[90:91], v[76:79], off
	s_nop 1
	s_waitcnt vmcnt(6)
;     __device__ __forceinline__ void operator()(const f32x4 (&acc)[2][2][4][2], const pg8::Unit& u, int wr, int wc, int fr, int fq) const {
;     ...
;         for (int ai = 0; ai < 2; ++ai)
; #pragma unroll
;             for (int m = 0; m < 4; ++m) { const size_t ro = (size_t)(row0 + ai * 128 + m * 16) * DM + col0;
; #pragma unroll
;                 for (int bj = 0; bj < 2; ++bj) {
;                     f32x4 x0, x1;
;                     if (XF32) { x0 = *(const f32x4*)(xin + ro + bj * 128); x1 = *(const f32x4*)(xin + ro + bj * 128 + 4); }
;                     else { const h8 xh = *(const h8*)(H + ro + bj * 128); x0 = (f32x4){(float)xh[0], (float)xh[1], (float)xh[2], (float)xh[3]}; x1 = (f32x4){(float)xh[4], (float)xh[5], (float)xh[6], (float)xh[7]}; }
;                     const f32x4 y0 = x0 + gv[bj][0] * acc[ai][bj][m][0], y1 = x1 + gv[bj][1] * acc[ai][bj][m][1];
;                     h8 o; o[0] = (half_t)y0[0]; o[1] = (half_t)y0[1]; o[2] = (half_t)y0[2]; o[3] = (half_t)y0[3]; o[4] = (half_t)y1[0]; o[5] = (half_t)y1[1]; o[6] = (half_t)y1[2]; o[7] = (half_t)y1[3];
;                     *(h8*)(H + ro + bj * 128) = o; } }
	v_mov_b32_e32 v76, v238
	v_mov_b32_e32 v77, v239
	v_mov_b32_e32 v78, v240
	v_mov_b32_e32 v79, v241
	s_nop 0
	v_cvt_f32_f16_e32 v80, v76
	v_cvt_f32_f16_sdwa v81, v76 dst_sel:DWORD dst_unused:UNUSED_PAD src0_sel:WORD_1
	v_cvt_f32_f16_e32 v76, v77
	v_cvt_f32_f16_sdwa v77, v77 dst_sel:DWORD dst_unused:UNUSED_PAD src0_sel:WORD_1
	v_cvt_f32_f16_e32 v82, v78
	v_cvt_f32_f16_sdwa v83, v78 dst_sel:DWORD dst_unused:UNUSED_PAD src0_sel:WORD_1
	v_cvt_f32_f16_e32 v78, v79
	v_cvt_f32_f16_sdwa v79, v79 dst_sel:DWORD dst_unused:UNUSED_PAD src0_sel:WORD_1
	v_pk_fma_f32 v[74:75], v[74:75], v[34:35], v[76:77]
	v_pk_fma_f32 v[68:69], v[68:69], v[28:29], v[82:83]
	v_pk_fma_f32 v[72:73], v[72:73], v[32:33], v[80:81]
	v_pk_fma_f32 v[70:71], v[70:71], v[30:31], v[78:79]
	s_nop 0
	v_cvt_pk_f16_f32 v71, v70, v71
	v_cvt_pk_f16_f32 v70, v68, v69
	v_cvt_pk_f16_f32 v69, v74, v75
	v_add_co_u32_e32 v74, vcc, s1, v170
	v_cvt_pk_f16_f32 v68, v72, v73
	s_nop 0
	v_addc_co_u32_e32 v75, vcc, 0, v171, vcc
	global_store_dwordx4 v[84:85], v[68:71], off offset:256
	s_nop 1
	s_waitcnt vmcnt(5)
	v_mov_b32_e32 v70, v244
	v_mov_b32_e32 v71, v245
	v_mov_b32_e32 v72, v246
	v_mov_b32_e32 v73, v247
	s_mov_b32 s1, 0xa0000
	v_lshl_add_u64 v[68:69], v[170:171], 0, s[12:13]
	s_mov_b64 s[12:13], 0xa0000
	s_nop 0
	v_cvt_f32_f16_e32 v76, v70
	v_cvt_f32_f16_sdwa v77, v70 dst_sel:DWORD dst_unused:UNUSED_PAD src0_sel:WORD_1
	v_cvt_f32_f16_e32 v70, v71
	v_cvt_f32_f16_sdwa v71, v71 dst_sel:DWORD dst_unused:UNUSED_PAD src0_sel:WORD_1
	v_cvt_f32_f16_e32 v78, v72
	v_cvt_f32_f16_sdwa v79, v72 dst_sel:DWORD dst_unused:UNUSED_PAD src0_sel:WORD_1
	v_cvt_f32_f16_e32 v72, v73
	v_cvt_f32_f16_sdwa v73, v73 dst_sel:DWORD dst_unused:UNUSED_PAD src0_sel:WORD_1
	v_pk_fma_f32 v[58:59], v[58:59], v[66:67], v[70:71]
	v_pk_fma_f32 v[56:57], v[56:57], v[64:65], v[76:77]
	v_pk_fma_f32 v[52:53], v[52:53], v[60:61], v[78:79]
	v_pk_fma_f32 v[54:55], v[54:55], v[62:63], v[72:73]
	s_nop 0
	v_cvt_pk_f16_f32 v55, v54, v55
	v_cvt_pk_f16_f32 v54, v52, v53
	v_cvt_pk_f16_f32 v53, v58, v59
	v_cvt_pk_f16_f32 v52, v56, v57
	global_store_dwordx4 v[74:75], v[52:55], off
	s_nop 1
	s_waitcnt vmcnt(4)
	v_mov_b32_e32 v52, v202
	v_mov_b32_e32 v53, v203
	v_mov_b32_e32 v54, v204
	v_mov_b32_e32 v55, v205
	s_nop 0
	v_cvt_f32_f16_e32 v56, v52
	v_cvt_f32_f16_sdwa v57, v52 dst_sel:DWORD dst_unused:UNUSED_PAD src0_sel:WORD_1
	v_cvt_f32_f16_e32 v52, v53
	v_cvt_f32_f16_sdwa v53, v53 dst_sel:DWORD dst_unused:UNUSED_PAD src0_sel:WORD_1
	v_cvt_f32_f16_e32 v58, v54
	v_cvt_f32_f16_sdwa v59, v54 dst_sel:DWORD dst_unused:UNUSED_PAD src0_sel:WORD_1
	v_cvt_f32_f16_e32 v54, v55
	v_cvt_f32_f16_sdwa v55, v55 dst_sel:DWORD dst_unused:UNUSED_PAD src0_sel:WORD_1
	v_pk_fma_f32 v[50:51], v[50:51], v[34:35], v[52:53]
	v_pk_fma_f32 v[44:45], v[44:45], v[28:29], v[58:59]
	v_pk_fma_f32 v[48:49], v[48:49], v[32:33], v[56:57]
	v_pk_fma_f32 v[46:47], v[46:47], v[30:31], v[54:55]
	s_nop 0
	v_cvt_pk_f16_f32 v47, v46, v47
	v_cvt_pk_f16_f32 v46, v44, v45
	v_cvt_pk_f16_f32 v45, v50, v51
	v_add_co_u32_e32 v50, vcc, s1, v170
	v_cvt_pk_f16_f32 v44, v48, v49
	s_nop 0
	v_addc_co_u32_e32 v51, vcc, 0, v171, vcc
	global_store_dwordx4 v[68:69], v[44:47], off offset:256
	s_nop 1
	s_waitcnt vmcnt(3)
	v_mov_b32_e32 v46, v206
	v_mov_b32_e32 v47, v207
	v_mov_b32_e32 v48, v208
	v_mov_b32_e32 v49, v209
	s_mov_b32 s1, 0xb0000
	v_lshl_add_u64 v[44:45], v[170:171], 0, s[12:13]
	s_mov_b64 s[12:13], 0xb0000
	s_nop 0
	v_cvt_f32_f16_e32 v52, v46
	v_cvt_f32_f16_sdwa v53, v46 dst_sel:DWORD dst_unused:UNUSED_PAD src0_sel:WORD_1
	v_cvt_f32_f16_e32 v46, v47
	v_cvt_f32_f16_sdwa v47, v47 dst_sel:DWORD dst_unused:UNUSED_PAD src0_sel:WORD_1
	v_cvt_f32_f16_e32 v54, v48
	v_cvt_f32_f16_sdwa v55, v48 dst_sel:DWORD dst_unused:UNUSED_PAD src0_sel:WORD_1
	v_cvt_f32_f16_e32 v48, v49
	v_cvt_f32_f16_sdwa v49, v49 dst_sel:DWORD dst_unused:UNUSED_PAD src0_sel:WORD_1
	v_pk_fma_f32 v[42:43], v[42:43], v[66:67], v[46:47]
	v_pk_fma_f32 v[40:41], v[40:41], v[64:65], v[52:53]
	v_pk_fma_f32 v[36:37], v[36:37], v[60:61], v[54:55]
	v_pk_fma_f32 v[38:39], v[38:39], v[62:63], v[48:49]
	s_nop 0
	v_cvt_pk_f16_f32 v39, v38, v39
	v_cvt_pk_f16_f32 v38, v36, v37
	v_cvt_pk_f16_f32 v37, v42, v43
	v_cvt_pk_f16_f32 v36, v40, v41
	global_store_dwordx4 v[50:51], v[36:39], off
	s_nop 1
	s_waitcnt vmcnt(2)
; #define PG8_WAIT_V(n) asm volatile("s_waitcnt vmcnt(" #n ")" ::: "memory")
; #define PG8_BAR __builtin_amdgcn_s_barrier()
; template <class Epi>
; __device__ __forceinline__ void gemm_phase(LAS unsigned char* lds, const Gemm g, const StaticOrder& S, const Epi& E, const int tid) {
;     ...
;         if (!has_next) break;
; #pragma unroll
;         for (int a = 0; a < 2; ++a)
; #pragma unroll
;             for (int b = 0; b < 2; ++b)
; #pragma unroll
;                 for (int m = 0; m < 4; ++m)
; #pragma unroll
;                     for (int n = 0; n < 2; ++n) acc[a][b][m][n] = (f32x4){0.f, 0.f, 0.f, 0.f};
;         cur = nxt; cA = nA; cB = nB; ++ui;
;     }
;     PG8_WAIT_V(0);
;     if (wr == 0) PG8_BAR;
;     PG8_BAR;
;     __device__ __forceinline__ void operator()(const f32x4 (&acc)[2][2][4][2], const pg8::Unit& u, int wr, int wc, int fr, int fq) const {
;     ...
;         for (int ai = 0; ai < 2; ++ai)
; #pragma unroll
;             for (int m = 0; m < 4; ++m) { const size_t ro = (size_t)(row0 + ai * 128 + m * 16) * DM + col0;
; #pragma unroll
;                 for (int bj = 0; bj < 2; ++bj) {
;                     f32x4 x0, x1;
;                     if (XF32) { x0 = *(const f32x4*)(xin + ro + bj * 128); x1 = *(const f32x4*)(xin + ro + bj * 128 + 4); }
;                     else { const h8 xh = *(const h8*)(H + ro + bj * 128); x0 = (f32x4){(float)xh[0], (float)xh[1], (float)xh[2], (float)xh[3]}; x1 = (f32x4){(float)xh[4], (float)xh[5], (float)xh[6], (float)xh[7]}; }
;                     const f32x4 y0 = x0 + gv[bj][0] * acc[ai][bj][m][0], y1 = x1 + gv[bj][1] * acc[ai][bj][m][1];
;                     h8 o; o[0] = (half_t)y0[0]; o[1] = (half_t)y0[1]; o[2] = (half_t)y0[2]; o[3] = (half_t)y0[3]; o[4] = (half_t)y1[0]; o[5] = (half_t)y1[1]; o[6] = (half_t)y1[2]; o[7] = (half_t)y1[3];
;                     *(h8*)(H + ro + bj * 128) = o; } }
	v_mov_b32_e32 v36, v210
	v_mov_b32_e32 v37, v211
	v_mov_b32_e32 v38, v212
	v_mov_b32_e32 v39, v213
	s_nop 0
	v_cvt_f32_f16_e32 v40, v36
	v_cvt_f32_f16_sdwa v41, v36 dst_sel:DWORD dst_unused:UNUSED_PAD src0_sel:WORD_1
	v_cvt_f32_f16_e32 v36, v37
	v_cvt_f32_f16_sdwa v37, v37 dst_sel:DWORD dst_unused:UNUSED_PAD src0_sel:WORD_1
	v_cvt_f32_f16_e32 v42, v38
	v_cvt_f32_f16_sdwa v43, v38 dst_sel:DWORD dst_unused:UNUSED_PAD src0_sel:WORD_1
	v_cvt_f32_f16_e32 v38, v39
	v_cvt_f32_f16_sdwa v39, v39 dst_sel:DWORD dst_unused:UNUSED_PAD src0_sel:WORD_1
	v_pk_fma_f32 v[26:27], v[26:27], v[34:35], v[36:37]
	v_pk_fma_f32 v[20:21], v[20:21], v[28:29], v[42:43]
	v_pk_fma_f32 v[24:25], v[24:25], v[32:33], v[40:41]
	v_pk_fma_f32 v[22:23], v[22:23], v[30:31], v[38:39]
	s_nop 0
	v_cvt_pk_f16_f32 v23, v22, v23
	v_cvt_pk_f16_f32 v22, v20, v21
	v_cvt_pk_f16_f32 v21, v26, v27
	v_add_co_u32_e32 v26, vcc, s1, v170
	v_cvt_pk_f16_f32 v20, v24, v25
	s_nop 0
	v_addc_co_u32_e32 v27, vcc, 0, v171, vcc
	global_store_dwordx4 v[44:45], v[20:23], off offset:256
	s_nop 1
	s_waitcnt vmcnt(1)
	v_mov_b32_e32 v22, v214
	v_mov_b32_e32 v23, v215
	v_mov_b32_e32 v24, v216
	v_mov_b32_e32 v25, v217
	s_and_b64 vcc, exec, s[4:5]
	v_lshl_add_u64 v[20:21], v[170:171], 0, s[12:13]
	s_mov_b64 s[12:13], s[8:9]
	s_nop 0
	v_cvt_f32_f16_e32 v36, v22
	v_cvt_f32_f16_sdwa v37, v22 dst_sel:DWORD dst_unused:UNUSED_PAD src0_sel:WORD_1
	v_cvt_f32_f16_e32 v22, v23
	v_cvt_f32_f16_sdwa v23, v23 dst_sel:DWORD dst_unused:UNUSED_PAD src0_sel:WORD_1
	v_cvt_f32_f16_e32 v38, v24
	v_cvt_f32_f16_sdwa v39, v24 dst_sel:DWORD dst_unused:UNUSED_PAD src0_sel:WORD_1
	v_cvt_f32_f16_e32 v24, v25
	v_cvt_f32_f16_sdwa v25, v25 dst_sel:DWORD dst_unused:UNUSED_PAD src0_sel:WORD_1
	v_pk_fma_f32 v[18:19], v[18:19], v[66:67], v[22:23]
	v_pk_fma_f32 v[16:17], v[16:17], v[64:65], v[36:37]
	v_pk_fma_f32 v[12:13], v[12:13], v[60:61], v[38:39]
	v_pk_fma_f32 v[14:15], v[14:15], v[62:63], v[24:25]
	s_nop 0
	v_cvt_pk_f16_f32 v15, v14, v15
	v_cvt_pk_f16_f32 v14, v12, v13
	v_cvt_pk_f16_f32 v13, v18, v19
	v_cvt_pk_f16_f32 v12, v16, v17
	global_store_dwordx4 v[26:27], v[12:15], off
	s_nop 1
	s_waitcnt vmcnt(0)
	v_mov_b32_e32 v12, v218
	v_mov_b32_e32 v13, v219
	v_mov_b32_e32 v14, v220
	v_mov_b32_e32 v15, v221
	s_nop 0
	v_cvt_f32_f16_e32 v16, v12
	v_cvt_f32_f16_sdwa v17, v12 dst_sel:DWORD dst_unused:UNUSED_PAD src0_sel:WORD_1
	v_cvt_f32_f16_e32 v12, v13
	v_cvt_f32_f16_sdwa v13, v13 dst_sel:DWORD dst_unused:UNUSED_PAD src0_sel:WORD_1
	v_cvt_f32_f16_e32 v18, v14
	v_cvt_f32_f16_sdwa v19, v14 dst_sel:DWORD dst_unused:UNUSED_PAD src0_sel:WORD_1
	v_cvt_f32_f16_e32 v14, v15
	v_cvt_f32_f16_sdwa v15, v15 dst_sel:DWORD dst_unused:UNUSED_PAD src0_sel:WORD_1
	v_pk_fma_f32 v[10:11], v[10:11], v[34:35], v[12:13]
	v_pk_fma_f32 v[8:9], v[8:9], v[32:33], v[16:17]
	v_pk_fma_f32 v[4:5], v[4:5], v[28:29], v[18:19]
	v_pk_fma_f32 v[6:7], v[6:7], v[30:31], v[14:15]
	s_nop 0
	v_cvt_pk_f16_f32 v7, v6, v7
	v_cvt_pk_f16_f32 v6, v4, v5
	v_cvt_pk_f16_f32 v5, v10, v11
	v_cvt_pk_f16_f32 v4, v8, v9
	global_store_dwordx4 v[20:21], v[4:7], off offset:256
	s_cbranch_vccz .LBB0_653
	s_waitcnt vmcnt(0)
	v_readlane_b32 s48, v251, 13
	s_cmpk_gt_u32 s25, 0xff
	v_readlane_b32 s49, v251, 14
	s_cbranch_scc1 .LBB0_664
	s_barrier

; #define PG8_STAGE(bufoff, gbase, voff) do { _Pragma("unroll") for (int _i = 0; _i < 2; ++_i) \
;         __builtin_amdgcn_global_load_lds((const unsigned*)((const char*)(gbase) + (voff)[_i]), (LAS unsigned*)(lds + (bufoff) + ldsw + _i * 8192), 16, 0, 0); } while (0)
; #define PG8_LDA(dst, b, h) do { _Pragma("unroll") for (int m = 0; m < 4; ++m) _Pragma("unroll") for (int k = 0; k < 2; ++k) dst[m][k] = *(const LAS h8*)(lds + PG8_SA(b, h) + aoff + m * 2048 + k * 1024); } while (0)
; #define PG8_LDB(dst, b, h) do { _Pragma("unroll") for (int n = 0; n < 2; ++n) _Pragma("unroll") for (int k = 0; k < 2; ++k) dst[n][k] = *(const LAS h8*)(lds + PG8_SB(b, h) + boff + n * 2048 + k * 1024); } while (0)
; #define PG8_WAIT_L(n) asm volatile("s_waitcnt lgkmcnt(" #n ")" ::: "memory")
; #define PG8_BAR __builtin_amdgcn_s_barrier()
; #define PG8_SCHED __builtin_amdgcn_sched_barrier(0)
; template <class Epi>
; __device__ __forceinline__ void gemm_phase(LAS unsigned char* lds, const Gemm g, const StaticOrder& S, const Epi& E, const int tid) {
;     ...
;         for (int t = 0; t < nt; t += 2) {
;             const bool last = (t == nt - 2);
;             const char* a1 = cA + (size_t)(t + 1) * kstep;
;             const char* a2 = last ? nA : cA + (size_t)(t + 2) * kstep; const char* b2 = last ? nB : cB + (size_t)(t + 2) * kstep;
;             const char* a3 = a2 + kstep; const char* b3 = b2 + kstep;
;             if constexpr (Epi::HAS_MID) { if (t == (nt >> 1)) E.mid(acc, cur, wr, wc, fr, fq); }
;             PG8_LDB(B0, 0, 0); PG8_SCHED; PG8_LDA(At, 0, 0); PG8_STAGE(PG8_SA(1, 1), a1 + hstep, voffA);
;             PG8_WAIT_L(8); PG8_BAR; PG8_WAIT_L(0); PG8_MMA(0, 0, At, B0); PG8_BAR; PG8_SCHED;
;             PG8_LDB(B1, 0, 1); PG8_STAGE(PG8_SB(0, 0), b2, voffB);
;             PG8_BAR; PG8_WAIT_L(0); PG8_MMA(0, 1, At, B1); PG8_BAR;
;             PG8_LDA(At, 0, 1); PG8_STAGE(PG8_SA(0, 0), a2, voffA);
;             PG8_BAR; PG8_WAIT_L(0); PG8_MMA(1, 0, At, B0); PG8_BAR; PG8_SCHED;
.LBB0_678:
	s_add_u32 s14, s12, 0xfff80080
	s_addc_u32 s15, s13, -1
	s_add_i32 s55, 0, 0x10000
	v_add_u32_e32 v88, s55, v176
	ds_read_b128 v[68:71], v88
	ds_read_b128 v[72:75], v88 offset:1024
	ds_read_b128 v[84:87], v88 offset:2048
	ds_read_b128 v[88:91], v88 offset:3072
	s_cmp_eq_u32 s54, 28
	s_cselect_b32 s19, s7, s15
	s_cselect_b32 s18, s50, s14
	s_cselect_b32 s15, s1, s53
	s_cselect_b32 s14, s51, s52
	v_lshl_add_u64 v[174:175], s[12:13], 0, v[166:167]
	s_add_i32 m0, s39, 0xc000
	ds_read_b128 v[170:173], v177
	ds_read_b128 v[190:193], v177 offset:1024
	ds_read_b128 v[194:197], v177 offset:2048
	ds_read_b128 v[198:201], v177 offset:3072
	ds_read_b128 v[202:205], v177 offset:4096
	ds_read_b128 v[206:209], v177 offset:5120
	ds_read_b128 v[210:213], v177 offset:6144
	ds_read_b128 v[214:217], v177 offset:7168
	global_load_lds_dwordx4 v[174:175], off
	s_add_i32 m0, s39, 0xe000
	v_lshl_add_u64 v[174:175], s[12:13], 0, v[168:169]
	global_load_lds_dwordx4 v[174:175], off
	s_waitcnt lgkmcnt(8)
	s_barrier
	s_waitcnt lgkmcnt(0)
	s_waitcnt lgkmcnt(0)
	v_mfma_f32_16x16x32_bf16 v[144:147], v[68:71], v[170:173], v[144:147]
	v_mfma_f32_16x16x32_bf16 v[140:143], v[84:87], v[170:173], v[140:143]
	v_mfma_f32_16x16x32_bf16 v[128:131], v[68:71], v[194:197], v[128:131]
	v_mfma_f32_16x16x32_bf16 v[124:127], v[84:87], v[194:197], v[124:127]
	v_mfma_f32_16x16x32_bf16 v[112:115], v[68:71], v[202:205], v[112:115]
	v_mfma_f32_16x16x32_bf16 v[108:111], v[84:87], v[202:205], v[108:111]
	v_mfma_f32_16x16x32_bf16 v[96:99], v[68:71], v[210:213], v[96:99]
	v_mfma_f32_16x16x32_bf16 v[92:95], v[84:87], v[210:213], v[92:95]
	v_mfma_f32_16x16x32_bf16 v[144:147], v[72:75], v[190:193], v[144:147]
	v_mfma_f32_16x16x32_bf16 v[140:143], v[88:91], v[190:193], v[140:143]
	v_mfma_f32_16x16x32_bf16 v[128:131], v[72:75], v[198:201], v[128:131]
	v_mfma_f32_16x16x32_bf16 v[124:127], v[88:91], v[198:201], v[124:127]
	v_mfma_f32_16x16x32_bf16 v[112:115], v[72:75], v[206:209], v[112:115]
	v_mfma_f32_16x16x32_bf16 v[108:111], v[88:91], v[206:209], v[108:111]
	v_mfma_f32_16x16x32_bf16 v[96:99], v[72:75], v[214:217], v[96:99]
	v_mfma_f32_16x16x32_bf16 v[92:95], v[88:91], v[214:217], v[92:95]
	s_barrier
	s_add_i32 s58, 0, 0x14000
	v_add_u32_e32 v174, s58, v176
	s_add_i32 s55, s55, s38
	ds_read_b128 v[218:221], v174
	ds_read_b128 v[222:225], v174 offset:1024
	ds_read_b128 v[226:229], v174 offset:2048
	ds_read_b128 v[230:233], v174 offset:3072
	v_lshl_add_u64 v[174:175], s[14:15], 0, v[2:3]
	s_mov_b32 m0, s55
	v_lshl_add_u64 v[234:235], s[14:15], 0, v[0:1]
	global_load_lds_dwordx4 v[174:175], off
	s_add_i32 m0, s55, 0x2000
	s_nop 0
	global_load_lds_dwordx4 v[234:235], off
	s_barrier
	s_waitcnt lgkmcnt(0)
	s_waitcnt lgkmcnt(0)
	v_mfma_f32_16x16x32_bf16 v[136:139], v[218:221], v[170:173], v[136:139]
	v_mfma_f32_16x16x32_bf16 v[132:135], v[226:229], v[170:173], v[132:135]
	v_mfma_f32_16x16x32_bf16 v[120:123], v[218:221], v[194:197], v[120:123]
	v_mfma_f32_16x16x32_bf16 v[116:119], v[226:229], v[194:197], v[116:119]
	v_mfma_f32_16x16x32_bf16 v[104:107], v[218:221], v[202:205], v[104:107]
	v_mfma_f32_16x16x32_bf16 v[100:103], v[226:229], v[202:205], v[100:103]
	v_mfma_f32_16x16x32_bf16 v[80:83], v[218:221], v[210:213], v[80:83]
	v_mfma_f32_16x16x32_bf16 v[76:79], v[226:229], v[210:213], v[76:79]
	v_mfma_f32_16x16x32_bf16 v[136:139], v[222:225], v[190:193], v[136:139]
	v_mfma_f32_16x16x32_bf16 v[132:135], v[230:233], v[190:193], v[132:135]
	v_mfma_f32_16x16x32_bf16 v[120:123], v[222:225], v[198:201], v[120:123]
	v_mfma_f32_16x16x32_bf16 v[116:119], v[230:233], v[198:201], v[116:119]
	v_mfma_f32_16x16x32_bf16 v[104:107], v[222:225], v[206:209], v[104:107]
	v_mfma_f32_16x16x32_bf16 v[100:103], v[230:233], v[206:209], v[100:103]
	v_mfma_f32_16x16x32_bf16 v[80:83], v[222:225], v[214:217], v[80:83]
	v_mfma_f32_16x16x32_bf16 v[76:79], v[230:233], v[214:217], v[76:79]
	s_mov_b32 m0, s39
	v_lshl_add_u64 v[236:237], s[18:19], 0, v[164:165]
	s_barrier
	ds_read_b128 v[170:173], v177 offset:16384
	ds_read_b128 v[190:193], v177 offset:17408
	ds_read_b128 v[194:197], v177 offset:18432
	ds_read_b128 v[198:201], v177 offset:19456
	ds_read_b128 v[202:205], v177 offset:20480
	ds_read_b128 v[206:209], v177 offset:21504
	ds_read_b128 v[210:213], v177 offset:22528
	ds_read_b128 v[214:217], v177 offset:23552
	global_load_lds_dwordx4 v[236:237], off
	s_mov_b32 m0, s40
	v_lshl_add_u64 v[238:239], s[18:19], 0, v[162:163]
	global_load_lds_dwordx4 v[238:239], off
	s_barrier
	s_waitcnt lgkmcnt(0)
	s_waitcnt lgkmcnt(0)
	v_mfma_f32_16x16x32_bf16 v[64:67], v[68:71], v[170:173], v[64:67]
	v_mfma_f32_16x16x32_bf16 v[60:63], v[84:87], v[170:173], v[60:63]
	v_mfma_f32_16x16x32_bf16 v[48:51], v[68:71], v[194:197], v[48:51]
	v_mfma_f32_16x16x32_bf16 v[44:47], v[84:87], v[194:197], v[44:47]
	v_mfma_f32_16x16x32_bf16 v[32:35], v[68:71], v[202:205], v[32:35]
	v_mfma_f32_16x16x32_bf16 v[28:31], v[84:87], v[202:205], v[28:31]
	v_mfma_f32_16x16x32_bf16 v[16:19], v[68:71], v[210:213], v[16:19]
	v_mfma_f32_16x16x32_bf16 v[12:15], v[84:87], v[210:213], v[12:15]
	v_mfma_f32_16x16x32_bf16 v[64:67], v[72:75], v[190:193], v[64:67]
	v_mfma_f32_16x16x32_bf16 v[60:63], v[88:91], v[190:193], v[60:63]
	v_mfma_f32_16x16x32_bf16 v[48:51], v[72:75], v[198:201], v[48:51]
	v_mfma_f32_16x16x32_bf16 v[44:47], v[88:91], v[198:201], v[44:47]
	v_mfma_f32_16x16x32_bf16 v[32:35], v[72:75], v[206:209], v[32:35]
	v_mfma_f32_16x16x32_bf16 v[28:31], v[88:91], v[206:209], v[28:31]
	v_mfma_f32_16x16x32_bf16 v[16:19], v[72:75], v[214:217], v[16:19]
	v_mfma_f32_16x16x32_bf16 v[12:15], v[88:91], v[214:217], v[12:15]
	s_barrier
; #define PG8_STAGE(bufoff, gbase, voff) do { _Pragma("unroll") for (int _i = 0; _i < 2; ++_i) \
;         __builtin_amdgcn_global_load_lds((const unsigned*)((const char*)(gbase) + (voff)[_i]), (LAS unsigned*)(lds + (bufoff) + ldsw + _i * 8192), 16, 0, 0); } while (0)
; #define PG8_LDA(dst, b, h) do { _Pragma("unroll") for (int m = 0; m < 4; ++m) _Pragma("unroll") for (int k = 0; k < 2; ++k) dst[m][k] = *(const LAS h8*)(lds + PG8_SA(b, h) + aoff + m * 2048 + k * 1024); } while (0)
; #define PG8_LDB(dst, b, h) do { _Pragma("unroll") for (int n = 0; n < 2; ++n) _Pragma("unroll") for (int k = 0; k < 2; ++k) dst[n][k] = *(const LAS h8*)(lds + PG8_SB(b, h) + boff + n * 2048 + k * 1024); } while (0)
; #define PG8_WAIT_V(n) asm volatile("s_waitcnt vmcnt(" #n ")" ::: "memory")
; #define PG8_WAIT_L(n) asm volatile("s_waitcnt lgkmcnt(" #n ")" ::: "memory")
; #define PG8_BAR __builtin_amdgcn_s_barrier()
; #define PG8_SCHED __builtin_amdgcn_sched_barrier(0)
; template <class Epi>
; __device__ __forceinline__ void gemm_phase(LAS unsigned char* lds, const Gemm g, const StaticOrder& S, const Epi& E, const int tid) {
;     ...
;             PG8_STAGE(PG8_SB(0, 1), b2 + hstepB, voffB);
;             PG8_WAIT_V(6); PG8_BAR; PG8_MMA(1, 1, At, B1); PG8_BAR;
;             PG8_LDB(B0, 1, 0); PG8_SCHED; PG8_LDA(At, 1, 0); PG8_STAGE(PG8_SA(0, 1), a2 + hstep, voffA);
;             PG8_WAIT_L(8); PG8_BAR; PG8_WAIT_L(0); PG8_MMA(0, 0, At, B0); PG8_BAR; PG8_SCHED;
;             PG8_LDB(B1, 1, 1); PG8_STAGE(PG8_SB(1, 0), b3, voffB);
;             PG8_BAR; PG8_WAIT_L(0); PG8_MMA(0, 1, At, B1); PG8_BAR;
;             PG8_LDA(At, 1, 1); PG8_STAGE(PG8_SA(1, 0), a3, voffA);
	s_add_u32 s56, s14, 0x80000
	s_addc_u32 s57, s15, 0
	s_add_i32 s55, s58, s38
	s_mov_b32 m0, s55
	v_lshl_add_u64 v[68:69], s[56:57], 0, v[2:3]
	global_load_lds_dwordx4 v[68:69], off
	s_add_i32 m0, s55, 0x2000
	v_lshl_add_u64 v[68:69], s[56:57], 0, v[0:1]
	global_load_lds_dwordx4 v[68:69], off
	s_waitcnt vmcnt(6)
	s_barrier
	v_mfma_f32_16x16x32_bf16 v[56:59], v[218:221], v[170:173], v[56:59]
	v_mfma_f32_16x16x32_bf16 v[52:55], v[226:229], v[170:173], v[52:55]
	v_mfma_f32_16x16x32_bf16 v[40:43], v[218:221], v[194:197], v[40:43]
	v_mfma_f32_16x16x32_bf16 v[36:39], v[226:229], v[194:197], v[36:39]
	v_mfma_f32_16x16x32_bf16 v[24:27], v[218:221], v[202:205], v[24:27]
	v_mfma_f32_16x16x32_bf16 v[20:23], v[226:229], v[202:205], v[20:23]
	v_mfma_f32_16x16x32_bf16 v[8:11], v[218:221], v[210:213], v[8:11]
	v_mfma_f32_16x16x32_bf16 v[4:7], v[226:229], v[210:213], v[4:7]
	v_mfma_f32_16x16x32_bf16 v[56:59], v[222:225], v[190:193], v[56:59]
	v_mfma_f32_16x16x32_bf16 v[52:55], v[230:233], v[190:193], v[52:55]
	v_mfma_f32_16x16x32_bf16 v[40:43], v[222:225], v[198:201], v[40:43]
	v_mfma_f32_16x16x32_bf16 v[36:39], v[230:233], v[198:201], v[36:39]
	v_mfma_f32_16x16x32_bf16 v[24:27], v[222:225], v[206:209], v[24:27]
	v_mfma_f32_16x16x32_bf16 v[20:23], v[230:233], v[206:209], v[20:23]
	v_mfma_f32_16x16x32_bf16 v[8:11], v[222:225], v[214:217], v[8:11]
	v_mfma_f32_16x16x32_bf16 v[4:7], v[230:233], v[214:217], v[4:7]
	s_add_i32 s55, 0, 0x18000
	v_add_u32_e32 v88, s55, v176
	s_barrier
	ds_read_b128 v[68:71], v88
	ds_read_b128 v[72:75], v88 offset:1024
	ds_read_b128 v[84:87], v88 offset:2048
	ds_read_b128 v[88:91], v88 offset:3072
	s_add_u32 s18, s18, 0x80000
	s_addc_u32 s19, s19, 0
	s_mov_b32 m0, s41
	v_lshl_add_u64 v[218:219], s[18:19], 0, v[164:165]
	ds_read_b128 v[170:173], v177 offset:32768
	ds_read_b128 v[190:193], v177 offset:33792
	ds_read_b128 v[194:197], v177 offset:34816
	ds_read_b128 v[198:201], v177 offset:35840
	ds_read_b128 v[202:205], v177 offset:36864
	ds_read_b128 v[206:209], v177 offset:37888
	ds_read_b128 v[210:213], v177 offset:38912
	ds_read_b128 v[214:217], v177 offset:39936
	global_load_lds_dwordx4 v[218:219], off
	s_mov_b32 m0, s42
	v_lshl_add_u64 v[218:219], s[18:19], 0, v[162:163]
	global_load_lds_dwordx4 v[218:219], off
	s_waitcnt lgkmcnt(8)
	s_barrier
	s_waitcnt lgkmcnt(0)
	s_waitcnt lgkmcnt(0)
	v_mfma_f32_16x16x32_bf16 v[144:147], v[68:71], v[170:173], v[144:147]
	v_mfma_f32_16x16x32_bf16 v[140:143], v[84:87], v[170:173], v[140:143]
	v_mfma_f32_16x16x32_bf16 v[128:131], v[68:71], v[194:197], v[128:131]
	v_mfma_f32_16x16x32_bf16 v[124:127], v[84:87], v[194:197], v[124:127]
	v_mfma_f32_16x16x32_bf16 v[112:115], v[68:71], v[202:205], v[112:115]
	v_mfma_f32_16x16x32_bf16 v[108:111], v[84:87], v[202:205], v[108:111]
	v_mfma_f32_16x16x32_bf16 v[96:99], v[68:71], v[210:213], v[96:99]
	v_mfma_f32_16x16x32_bf16 v[92:95], v[84:87], v[210:213], v[92:95]
	v_mfma_f32_16x16x32_bf16 v[144:147], v[72:75], v[190:193], v[144:147]
	v_mfma_f32_16x16x32_bf16 v[140:143], v[88:91], v[190:193], v[140:143]
	v_mfma_f32_16x16x32_bf16 v[128:131], v[72:75], v[198:201], v[128:131]
	v_mfma_f32_16x16x32_bf16 v[124:127], v[88:91], v[198:201], v[124:127]
	v_mfma_f32_16x16x32_bf16 v[112:115], v[72:75], v[206:209], v[112:115]
	v_mfma_f32_16x16x32_bf16 v[108:111], v[88:91], v[206:209], v[108:111]
	v_mfma_f32_16x16x32_bf16 v[96:99], v[72:75], v[214:217], v[96:99]
	v_mfma_f32_16x16x32_bf16 v[92:95], v[88:91], v[214:217], v[92:95]
	s_barrier
	s_add_i32 s18, 0, 0x1c000
	s_add_i32 s19, s55, s38
	v_add_u32_e32 v178, s18, v176
	v_lshl_add_u64 v[174:175], v[174:175], 0, s[30:31]
	s_mov_b32 m0, s19
	ds_read_b128 v[218:221], v178
	ds_read_b128 v[222:225], v178 offset:1024
	ds_read_b128 v[226:229], v178 offset:2048
	ds_read_b128 v[230:233], v178 offset:3072
	global_load_lds_dwordx4 v[174:175], off
	s_add_i32 m0, s19, 0x2000
	v_lshl_add_u64 v[174:175], v[234:235], 0, s[30:31]
	global_load_lds_dwordx4 v[174:175], off
	s_barrier
	s_waitcnt lgkmcnt(0)
	s_waitcnt lgkmcnt(0)
	v_mfma_f32_16x16x32_bf16 v[136:139], v[218:221], v[170:173], v[136:139]
	v_mfma_f32_16x16x32_bf16 v[132:135], v[226:229], v[170:173], v[132:135]
	v_mfma_f32_16x16x32_bf16 v[120:123], v[218:221], v[194:197], v[120:123]
	v_mfma_f32_16x16x32_bf16 v[116:119], v[226:229], v[194:197], v[116:119]
	v_mfma_f32_16x16x32_bf16 v[104:107], v[218:221], v[202:205], v[104:107]
	v_mfma_f32_16x16x32_bf16 v[100:103], v[226:229], v[202:205], v[100:103]
	v_mfma_f32_16x16x32_bf16 v[80:83], v[218:221], v[210:213], v[80:83]
	v_mfma_f32_16x16x32_bf16 v[76:79], v[226:229], v[210:213], v[76:79]
	v_mfma_f32_16x16x32_bf16 v[136:139], v[222:225], v[190:193], v[136:139]
	v_mfma_f32_16x16x32_bf16 v[132:135], v[230:233], v[190:193], v[132:135]
	v_mfma_f32_16x16x32_bf16 v[120:123], v[222:225], v[198:201], v[120:123]
	v_mfma_f32_16x16x32_bf16 v[116:119], v[230:233], v[198:201], v[116:119]
	v_mfma_f32_16x16x32_bf16 v[104:107], v[222:225], v[206:209], v[104:107]
	v_mfma_f32_16x16x32_bf16 v[100:103], v[230:233], v[206:209], v[100:103]
	v_mfma_f32_16x16x32_bf16 v[80:83], v[222:225], v[214:217], v[80:83]
	v_mfma_f32_16x16x32_bf16 v[76:79], v[230:233], v[214:217], v[76:79]
	s_mov_b32 m0, s43
	v_lshl_add_u64 v[174:175], v[236:237], 0, s[30:31]
	s_barrier
	ds_read_b128 v[170:173], v177 offset:49152
	ds_read_b128 v[190:193], v177 offset:50176
	ds_read_b128 v[194:197], v177 offset:51200
	ds_read_b128 v[198:201], v177 offset:52224
	ds_read_b128 v[202:205], v177 offset:53248
	ds_read_b128 v[206:209], v177 offset:54272
	ds_read_b128 v[210:213], v177 offset:55296
	ds_read_b128 v[214:217], v177 offset:56320
	global_load_lds_dwordx4 v[174:175], off
	s_mov_b32 m0, s46
	v_lshl_add_u64 v[174:175], v[238:239], 0, s[30:31]
	global_load_lds_dwordx4 v[174:175], off
	s_barrier
; #define PG8_STAGE(bufoff, gbase, voff) do { _Pragma("unroll") for (int _i = 0; _i < 2; ++_i) \
;         __builtin_amdgcn_global_load_lds((const unsigned*)((const char*)(gbase) + (voff)[_i]), (LAS unsigned*)(lds + (bufoff) + ldsw + _i * 8192), 16, 0, 0); } while (0)
; #define PG8_WAIT_V(n) asm volatile("s_waitcnt vmcnt(" #n ")" ::: "memory")
; #define PG8_WAIT_L(n) asm volatile("s_waitcnt lgkmcnt(" #n ")" ::: "memory")
; #define PG8_BAR __builtin_amdgcn_s_barrier()
; template <class Epi>
; __device__ __forceinline__ void gemm_phase(LAS unsigned char* lds, const Gemm g, const StaticOrder& S, const Epi& E, const int tid) {
;     ...
;             PG8_BAR; PG8_WAIT_L(0); PG8_MMA(1, 0, At, B0); PG8_BAR; PG8_SCHED;
;             PG8_STAGE(PG8_SB(1, 1), b3 + hstepB, voffB);
;             PG8_WAIT_V(6); PG8_BAR; PG8_MMA(1, 1, At, B1); PG8_BAR;
;     __device__ __forceinline__ void operator()(const f32x4 (&acc)[2][2][4][2], const pg8::Unit& u, int wr, int wc, int fr, int fq) const {
;         const int row0 = u.pm * 256 + wr * 64 + fr, col0 = u.pn * 256 + wc * 32 + 8 * fq;
;         const float* gp = gate + (size_t)((u.pm * 256) >> 12) * 6144 + col0;
;         f32x4 gv[2][2];
; #pragma unroll
;         for (int bj = 0; bj < 2; ++bj)
; #pragma unroll
;             for (int n = 0; n < 2; ++n) gv[bj][n] = *(const f32x4*)(gp + bj * 128 + 4 * n);
; #pragma unroll
;         for (int ai = 0; ai < 2; ++ai)
; #pragma unroll
;             for (int m = 0; m < 4; ++m) { const size_t ro = (size_t)(row0 + ai * 128 + m * 16) * DM + col0;
; #pragma unroll
;                 for (int bj = 0; bj < 2; ++bj) {
;                     f32x4 x0, x1;
;                     if (XF32) { x0 = *(const f32x4*)(xin + ro + bj * 128); x1 = *(const f32x4*)(xin + ro + bj * 128 + 4); }
;                     else { const h8 xh = *(const h8*)(H + ro + bj * 128); x0 = (f32x4){(float)xh[0], (float)xh[1], (float)xh[2], (float)xh[3]}; x1 = (f32x4){(float)xh[4], (float)xh[5], (float)xh[6], (float)xh[7]}; }
;                     const f32x4 y0 = x0 + gv[bj][0] * acc[ai][bj][m][0], y1 = x1 + gv[bj][1] * acc[ai][bj][m][1];
;                     h8 o; o[0] = (half_t)y0[0]; o[1] = (half_t)y0[1]; o[2] = (half_t)y0[2]; o[3] = (half_t)y0[3]; o[4] = (half_t)y1[0]; o[5] = (half_t)y1[1]; o[6] = (half_t)y1[2]; o[7] = (half_t)y1[3];
;                     *(h8*)(H + ro + bj * 128) = o; } }
	s_waitcnt lgkmcnt(0)
	s_waitcnt lgkmcnt(0)
	v_mfma_f32_16x16x32_bf16 v[64:67], v[68:71], v[170:173], v[64:67]
	v_mfma_f32_16x16x32_bf16 v[60:63], v[84:87], v[170:173], v[60:63]
	v_mfma_f32_16x16x32_bf16 v[48:51], v[68:71], v[194:197], v[48:51]
	v_mfma_f32_16x16x32_bf16 v[44:47], v[84:87], v[194:197], v[44:47]
	v_mfma_f32_16x16x32_bf16 v[32:35], v[68:71], v[202:205], v[32:35]
	v_mfma_f32_16x16x32_bf16 v[28:31], v[84:87], v[202:205], v[28:31]
	v_mfma_f32_16x16x32_bf16 v[16:19], v[68:71], v[210:213], v[16:19]
	v_mfma_f32_16x16x32_bf16 v[12:15], v[84:87], v[210:213], v[12:15]
	v_mfma_f32_16x16x32_bf16 v[64:67], v[72:75], v[190:193], v[64:67]
	v_mfma_f32_16x16x32_bf16 v[60:63], v[88:91], v[190:193], v[60:63]
	v_mfma_f32_16x16x32_bf16 v[48:51], v[72:75], v[198:201], v[48:51]
	v_mfma_f32_16x16x32_bf16 v[44:47], v[88:91], v[198:201], v[44:47]
	v_mfma_f32_16x16x32_bf16 v[32:35], v[72:75], v[206:209], v[32:35]
	v_mfma_f32_16x16x32_bf16 v[28:31], v[88:91], v[206:209], v[28:31]
	v_mfma_f32_16x16x32_bf16 v[16:19], v[72:75], v[214:217], v[16:19]
	v_mfma_f32_16x16x32_bf16 v[12:15], v[88:91], v[214:217], v[12:15]
	s_barrier
	s_add_u32 s14, s14, 0x80080
	s_addc_u32 s15, s15, 0
	s_add_i32 s18, s18, s38
	s_mov_b32 m0, s18
	v_lshl_add_u64 v[68:69], s[14:15], 0, v[2:3]
	global_load_lds_dwordx4 v[68:69], off
	s_add_i32 m0, s18, 0x2000
	v_lshl_add_u64 v[68:69], s[14:15], 0, v[0:1]
	global_load_lds_dwordx4 v[68:69], off
	s_waitcnt vmcnt(6)
	s_barrier
	v_mfma_f32_16x16x32_bf16 v[56:59], v[218:221], v[170:173], v[56:59]
	v_mfma_f32_16x16x32_bf16 v[52:55], v[226:229], v[170:173], v[52:55]
	v_mfma_f32_16x16x32_bf16 v[40:43], v[218:221], v[194:197], v[40:43]
	v_mfma_f32_16x16x32_bf16 v[36:39], v[226:229], v[194:197], v[36:39]
	v_mfma_f32_16x16x32_bf16 v[24:27], v[218:221], v[202:205], v[24:27]
	v_mfma_f32_16x16x32_bf16 v[20:23], v[226:229], v[202:205], v[20:23]
	v_mfma_f32_16x16x32_bf16 v[8:11], v[218:221], v[210:213], v[8:11]
	v_mfma_f32_16x16x32_bf16 v[4:7], v[226:229], v[210:213], v[4:7]
	v_mfma_f32_16x16x32_bf16 v[56:59], v[222:225], v[190:193], v[56:59]
	v_mfma_f32_16x16x32_bf16 v[52:55], v[230:233], v[190:193], v[52:55]
	v_mfma_f32_16x16x32_bf16 v[40:43], v[222:225], v[198:201], v[40:43]
	v_mfma_f32_16x16x32_bf16 v[36:39], v[230:233], v[198:201], v[36:39]
	v_mfma_f32_16x16x32_bf16 v[24:27], v[222:225], v[206:209], v[24:27]
	v_mfma_f32_16x16x32_bf16 v[20:23], v[230:233], v[206:209], v[20:23]
	v_mfma_f32_16x16x32_bf16 v[8:11], v[222:225], v[214:217], v[8:11]
	v_mfma_f32_16x16x32_bf16 v[4:7], v[230:233], v[214:217], v[4:7]
	s_add_i32 s54, s54, 2
	s_add_u32 s12, s12, 0x100
	s_addc_u32 s13, s13, 0
	s_add_u32 s52, s52, 0x100
	s_addc_u32 s53, s53, 0
	s_cmp_gt_u32 s54, 29
	s_barrier
	s_cbranch_scc0 .LBB0_678
	s_ashr_i32 s1, s48, 4
	v_lshl_add_u32 v174, s48, 8, v179
	v_lshl_or_b32 v172, s49, 8, v157
	s_mul_hi_i32 s7, s1, 0x6000
	s_mulk_i32 s1, 0x6000
	v_ashrrev_i32_e32 v175, 31, v174
	s_add_u32 s12, s23, s1
	v_ashrrev_i32_e32 v173, 31, v172
	v_lshlrev_b64 v[170:171], 11, v[174:175]
	s_addc_u32 s13, s24, s7
	v_lshl_add_u64 v[170:171], v[170:171], 0, v[172:173]
	v_lshl_add_u64 v[72:73], v[172:173], 2, s[12:13]
	v_lshl_add_u64 v[198:199], v[170:171], 2, s[80:81]
	global_load_dwordx4 v[84:87], v[72:73], off offset:16
	global_load_dwordx4 v[88:91], v[72:73], off
	global_load_dwordx4 v[68:71], v[72:73], off offset:528
	s_nop 0
	global_load_dwordx4 v[72:75], v[72:73], off offset:512
	s_mov_b64 s[98:99], 0x0
	v_lshl_add_u64 v[248:249], v[198:199], 0, s[98:99]
	global_load_dwordx4 v[200:203], v[248:249], off offset:16
	global_load_dwordx4 v[204:207], v[248:249], off
	s_mov_b64 s[98:99], 0x0
	v_lshl_add_u64 v[248:249], v[198:199], 0, s[98:99]
	global_load_dwordx4 v[208:211], v[248:249], off offset:528
	global_load_dwordx4 v[212:215], v[248:249], off offset:512
	s_mov_b64 s[98:99], 0x20000
	v_lshl_add_u64 v[248:249], v[198:199], 0, s[98:99]
	global_load_dwordx4 v[216:219], v[248:249], off offset:16
	global_load_dwordx4 v[220:223], v[248:249], off
	s_mov_b64 s[98:99], 0x20000
	v_lshl_add_u64 v[248:249], v[198:199], 0, s[98:99]
	global_load_dwordx4 v[224:227], v[248:249], off offset:528
	global_load_dwordx4 v[228:231], v[248:249], off offset:512
	s_mov_b64 s[98:99], 0x40000
	v_lshl_add_u64 v[248:249], v[198:199], 0, s[98:99]
	global_load_dwordx4 v[232:235], v[248:249], off offset:16
	global_load_dwordx4 v[236:239], v[248:249], off
	s_mov_b64 s[98:99], 0x40000
	v_lshl_add_u64 v[248:249], v[198:199], 0, s[98:99]
	global_load_dwordx4 v[240:243], v[248:249], off offset:528
	global_load_dwordx4 v[244:247], v[248:249], off offset:512
	s_nop 0
	s_nop 1
	s_waitcnt vmcnt(10)
	v_mov_b32_e32 v190, v200
	v_mov_b32_e32 v191, v201
	v_mov_b32_e32 v192, v202
	v_mov_b32_e32 v193, v203
	s_nop 1
	v_mov_b32_e32 v194, v204
	v_mov_b32_e32 v195, v205
	v_mov_b32_e32 v196, v206
	v_mov_b32_e32 v197, v207
	s_mov_b64 s[98:99], 0x60000
	v_lshl_add_u64 v[248:249], v[198:199], 0, s[98:99]
	global_load_dwordx4 v[200:203], v[248:249], off offset:16
	global_load_dwordx4 v[204:207], v[248:249], off
	s_mov_b64 s[12:13], 0x40000
	s_and_b64 vcc, exec, s[4:5]
	s_mov_b32 s49, s0
	s_mov_b32 s48, s6
	s_mov_b64 s[14:15], s[10:11]
	s_nop 0
	v_pk_fma_f32 v[142:143], v[142:143], v[86:87], v[192:193]
	v_pk_fma_f32 v[146:147], v[146:147], v[90:91], v[196:197]
	v_pk_fma_f32 v[144:145], v[144:145], v[88:89], v[194:195]
	v_pk_fma_f32 v[190:191], v[140:141], v[84:85], v[190:191]
	v_cvt_pk_f16_f32 v143, v142, v143
	v_cvt_pk_f16_f32 v141, v146, v147
	v_cvt_pk_f16_f32 v142, v190, v191
	v_cvt_pk_f16_f32 v140, v144, v145
	v_lshl_add_u64 v[190:191], v[170:171], 1, s[16:17]
	global_store_dwordx4 v[190:191], v[140:143], off
	s_nop 1
	s_waitcnt vmcnt(10)
;     __device__ __forceinline__ void operator()(const f32x4 (&acc)[2][2][4][2], const pg8::Unit& u, int wr, int wc, int fr, int fq) const {
;         const int row0 = u.pm * 256 + wr * 64 + fr, col0 = u.pn * 256 + wc * 32 + 8 * fq;
;         const float* gp = gate + (size_t)((u.pm * 256) >> 12) * 6144 + col0;
;         f32x4 gv[2][2];
; #pragma unroll
;         for (int bj = 0; bj < 2; ++bj)
; #pragma unroll
;             for (int n = 0; n < 2; ++n) gv[bj][n] = *(const f32x4*)(gp + bj * 128 + 4 * n);
; #pragma unroll
;         for (int ai = 0; ai < 2; ++ai)
; #pragma unroll
;             for (int m = 0; m < 4; ++m) { const size_t ro = (size_t)(row0 + ai * 128 + m * 16) * DM + col0;
; #pragma unroll
;                 for (int bj = 0; bj < 2; ++bj) {
;                     f32x4 x0, x1;
;                     if (XF32) { x0 = *(const f32x4*)(xin + ro + bj * 128); x1 = *(const f32x4*)(xin + ro + bj * 128 + 4); }
;                     else { const h8 xh = *(const h8*)(H + ro + bj * 128); x0 = (f32x4){(float)xh[0], (float)xh[1], (float)xh[2], (float)xh[3]}; x1 = (f32x4){(float)xh[4], (float)xh[5], (float)xh[6], (float)xh[7]}; }
;                     const f32x4 y0 = x0 + gv[bj][0] * acc[ai][bj][m][0], y1 = x1 + gv[bj][1] * acc[ai][bj][m][1];
;                     h8 o; o[0] = (half_t)y0[0]; o[1] = (half_t)y0[1]; o[2] = (half_t)y0[2]; o[3] = (half_t)y0[3]; o[4] = (half_t)y1[0]; o[5] = (half_t)y1[1]; o[6] = (half_t)y1[2]; o[7] = (half_t)y1[3];
;                     *(h8*)(H + ro + bj * 128) = o; } }
	v_mov_b32_e32 v140, v208
	v_mov_b32_e32 v141, v209
	v_mov_b32_e32 v142, v210
	v_mov_b32_e32 v143, v211
	s_nop 0
	s_nop 1
	v_mov_b32_e32 v144, v212
	v_mov_b32_e32 v145, v213
	v_mov_b32_e32 v146, v214
	v_mov_b32_e32 v147, v215
	s_mov_b64 s[98:99], 0x60000
	v_lshl_add_u64 v[248:249], v[198:199], 0, s[98:99]
	global_load_dwordx4 v[208:211], v[248:249], off offset:528
	global_load_dwordx4 v[212:215], v[248:249], off offset:512
	s_nop 0
	v_pk_fma_f32 v[134:135], v[134:135], v[70:71], v[142:143]
	v_pk_fma_f32 v[138:139], v[138:139], v[74:75], v[146:147]
	v_pk_fma_f32 v[136:137], v[136:137], v[72:73], v[144:145]
	v_pk_fma_f32 v[140:141], v[132:133], v[68:69], v[140:141]
	v_cvt_pk_f16_f32 v135, v134, v135
	v_cvt_pk_f16_f32 v133, v138, v139
	v_cvt_pk_f16_f32 v134, v140, v141
	v_cvt_pk_f16_f32 v132, v136, v137
	global_store_dwordx4 v[190:191], v[132:135], off offset:256
	s_nop 1
	v_or_b32_e32 v132, 16, v174
	v_ashrrev_i32_e32 v133, 31, v132
	v_lshlrev_b64 v[132:133], 11, v[132:133]
	v_lshl_add_u64 v[140:141], v[132:133], 0, v[172:173]
	v_lshl_add_u64 v[142:143], v[140:141], 2, s[80:81]
	s_nop 1
	s_waitcnt vmcnt(10)
	v_mov_b32_e32 v132, v216
	v_mov_b32_e32 v133, v217
	v_mov_b32_e32 v134, v218
	v_mov_b32_e32 v135, v219
	s_nop 1
	v_mov_b32_e32 v136, v220
	v_mov_b32_e32 v137, v221
	v_mov_b32_e32 v138, v222
	v_mov_b32_e32 v139, v223
	s_mov_b64 s[98:99], 0x100000
	v_lshl_add_u64 v[248:249], v[198:199], 0, s[98:99]
	global_load_dwordx4 v[216:219], v[248:249], off offset:16
	global_load_dwordx4 v[220:223], v[248:249], off
	s_nop 0
	v_pk_fma_f32 v[126:127], v[126:127], v[86:87], v[134:135]
	v_pk_fma_f32 v[130:131], v[130:131], v[90:91], v[138:139]
	v_pk_fma_f32 v[128:129], v[128:129], v[88:89], v[136:137]
	v_pk_fma_f32 v[132:133], v[124:125], v[84:85], v[132:133]
	v_cvt_pk_f16_f32 v127, v126, v127
	v_cvt_pk_f16_f32 v125, v130, v131
	v_cvt_pk_f16_f32 v126, v132, v133
	v_cvt_pk_f16_f32 v124, v128, v129
	v_lshl_add_u64 v[132:133], v[140:141], 1, s[16:17]
	global_store_dwordx4 v[132:133], v[124:127], off
	s_nop 1
	s_waitcnt vmcnt(10)
	v_mov_b32_e32 v124, v224
	v_mov_b32_e32 v125, v225
	v_mov_b32_e32 v126, v226
	v_mov_b32_e32 v127, v227
	s_nop 0
	s_nop 1
	v_mov_b32_e32 v128, v228
	v_mov_b32_e32 v129, v229
	v_mov_b32_e32 v130, v230
	v_mov_b32_e32 v131, v231
	s_mov_b64 s[98:99], 0x100000
	v_lshl_add_u64 v[248:249], v[198:199], 0, s[98:99]
	global_load_dwordx4 v[224:227], v[248:249], off offset:528
	global_load_dwordx4 v[228:231], v[248:249], off offset:512
	s_nop 0
	v_pk_fma_f32 v[118:119], v[118:119], v[70:71], v[126:127]
	v_pk_fma_f32 v[122:123], v[122:123], v[74:75], v[130:131]
	v_pk_fma_f32 v[120:121], v[120:121], v[72:73], v[128:129]
	v_pk_fma_f32 v[124:125], v[116:117], v[68:69], v[124:125]
	v_cvt_pk_f16_f32 v119, v118, v119
	v_cvt_pk_f16_f32 v117, v122, v123
	v_cvt_pk_f16_f32 v118, v124, v125
	v_cvt_pk_f16_f32 v116, v120, v121
	global_store_dwordx4 v[132:133], v[116:119], off offset:256
	s_nop 1
	v_or_b32_e32 v116, 32, v174
	v_ashrrev_i32_e32 v117, 31, v116
	v_lshlrev_b64 v[116:117], 11, v[116:117]
	v_lshl_add_u64 v[124:125], v[116:117], 0, v[172:173]
	v_lshl_add_u64 v[126:127], v[124:125], 2, s[80:81]
	s_nop 1
	s_waitcnt vmcnt(10)
	v_mov_b32_e32 v116, v232
	v_mov_b32_e32 v117, v233
	v_mov_b32_e32 v118, v234
	v_mov_b32_e32 v119, v235
	s_nop 1
	v_mov_b32_e32 v120, v236
	v_mov_b32_e32 v121, v237
	v_mov_b32_e32 v122, v238
	v_mov_b32_e32 v123, v239
	s_mov_b64 s[98:99], 0x120000
	v_lshl_add_u64 v[248:249], v[198:199], 0, s[98:99]
	global_load_dwordx4 v[232:235], v[248:249], off offset:16
	global_load_dwordx4 v[236:239], v[248:249], off
	s_nop 0
	v_pk_fma_f32 v[110:111], v[110:111], v[86:87], v[118:119]
	v_pk_fma_f32 v[114:115], v[114:115], v[90:91], v[122:123]
	v_pk_fma_f32 v[112:113], v[112:113], v[88:89], v[120:121]
	v_pk_fma_f32 v[116:117], v[108:109], v[84:85], v[116:117]
	v_cvt_pk_f16_f32 v111, v110, v111
	v_cvt_pk_f16_f32 v109, v114, v115
	v_cvt_pk_f16_f32 v110, v116, v117
	v_cvt_pk_f16_f32 v108, v112, v113
	v_lshl_add_u64 v[116:117], v[124:125], 1, s[16:17]
	global_store_dwordx4 v[116:117], v[108:111], off
	s_nop 1
	s_waitcnt vmcnt(10)
	v_mov_b32_e32 v108, v240
	v_mov_b32_e32 v109, v241
	v_mov_b32_e32 v110, v242
	v_mov_b32_e32 v111, v243
	s_nop 0
	s_nop 1
	v_mov_b32_e32 v112, v244
	v_mov_b32_e32 v113, v245
	v_mov_b32_e32 v114, v246
	v_mov_b32_e32 v115, v247
	s_mov_b64 s[98:99], 0x120000
	v_lshl_add_u64 v[248:249], v[198:199], 0, s[98:99]
	global_load_dwordx4 v[240:243], v[248:249], off offset:528
	global_load_dwordx4 v[244:247], v[248:249], off offset:512
	s_nop 0
	v_pk_fma_f32 v[102:103], v[102:103], v[70:71], v[110:111]
	v_pk_fma_f32 v[106:107], v[106:107], v[74:75], v[114:115]
	v_pk_fma_f32 v[104:105], v[104:105], v[72:73], v[112:113]
	v_pk_fma_f32 v[108:109], v[100:101], v[68:69], v[108:109]
	v_cvt_pk_f16_f32 v103, v102, v103
	v_cvt_pk_f16_f32 v101, v106, v107
	v_cvt_pk_f16_f32 v102, v108, v109
	v_cvt_pk_f16_f32 v100, v104, v105
	global_store_dwordx4 v[116:117], v[100:103], off offset:256
	s_nop 1
	v_or_b32_e32 v100, 48, v174
	v_ashrrev_i32_e32 v101, 31, v100
	v_lshlrev_b64 v[100:101], 11, v[100:101]
	v_lshl_add_u64 v[108:109], v[100:101], 0, v[172:173]
	v_lshl_add_u64 v[110:111], v[108:109], 2, s[80:81]
	s_nop 1
	s_waitcnt vmcnt(10)
;     __device__ __forceinline__ void operator()(const f32x4 (&acc)[2][2][4][2], const pg8::Unit& u, int wr, int wc, int fr, int fq) const {
;     ...
;         for (int ai = 0; ai < 2; ++ai)
; #pragma unroll
;             for (int m = 0; m < 4; ++m) { const size_t ro = (size_t)(row0 + ai * 128 + m * 16) * DM + col0;
; #pragma unroll
;                 for (int bj = 0; bj < 2; ++bj) {
;                     f32x4 x0, x1;
;                     if (XF32) { x0 = *(const f32x4*)(xin + ro + bj * 128); x1 = *(const f32x4*)(xin + ro + bj * 128 + 4); }
;                     else { const h8 xh = *(const h8*)(H + ro + bj * 128); x0 = (f32x4){(float)xh[0], (float)xh[1], (float)xh[2], (float)xh[3]}; x1 = (f32x4){(float)xh[4], (float)xh[5], (float)xh[6], (float)xh[7]}; }
;                     const f32x4 y0 = x0 + gv[bj][0] * acc[ai][bj][m][0], y1 = x1 + gv[bj][1] * acc[ai][bj][m][1];
;                     h8 o; o[0] = (half_t)y0[0]; o[1] = (half_t)y0[1]; o[2] = (half_t)y0[2]; o[3] = (half_t)y0[3]; o[4] = (half_t)y1[0]; o[5] = (half_t)y1[1]; o[6] = (half_t)y1[2]; o[7] = (half_t)y1[3];
;                     *(h8*)(H + ro + bj * 128) = o; } }
	v_mov_b32_e32 v100, v200
	v_mov_b32_e32 v101, v201
	v_mov_b32_e32 v102, v202
	v_mov_b32_e32 v103, v203
	s_nop 1
	v_mov_b32_e32 v104, v204
	v_mov_b32_e32 v105, v205
	v_mov_b32_e32 v106, v206
	v_mov_b32_e32 v107, v207
	s_mov_b64 s[98:99], 0x140000
	v_lshl_add_u64 v[248:249], v[198:199], 0, s[98:99]
	global_load_dwordx4 v[200:203], v[248:249], off offset:16
	global_load_dwordx4 v[204:207], v[248:249], off
	s_nop 0
	v_pk_fma_f32 v[94:95], v[94:95], v[86:87], v[102:103]
	v_pk_fma_f32 v[98:99], v[98:99], v[90:91], v[106:107]
	v_pk_fma_f32 v[96:97], v[96:97], v[88:89], v[104:105]
	v_pk_fma_f32 v[100:101], v[92:93], v[84:85], v[100:101]
	v_cvt_pk_f16_f32 v95, v94, v95
	v_cvt_pk_f16_f32 v93, v98, v99
	v_cvt_pk_f16_f32 v94, v100, v101
	v_cvt_pk_f16_f32 v92, v96, v97
	v_lshl_add_u64 v[100:101], v[108:109], 1, s[16:17]
	global_store_dwordx4 v[100:101], v[92:95], off
	s_nop 1
	s_waitcnt vmcnt(10)
	v_mov_b32_e32 v92, v208
	v_mov_b32_e32 v93, v209
	v_mov_b32_e32 v94, v210
	v_mov_b32_e32 v95, v211
	s_nop 0
	s_nop 1
	v_mov_b32_e32 v96, v212
	v_mov_b32_e32 v97, v213
	v_mov_b32_e32 v98, v214
	v_mov_b32_e32 v99, v215
	s_mov_b64 s[98:99], 0x140000
	v_lshl_add_u64 v[248:249], v[198:199], 0, s[98:99]
	global_load_dwordx4 v[208:211], v[248:249], off offset:528
	global_load_dwordx4 v[212:215], v[248:249], off offset:512
	s_nop 0
	v_pk_fma_f32 v[78:79], v[78:79], v[70:71], v[94:95]
	v_pk_fma_f32 v[82:83], v[82:83], v[74:75], v[98:99]
	v_pk_fma_f32 v[80:81], v[80:81], v[72:73], v[96:97]
	v_pk_fma_f32 v[92:93], v[76:77], v[68:69], v[92:93]
	v_cvt_pk_f16_f32 v79, v78, v79
	v_cvt_pk_f16_f32 v77, v82, v83
	v_cvt_pk_f16_f32 v78, v92, v93
	v_cvt_pk_f16_f32 v76, v80, v81
	v_lshl_add_u64 v[92:93], v[170:171], 0, s[12:13]
	global_store_dwordx4 v[100:101], v[76:79], off offset:256
	v_lshl_add_u64 v[94:95], v[92:93], 2, s[80:81]
	s_nop 1
	s_waitcnt vmcnt(10)
	v_mov_b32_e32 v76, v216
	v_mov_b32_e32 v77, v217
	v_mov_b32_e32 v78, v218
	v_mov_b32_e32 v79, v219
	s_nop 1
	v_mov_b32_e32 v80, v220
	v_mov_b32_e32 v81, v221
	v_mov_b32_e32 v82, v222
	v_mov_b32_e32 v83, v223
	s_mov_b64 s[98:99], 0x160000
	v_lshl_add_u64 v[248:249], v[198:199], 0, s[98:99]
	global_load_dwordx4 v[216:219], v[248:249], off offset:16
	global_load_dwordx4 v[220:223], v[248:249], off
	s_mov_b64 s[12:13], 0x48000
	s_nop 0
	v_pk_fma_f32 v[62:63], v[62:63], v[86:87], v[78:79]
	v_pk_fma_f32 v[66:67], v[66:67], v[90:91], v[82:83]
	v_pk_fma_f32 v[64:65], v[64:65], v[88:89], v[80:81]
	v_pk_fma_f32 v[76:77], v[60:61], v[84:85], v[76:77]
	v_cvt_pk_f16_f32 v63, v62, v63
	v_cvt_pk_f16_f32 v61, v66, v67
	v_cvt_pk_f16_f32 v62, v76, v77
	v_cvt_pk_f16_f32 v60, v64, v65
	v_lshl_add_u64 v[76:77], v[92:93], 1, s[16:17]
	global_store_dwordx4 v[76:77], v[60:63], off
	s_nop 1
	s_waitcnt vmcnt(10)
	v_mov_b32_e32 v60, v224
	v_mov_b32_e32 v61, v225
	v_mov_b32_e32 v62, v226
	v_mov_b32_e32 v63, v227
	s_nop 0
	s_nop 1
	v_mov_b32_e32 v64, v228
	v_mov_b32_e32 v65, v229
	v_mov_b32_e32 v66, v230
	v_mov_b32_e32 v67, v231
	s_mov_b64 s[98:99], 0x160000
	v_lshl_add_u64 v[248:249], v[198:199], 0, s[98:99]
	global_load_dwordx4 v[224:227], v[248:249], off offset:528
	global_load_dwordx4 v[228:231], v[248:249], off offset:512
	s_nop 0
	v_pk_fma_f32 v[54:55], v[54:55], v[70:71], v[62:63]
	v_pk_fma_f32 v[58:59], v[58:59], v[74:75], v[66:67]
	v_pk_fma_f32 v[56:57], v[56:57], v[72:73], v[64:65]
	v_pk_fma_f32 v[60:61], v[52:53], v[68:69], v[60:61]
	v_cvt_pk_f16_f32 v55, v54, v55
	v_cvt_pk_f16_f32 v53, v58, v59
	v_cvt_pk_f16_f32 v54, v60, v61
	v_cvt_pk_f16_f32 v52, v56, v57
	v_lshl_add_u64 v[60:61], v[170:171], 0, s[12:13]
	global_store_dwordx4 v[76:77], v[52:55], off offset:256
	v_lshl_add_u64 v[62:63], v[60:61], 2, s[80:81]
	s_nop 1
	s_waitcnt vmcnt(10)
	v_mov_b32_e32 v52, v232
	v_mov_b32_e32 v53, v233
	v_mov_b32_e32 v54, v234
	v_mov_b32_e32 v55, v235
	s_nop 1
	v_mov_b32_e32 v56, v236
	v_mov_b32_e32 v57, v237
	v_mov_b32_e32 v58, v238
	v_mov_b32_e32 v59, v239
	s_mov_b64 s[12:13], 0x50000
	s_nop 0
	v_pk_fma_f32 v[46:47], v[46:47], v[86:87], v[54:55]
	v_pk_fma_f32 v[50:51], v[50:51], v[90:91], v[58:59]
	v_pk_fma_f32 v[48:49], v[48:49], v[88:89], v[56:57]
	v_pk_fma_f32 v[52:53], v[44:45], v[84:85], v[52:53]
	v_cvt_pk_f16_f32 v47, v46, v47
	v_cvt_pk_f16_f32 v45, v50, v51
	v_cvt_pk_f16_f32 v46, v52, v53
	v_cvt_pk_f16_f32 v44, v48, v49
	v_lshl_add_u64 v[52:53], v[60:61], 1, s[16:17]
	global_store_dwordx4 v[52:53], v[44:47], off
	s_nop 1
	s_waitcnt vmcnt(8)
; #define PG8_WAIT_V(n) asm volatile("s_waitcnt vmcnt(" #n ")" ::: "memory")
; #define PG8_BAR __builtin_amdgcn_s_barrier()
; template <class Epi>
; __device__ __forceinline__ void gemm_phase(LAS unsigned char* lds, const Gemm g, const StaticOrder& S, const Epi& E, const int tid) {
;     ...
;     PG8_WAIT_V(0);
;     if (wr == 0) PG8_BAR;
;     PG8_BAR;
;     __device__ __forceinline__ void operator()(const f32x4 (&acc)[2][2][4][2], const pg8::Unit& u, int wr, int wc, int fr, int fq) const {
;     ...
;         for (int ai = 0; ai < 2; ++ai)
; #pragma unroll
;             for (int m = 0; m < 4; ++m) { const size_t ro = (size_t)(row0 + ai * 128 + m * 16) * DM + col0;
; #pragma unroll
;                 for (int bj = 0; bj < 2; ++bj) {
;                     f32x4 x0, x1;
;                     if (XF32) { x0 = *(const f32x4*)(xin + ro + bj * 128); x1 = *(const f32x4*)(xin + ro + bj * 128 + 4); }
;                     else { const h8 xh = *(const h8*)(H + ro + bj * 128); x0 = (f32x4){(float)xh[0], (float)xh[1], (float)xh[2], (float)xh[3]}; x1 = (f32x4){(float)xh[4], (float)xh[5], (float)xh[6], (float)xh[7]}; }
;                     const f32x4 y0 = x0 + gv[bj][0] * acc[ai][bj][m][0], y1 = x1 + gv[bj][1] * acc[ai][bj][m][1];
;                     h8 o; o[0] = (half_t)y0[0]; o[1] = (half_t)y0[1]; o[2] = (half_t)y0[2]; o[3] = (half_t)y0[3]; o[4] = (half_t)y1[0]; o[5] = (half_t)y1[1]; o[6] = (half_t)y1[2]; o[7] = (half_t)y1[3];
;                     *(h8*)(H + ro + bj * 128) = o; } }
	v_mov_b32_e32 v44, v240
	v_mov_b32_e32 v45, v241
	v_mov_b32_e32 v46, v242
	v_mov_b32_e32 v47, v243
	s_nop 0
	s_nop 1
	v_mov_b32_e32 v48, v244
	v_mov_b32_e32 v49, v245
	v_mov_b32_e32 v50, v246
	v_mov_b32_e32 v51, v247
	s_nop 0
	v_pk_fma_f32 v[38:39], v[38:39], v[70:71], v[46:47]
	v_pk_fma_f32 v[42:43], v[42:43], v[74:75], v[50:51]
	v_pk_fma_f32 v[40:41], v[40:41], v[72:73], v[48:49]
	v_pk_fma_f32 v[44:45], v[36:37], v[68:69], v[44:45]
	v_cvt_pk_f16_f32 v39, v38, v39
	v_cvt_pk_f16_f32 v37, v42, v43
	v_cvt_pk_f16_f32 v38, v44, v45
	v_cvt_pk_f16_f32 v36, v40, v41
	v_lshl_add_u64 v[44:45], v[170:171], 0, s[12:13]
	global_store_dwordx4 v[52:53], v[36:39], off offset:256
	v_lshl_add_u64 v[46:47], v[44:45], 2, s[80:81]
	s_nop 1
	s_waitcnt vmcnt(6)
	v_mov_b32_e32 v36, v200
	v_mov_b32_e32 v37, v201
	v_mov_b32_e32 v38, v202
	v_mov_b32_e32 v39, v203
	s_nop 1
	v_mov_b32_e32 v40, v204
	v_mov_b32_e32 v41, v205
	v_mov_b32_e32 v42, v206
	v_mov_b32_e32 v43, v207
	s_mov_b64 s[12:13], 0x58000
	s_nop 0
	v_pk_fma_f32 v[30:31], v[30:31], v[86:87], v[38:39]
	v_pk_fma_f32 v[34:35], v[34:35], v[90:91], v[42:43]
	v_pk_fma_f32 v[32:33], v[32:33], v[88:89], v[40:41]
	v_pk_fma_f32 v[36:37], v[28:29], v[84:85], v[36:37]
	v_cvt_pk_f16_f32 v31, v30, v31
	v_cvt_pk_f16_f32 v29, v34, v35
	v_cvt_pk_f16_f32 v30, v36, v37
	v_cvt_pk_f16_f32 v28, v32, v33
	v_lshl_add_u64 v[36:37], v[44:45], 1, s[16:17]
	global_store_dwordx4 v[36:37], v[28:31], off
	s_nop 1
	s_waitcnt vmcnt(4)
	v_mov_b32_e32 v28, v208
	v_mov_b32_e32 v29, v209
	v_mov_b32_e32 v30, v210
	v_mov_b32_e32 v31, v211
	s_nop 0
	s_nop 1
	v_mov_b32_e32 v32, v212
	v_mov_b32_e32 v33, v213
	v_mov_b32_e32 v34, v214
	v_mov_b32_e32 v35, v215
	s_nop 0
	v_pk_fma_f32 v[22:23], v[22:23], v[70:71], v[30:31]
	v_pk_fma_f32 v[26:27], v[26:27], v[74:75], v[34:35]
	v_pk_fma_f32 v[24:25], v[24:25], v[72:73], v[32:33]
	v_pk_fma_f32 v[28:29], v[20:21], v[68:69], v[28:29]
	v_cvt_pk_f16_f32 v23, v22, v23
	v_cvt_pk_f16_f32 v21, v26, v27
	v_cvt_pk_f16_f32 v22, v28, v29
	v_cvt_pk_f16_f32 v20, v24, v25
	v_lshl_add_u64 v[28:29], v[170:171], 0, s[12:13]
	global_store_dwordx4 v[36:37], v[20:23], off offset:256
	v_lshl_add_u64 v[30:31], v[28:29], 2, s[80:81]
	s_nop 1
	s_waitcnt vmcnt(2)
	v_mov_b32_e32 v20, v216
	v_mov_b32_e32 v21, v217
	v_mov_b32_e32 v22, v218
	v_mov_b32_e32 v23, v219
	s_nop 1
	v_mov_b32_e32 v24, v220
	v_mov_b32_e32 v25, v221
	v_mov_b32_e32 v26, v222
	v_mov_b32_e32 v27, v223
	s_mov_b64 s[12:13], s[8:9]
	s_nop 0
	v_pk_fma_f32 v[14:15], v[14:15], v[86:87], v[22:23]
	v_pk_fma_f32 v[18:19], v[18:19], v[90:91], v[26:27]
	v_pk_fma_f32 v[16:17], v[16:17], v[88:89], v[24:25]
	v_pk_fma_f32 v[20:21], v[12:13], v[84:85], v[20:21]
	v_cvt_pk_f16_f32 v15, v14, v15
	v_cvt_pk_f16_f32 v13, v18, v19
	v_cvt_pk_f16_f32 v14, v20, v21
	v_cvt_pk_f16_f32 v12, v16, v17
	v_lshl_add_u64 v[20:21], v[28:29], 1, s[16:17]
	global_store_dwordx4 v[20:21], v[12:15], off
	s_nop 1
	s_waitcnt vmcnt(0)
	v_mov_b32_e32 v12, v224
	v_mov_b32_e32 v13, v225
	v_mov_b32_e32 v14, v226
	v_mov_b32_e32 v15, v227
	s_nop 0
	s_nop 1
	v_mov_b32_e32 v16, v228
	v_mov_b32_e32 v17, v229
	v_mov_b32_e32 v18, v230
	v_mov_b32_e32 v19, v231
	s_nop 0
	v_pk_fma_f32 v[6:7], v[6:7], v[70:71], v[14:15]
	v_pk_fma_f32 v[10:11], v[10:11], v[74:75], v[18:19]
	v_pk_fma_f32 v[8:9], v[8:9], v[72:73], v[16:17]
	v_pk_fma_f32 v[12:13], v[4:5], v[68:69], v[12:13]
	v_cvt_pk_f16_f32 v7, v6, v7
	v_cvt_pk_f16_f32 v5, v10, v11
	v_cvt_pk_f16_f32 v6, v12, v13
	v_cvt_pk_f16_f32 v4, v8, v9
	global_store_dwordx4 v[20:21], v[4:7], off offset:256
	s_cbranch_vccz .LBB0_671
	s_waitcnt vmcnt(0)
	v_readlane_b32 s42, v251, 7
	v_readlane_b32 s46, v251, 9
	v_readlane_b32 s48, v251, 13
	s_cmpk_gt_u32 s25, 0xff
	v_readlane_b32 s43, v251, 8
	v_readlane_b32 s47, v251, 10
	v_readlane_b32 s49, v251, 14
	s_cbranch_scc1 .LBB0_682
	s_barrier
